# GEMM row-sum epilogues: ds_bpermute (LDS round trip + wait, 16 per tile) replaced by v_permlane16/32_swap on a copy (bit-identical pairwise sum)
# baseline (speedup 1.0000x reference)
; #define PG8_STAGE(bufoff, gbase, voff) do { _Pragma("unroll") for (int _i = 0; _i < 2; ++_i) \
;         __builtin_amdgcn_global_load_lds((const unsigned*)((const char*)(gbase) + (voff)[_i]), (PG8_LAS unsigned*)(lds + (bufoff) + ldsw + _i * 8192), 16, 0, 0); } while (0)
; #define PG8_LDA(dst, b, h) do { _Pragma("unroll") for (int m = 0; m < 4; ++m) _Pragma("unroll") for (int k = 0; k < 2; ++k) dst[m][k] = *(const PG8_LAS bf16x8*)(lds + PG8_SA(b, h) + aoff + m * 2048 + k * 1024); } while (0)
; #define PG8_LDB(dst, b, h) do { _Pragma("unroll") for (int n = 0; n < 2; ++n) _Pragma("unroll") for (int k = 0; k < 2; ++k) dst[n][k] = *(const PG8_LAS bf16x8*)(lds + PG8_SB(b, h) + boff + n * 2048 + k * 1024); } while (0)
; #define PG8_MMA(ai, bj, At, Bt) do { __builtin_amdgcn_s_setprio(1); _Pragma("unroll") for (int m = 0; m < 4; ++m) _Pragma("unroll") for (int n = 0; n < 2; ++n) _Pragma("unroll") for (int k = 0; k < 2; ++k) \
;         acc[ai][bj][m][n] = __builtin_amdgcn_mfma_f32_16x16x32_bf16(Bt[n][k], At[m][k], acc[ai][bj][m][n], 0, 0, 0); __builtin_amdgcn_s_setprio(0); } while (0)
; #define PG8_WAIT_V(n) asm volatile("s_waitcnt vmcnt(" #n ")" ::: "memory")
; #define PG8_WAIT_L(n) asm volatile("s_waitcnt lgkmcnt(" #n ")" ::: "memory")
; #define PG8_BAR __builtin_amdgcn_s_barrier()
; #define PG8_SCHED __builtin_amdgcn_sched_barrier(0)
; template <class Epi, class Sched, bool ALIGN_EPI = false, bool SP2 = false>
; __device__ __forceinline__ void gemm_phase(PG8_LAS unsigned char* lds, const Gemm g, const Sched& S, const Epi& E) {
;     ...
;             PG8_LDB(B0, 0, 0); PG8_LDB(B1, 0, 1); PG8_SCHED; PG8_LDA(At, 0, 0); PG8_STAGE(PG8_SA(1, 1), a1 + hstep, voffA);
;             PG8_WAIT_V(8); PG8_WAIT_L(0); PG8_BAR; PG8_MMA(0, 0, At, B0); PG8_MMA(0, 1, At, B1); PG8_BAR; PG8_SCHED;
;             PG8_LDA(At, 0, 1); PG8_STAGE(PG8_SB(0, 0), b2, voffB); PG8_STAGE(PG8_SB(0, 1), b2 + hstep, voffB); PG8_STAGE(PG8_SA(0, 0), a2, voffA);
;             PG8_WAIT_V(8); PG8_WAIT_L(0); PG8_BAR; PG8_MMA(1, 0, At, B0); PG8_MMA(1, 1, At, B1); PG8_BAR; PG8_SCHED;
.LBB0_914:
	ds_read_b128 v[140:143], v147
	ds_read_b128 v[152:155], v147 offset:1024
	ds_read_b128 v[156:159], v147 offset:2048
	ds_read_b128 v[160:163], v147 offset:3072
	ds_read_b128 v[164:167], v148
	ds_read_b128 v[168:171], v148 offset:1024
	ds_read_b128 v[172:175], v148 offset:2048
	ds_read_b128 v[180:183], v148 offset:3072
	s_add_u32 s3, s28, 0xfffc0080
	s_addc_u32 s30, s29, -1
	s_cmp_eq_u32 s72, 12
	s_cselect_b32 s35, s19, s30
	s_cselect_b32 s34, s25, s3
	s_cselect_b32 s31, s17, s71
	s_cselect_b32 s30, s69, s70
	v_lshl_add_u64 v[216:217], s[28:29], 0, v[132:133]
	s_add_i32 m0, s27, 0xc000
	ds_read_b128 v[184:187], v149
	ds_read_b128 v[188:191], v149 offset:1024
	ds_read_b128 v[192:195], v149 offset:2048
	ds_read_b128 v[196:199], v149 offset:3072
	ds_read_b128 v[200:203], v149 offset:4096
	ds_read_b128 v[204:207], v149 offset:5120
	ds_read_b128 v[208:211], v149 offset:6144
	ds_read_b128 v[212:215], v149 offset:7168
	global_load_lds_dwordx4 v[216:217], off
	v_lshl_add_u64 v[216:217], s[28:29], 0, v[134:135]
	s_add_i32 m0, s27, 0xe000
	s_nop 0
	global_load_lds_dwordx4 v[216:217], off
	s_waitcnt vmcnt(8)
	s_waitcnt lgkmcnt(0)
	s_barrier
	s_setprio 1
	s_waitcnt lgkmcnt(0)
	v_mfma_f32_16x16x32_bf16 v[124:127], v[140:143], v[184:187], v[124:127]
	v_mfma_f32_16x16x32_bf16 v[120:123], v[156:159], v[184:187], v[120:123]
	v_mfma_f32_16x16x32_bf16 v[112:115], v[140:143], v[192:195], v[112:115]
	v_mfma_f32_16x16x32_bf16 v[104:107], v[156:159], v[192:195], v[104:107]
	v_mfma_f32_16x16x32_bf16 v[96:99], v[140:143], v[200:203], v[96:99]
	v_mfma_f32_16x16x32_bf16 v[88:91], v[156:159], v[200:203], v[88:91]
	v_mfma_f32_16x16x32_bf16 v[80:83], v[140:143], v[208:211], v[80:83]
	v_mfma_f32_16x16x32_bf16 v[72:75], v[156:159], v[208:211], v[72:75]
	v_mfma_f32_16x16x32_bf16 v[124:127], v[152:155], v[188:191], v[124:127]
	v_mfma_f32_16x16x32_bf16 v[120:123], v[160:163], v[188:191], v[120:123]
	v_mfma_f32_16x16x32_bf16 v[112:115], v[152:155], v[196:199], v[112:115]
	v_mfma_f32_16x16x32_bf16 v[104:107], v[160:163], v[196:199], v[104:107]
	v_mfma_f32_16x16x32_bf16 v[96:99], v[152:155], v[204:207], v[96:99]
	v_mfma_f32_16x16x32_bf16 v[88:91], v[160:163], v[204:207], v[88:91]
	v_mfma_f32_16x16x32_bf16 v[80:83], v[152:155], v[212:215], v[80:83]
	v_mfma_f32_16x16x32_bf16 v[72:75], v[160:163], v[212:215], v[72:75]
	s_setprio 0
	s_setprio 1
	v_mfma_f32_16x16x32_bf16 v[116:119], v[164:167], v[184:187], v[116:119]
	v_mfma_f32_16x16x32_bf16 v[108:111], v[172:175], v[184:187], v[108:111]
	v_mfma_f32_16x16x32_bf16 v[100:103], v[164:167], v[192:195], v[100:103]
	v_mfma_f32_16x16x32_bf16 v[92:95], v[172:175], v[192:195], v[92:95]
	v_mfma_f32_16x16x32_bf16 v[84:87], v[164:167], v[200:203], v[84:87]
	v_mfma_f32_16x16x32_bf16 v[76:79], v[172:175], v[200:203], v[76:79]
	v_mfma_f32_16x16x32_bf16 v[68:71], v[164:167], v[208:211], v[68:71]
	v_mfma_f32_16x16x32_bf16 v[64:67], v[172:175], v[208:211], v[64:67]
	v_mfma_f32_16x16x32_bf16 v[116:119], v[168:171], v[188:191], v[116:119]
	v_mfma_f32_16x16x32_bf16 v[108:111], v[180:183], v[188:191], v[108:111]
	v_mfma_f32_16x16x32_bf16 v[100:103], v[168:171], v[196:199], v[100:103]
	v_mfma_f32_16x16x32_bf16 v[92:95], v[180:183], v[196:199], v[92:95]
	v_mfma_f32_16x16x32_bf16 v[84:87], v[168:171], v[204:207], v[84:87]
	v_mfma_f32_16x16x32_bf16 v[76:79], v[180:183], v[204:207], v[76:79]
	v_mfma_f32_16x16x32_bf16 v[68:71], v[168:171], v[212:215], v[68:71]
	v_mfma_f32_16x16x32_bf16 v[64:67], v[180:183], v[212:215], v[64:67]
	s_setprio 0
	s_barrier
	s_add_i32 s3, s67, s45
	v_lshl_add_u64 v[216:217], s[30:31], 0, v[128:129]
	s_mov_b32 m0, s3
	ds_read_b128 v[184:187], v149 offset:16384
	ds_read_b128 v[188:191], v149 offset:17408
	ds_read_b128 v[192:195], v149 offset:18432
	ds_read_b128 v[196:199], v149 offset:19456
	ds_read_b128 v[200:203], v149 offset:20480
	ds_read_b128 v[204:207], v149 offset:21504
	ds_read_b128 v[208:211], v149 offset:22528
	ds_read_b128 v[212:215], v149 offset:23552
	global_load_lds_dwordx4 v[216:217], off
	s_add_i32 m0, s3, 0x2000
	s_add_u32 s36, s30, 0x40000
	v_lshl_add_u64 v[218:219], s[30:31], 0, v[130:131]
	s_addc_u32 s37, s31, 0
	s_add_i32 s3, s68, s45
	global_load_lds_dwordx4 v[218:219], off
	v_lshl_add_u64 v[220:221], s[36:37], 0, v[128:129]
	s_mov_b32 m0, s3
	v_lshl_add_u64 v[222:223], s[34:35], 0, v[130:131]
	global_load_lds_dwordx4 v[220:221], off
	v_lshl_add_u64 v[220:221], s[36:37], 0, v[130:131]
	s_add_i32 m0, s3, 0x2000
	s_nop 0
	global_load_lds_dwordx4 v[220:221], off
	v_lshl_add_u64 v[220:221], s[34:35], 0, v[128:129]
	s_mov_b32 m0, s27
	s_nop 0
	global_load_lds_dwordx4 v[220:221], off
	s_mov_b32 m0, s46
	s_nop 0
	global_load_lds_dwordx4 v[222:223], off
	s_waitcnt vmcnt(8)
	s_waitcnt lgkmcnt(0)
	s_barrier
; #define PG8_STAGE(bufoff, gbase, voff) do { _Pragma("unroll") for (int _i = 0; _i < 2; ++_i) \
;         __builtin_amdgcn_global_load_lds((const unsigned*)((const char*)(gbase) + (voff)[_i]), (PG8_LAS unsigned*)(lds + (bufoff) + ldsw + _i * 8192), 16, 0, 0); } while (0)
; #define PG8_LDA(dst, b, h) do { _Pragma("unroll") for (int m = 0; m < 4; ++m) _Pragma("unroll") for (int k = 0; k < 2; ++k) dst[m][k] = *(const PG8_LAS bf16x8*)(lds + PG8_SA(b, h) + aoff + m * 2048 + k * 1024); } while (0)
; #define PG8_LDB(dst, b, h) do { _Pragma("unroll") for (int n = 0; n < 2; ++n) _Pragma("unroll") for (int k = 0; k < 2; ++k) dst[n][k] = *(const PG8_LAS bf16x8*)(lds + PG8_SB(b, h) + boff + n * 2048 + k * 1024); } while (0)
; #define PG8_MMA(ai, bj, At, Bt) do { __builtin_amdgcn_s_setprio(1); _Pragma("unroll") for (int m = 0; m < 4; ++m) _Pragma("unroll") for (int n = 0; n < 2; ++n) _Pragma("unroll") for (int k = 0; k < 2; ++k) \
;         acc[ai][bj][m][n] = __builtin_amdgcn_mfma_f32_16x16x32_bf16(Bt[n][k], At[m][k], acc[ai][bj][m][n], 0, 0, 0); __builtin_amdgcn_s_setprio(0); } while (0)
; #define PG8_WAIT_V(n) asm volatile("s_waitcnt vmcnt(" #n ")" ::: "memory")
; #define PG8_WAIT_L(n) asm volatile("s_waitcnt lgkmcnt(" #n ")" ::: "memory")
; #define PG8_BAR __builtin_amdgcn_s_barrier()
; #define PG8_SCHED __builtin_amdgcn_sched_barrier(0)
; template <class Epi, class Sched, bool ALIGN_EPI = false, bool SP2 = false>
; __device__ __forceinline__ void gemm_phase(PG8_LAS unsigned char* lds, const Gemm g, const Sched& S, const Epi& E) {
;     ...
;             PG8_WAIT_V(8); PG8_WAIT_L(0); PG8_BAR; PG8_MMA(1, 0, At, B0); PG8_MMA(1, 1, At, B1); PG8_BAR; PG8_SCHED;
;             PG8_LDB(B0, 1, 0); PG8_LDB(B1, 1, 1); PG8_SCHED; PG8_LDA(At, 1, 0); PG8_STAGE(PG8_SA(0, 1), a2 + hstep, voffA);
;             PG8_WAIT_V(8); PG8_WAIT_L(0); PG8_BAR; PG8_MMA(0, 0, At, B0); PG8_MMA(0, 1, At, B1); PG8_BAR; PG8_SCHED;
	s_setprio 1
	s_waitcnt lgkmcnt(0)
	v_mfma_f32_16x16x32_bf16 v[60:63], v[140:143], v[184:187], v[60:63]
	v_mfma_f32_16x16x32_bf16 v[56:59], v[156:159], v[184:187], v[56:59]
	v_mfma_f32_16x16x32_bf16 v[48:51], v[140:143], v[192:195], v[48:51]
	v_mfma_f32_16x16x32_bf16 v[40:43], v[156:159], v[192:195], v[40:43]
	v_mfma_f32_16x16x32_bf16 v[32:35], v[140:143], v[200:203], v[32:35]
	v_mfma_f32_16x16x32_bf16 v[24:27], v[156:159], v[200:203], v[24:27]
	v_mfma_f32_16x16x32_bf16 v[16:19], v[140:143], v[208:211], v[16:19]
	v_mfma_f32_16x16x32_bf16 v[8:11], v[156:159], v[208:211], v[8:11]
	v_mfma_f32_16x16x32_bf16 v[60:63], v[152:155], v[188:191], v[60:63]
	v_mfma_f32_16x16x32_bf16 v[56:59], v[160:163], v[188:191], v[56:59]
	v_mfma_f32_16x16x32_bf16 v[48:51], v[152:155], v[196:199], v[48:51]
	v_mfma_f32_16x16x32_bf16 v[40:43], v[160:163], v[196:199], v[40:43]
	v_mfma_f32_16x16x32_bf16 v[32:35], v[152:155], v[204:207], v[32:35]
	v_mfma_f32_16x16x32_bf16 v[24:27], v[160:163], v[204:207], v[24:27]
	v_mfma_f32_16x16x32_bf16 v[16:19], v[152:155], v[212:215], v[16:19]
	v_mfma_f32_16x16x32_bf16 v[8:11], v[160:163], v[212:215], v[8:11]
	s_setprio 0
	s_setprio 1
	v_mfma_f32_16x16x32_bf16 v[52:55], v[164:167], v[184:187], v[52:55]
	v_mfma_f32_16x16x32_bf16 v[44:47], v[172:175], v[184:187], v[44:47]
	v_mfma_f32_16x16x32_bf16 v[36:39], v[164:167], v[192:195], v[36:39]
	v_mfma_f32_16x16x32_bf16 v[28:31], v[172:175], v[192:195], v[28:31]
	v_mfma_f32_16x16x32_bf16 v[20:23], v[164:167], v[200:203], v[20:23]
	v_mfma_f32_16x16x32_bf16 v[12:15], v[172:175], v[200:203], v[12:15]
	v_mfma_f32_16x16x32_bf16 v[4:7], v[164:167], v[208:211], v[4:7]
	v_mfma_f32_16x16x32_bf16 v[0:3], v[172:175], v[208:211], v[0:3]
	v_mfma_f32_16x16x32_bf16 v[52:55], v[168:171], v[188:191], v[52:55]
	v_mfma_f32_16x16x32_bf16 v[44:47], v[180:183], v[188:191], v[44:47]
	v_mfma_f32_16x16x32_bf16 v[36:39], v[168:171], v[196:199], v[36:39]
	v_mfma_f32_16x16x32_bf16 v[28:31], v[180:183], v[196:199], v[28:31]
	v_mfma_f32_16x16x32_bf16 v[20:23], v[168:171], v[204:207], v[20:23]
	v_mfma_f32_16x16x32_bf16 v[12:15], v[180:183], v[204:207], v[12:15]
	v_mfma_f32_16x16x32_bf16 v[4:7], v[168:171], v[212:215], v[4:7]
	v_mfma_f32_16x16x32_bf16 v[0:3], v[180:183], v[212:215], v[0:3]
	s_setprio 0
	s_barrier
	s_add_i32 s3, 0, 0x18000
	v_add_u32_e32 v151, s3, v145
	s_add_i32 s33, 0, 0x1c000
	ds_read_b128 v[140:143], v151
	ds_read_b128 v[152:155], v151 offset:1024
	ds_read_b128 v[156:159], v151 offset:2048
	ds_read_b128 v[160:163], v151 offset:3072
	v_add_u32_e32 v151, s33, v145
	ds_read_b128 v[164:167], v151
	ds_read_b128 v[168:171], v151 offset:1024
	ds_read_b128 v[172:175], v151 offset:2048
	ds_read_b128 v[180:183], v151 offset:3072
	s_add_u32 s34, s34, 0x40000
	s_addc_u32 s35, s35, 0
	s_mov_b32 m0, s47
	v_lshl_add_u64 v[224:225], s[34:35], 0, v[128:129]
	ds_read_b128 v[184:187], v149 offset:32768
	ds_read_b128 v[188:191], v149 offset:33792
	ds_read_b128 v[192:195], v149 offset:34816
	ds_read_b128 v[196:199], v149 offset:35840
	ds_read_b128 v[200:203], v149 offset:36864
	ds_read_b128 v[204:207], v149 offset:37888
	ds_read_b128 v[208:211], v149 offset:38912
	ds_read_b128 v[212:215], v149 offset:39936
	global_load_lds_dwordx4 v[224:225], off
	v_lshl_add_u64 v[224:225], s[34:35], 0, v[130:131]
	s_mov_b32 m0, s60
	s_nop 0
	global_load_lds_dwordx4 v[224:225], off
	s_waitcnt vmcnt(8)
	s_waitcnt lgkmcnt(0)
	s_barrier
	s_setprio 1
	s_waitcnt lgkmcnt(0)
	v_mfma_f32_16x16x32_bf16 v[124:127], v[140:143], v[184:187], v[124:127]
	v_mfma_f32_16x16x32_bf16 v[120:123], v[156:159], v[184:187], v[120:123]
	v_mfma_f32_16x16x32_bf16 v[112:115], v[140:143], v[192:195], v[112:115]
	v_mfma_f32_16x16x32_bf16 v[104:107], v[156:159], v[192:195], v[104:107]
	v_mfma_f32_16x16x32_bf16 v[96:99], v[140:143], v[200:203], v[96:99]
	v_mfma_f32_16x16x32_bf16 v[88:91], v[156:159], v[200:203], v[88:91]
	v_mfma_f32_16x16x32_bf16 v[80:83], v[140:143], v[208:211], v[80:83]
	v_mfma_f32_16x16x32_bf16 v[72:75], v[156:159], v[208:211], v[72:75]
	v_mfma_f32_16x16x32_bf16 v[124:127], v[152:155], v[188:191], v[124:127]
	v_mfma_f32_16x16x32_bf16 v[120:123], v[160:163], v[188:191], v[120:123]
	v_mfma_f32_16x16x32_bf16 v[112:115], v[152:155], v[196:199], v[112:115]
	v_mfma_f32_16x16x32_bf16 v[104:107], v[160:163], v[196:199], v[104:107]
	v_mfma_f32_16x16x32_bf16 v[96:99], v[152:155], v[204:207], v[96:99]
	v_mfma_f32_16x16x32_bf16 v[88:91], v[160:163], v[204:207], v[88:91]
	v_mfma_f32_16x16x32_bf16 v[80:83], v[152:155], v[212:215], v[80:83]
	v_mfma_f32_16x16x32_bf16 v[72:75], v[160:163], v[212:215], v[72:75]
	s_setprio 0
	s_setprio 1
	v_mfma_f32_16x16x32_bf16 v[116:119], v[164:167], v[184:187], v[116:119]
	v_mfma_f32_16x16x32_bf16 v[108:111], v[172:175], v[184:187], v[108:111]
	v_mfma_f32_16x16x32_bf16 v[100:103], v[164:167], v[192:195], v[100:103]
	v_mfma_f32_16x16x32_bf16 v[92:95], v[172:175], v[192:195], v[92:95]
	v_mfma_f32_16x16x32_bf16 v[84:87], v[164:167], v[200:203], v[84:87]
	v_mfma_f32_16x16x32_bf16 v[76:79], v[172:175], v[200:203], v[76:79]
	v_mfma_f32_16x16x32_bf16 v[68:71], v[164:167], v[208:211], v[68:71]
	v_mfma_f32_16x16x32_bf16 v[64:67], v[172:175], v[208:211], v[64:67]
	v_mfma_f32_16x16x32_bf16 v[116:119], v[168:171], v[188:191], v[116:119]
	v_mfma_f32_16x16x32_bf16 v[108:111], v[180:183], v[188:191], v[108:111]
	v_mfma_f32_16x16x32_bf16 v[100:103], v[168:171], v[196:199], v[100:103]
	v_mfma_f32_16x16x32_bf16 v[92:95], v[180:183], v[196:199], v[92:95]
	v_mfma_f32_16x16x32_bf16 v[84:87], v[168:171], v[204:207], v[84:87]
	v_mfma_f32_16x16x32_bf16 v[76:79], v[180:183], v[204:207], v[76:79]
	v_mfma_f32_16x16x32_bf16 v[68:71], v[168:171], v[212:215], v[68:71]
	v_mfma_f32_16x16x32_bf16 v[64:67], v[180:183], v[212:215], v[64:67]
	s_setprio 0
	s_barrier
; #define PG8_STAGE(bufoff, gbase, voff) do { _Pragma("unroll") for (int _i = 0; _i < 2; ++_i) \
;         __builtin_amdgcn_global_load_lds((const unsigned*)((const char*)(gbase) + (voff)[_i]), (PG8_LAS unsigned*)(lds + (bufoff) + ldsw + _i * 8192), 16, 0, 0); } while (0)
; #define PG8_LDA(dst, b, h) do { _Pragma("unroll") for (int m = 0; m < 4; ++m) _Pragma("unroll") for (int k = 0; k < 2; ++k) dst[m][k] = *(const PG8_LAS bf16x8*)(lds + PG8_SA(b, h) + aoff + m * 2048 + k * 1024); } while (0)
; #define PG8_WAIT_V(n) asm volatile("s_waitcnt vmcnt(" #n ")" ::: "memory")
; #define PG8_WAIT_L(n) asm volatile("s_waitcnt lgkmcnt(" #n ")" ::: "memory")
; #define PG8_BAR __builtin_amdgcn_s_barrier()
; #define PG8_SCHED __builtin_amdgcn_sched_barrier(0)
; template <class Epi, class Sched, bool ALIGN_EPI = false, bool SP2 = false>
; __device__ __forceinline__ void gemm_phase(PG8_LAS unsigned char* lds, const Gemm g, const Sched& S, const Epi& E) {
;     ...
;             PG8_LDA(At, 1, 1); PG8_STAGE(PG8_SB(1, 0), b3, voffB); PG8_STAGE(PG8_SB(1, 1), b3 + hstep, voffB); PG8_STAGE(PG8_SA(1, 0), a3, voffA);
;             PG8_WAIT_V(8); PG8_WAIT_L(0); PG8_BAR; PG8_MMA(1, 0, At, B0); PG8_MMA(1, 1, At, B1); PG8_BAR; PG8_SCHED;
;     __device__ __forceinline__ void operator()(const AccT& acc, const pg8::Unit& u, int wr, int wc, int fr, int fq) const {
;         const int col0 = u.pn * 256 + wc * 32 + 4 * fq, row0 = row_base + u.pm * 256 + wr * 64 + fr;
; #pragma unroll
;         for (int ai = 0; ai < 2; ++ai)
; #pragma unroll
;             for (int m = 0; m < 4; ++m) { const int row = row0 + ai * 128 + m * 16; float ss = 0.f;
; #pragma unroll
;                 for (int bj = 0; bj < 2; ++bj)
; #pragma unroll
;                     for (int n = 0; n < 2; ++n) { f32x4 v = acc[ai][bj][m][n]; const size_t idx = (size_t)row * 1024 + col0 + bj * 128 + n * 16;
;                         if (MODE == 0) v = v * up4(*(const u32x2*)(io + idx));
;                         else if (MODE == 1) v = up4(*(const u32x2*)(io + idx)) + up4(*(const u32x2*)(g2 + idx)) * v;
;                         else ss += (v[0] * v[0] + v[1] * v[1]) + (v[2] * v[2] + v[3] * v[3]);
;                         if (!DRYE || v[0] == 123.456f) *(u32x2*)(io + idx) = pk4(v); }
;                 if (MODE == 2 && !DRYE) { ss += __shfl_xor(ss, 16); ss += __shfl_xor(ss, 32); if (fq == 0) atomicAdd(rowss + row, ss); } }
	s_add_i32 s3, s3, s45
	v_lshl_add_u64 v[216:217], v[216:217], 0, s[14:15]
	s_mov_b32 m0, s3
	ds_read_b128 v[184:187], v149 offset:49152
	ds_read_b128 v[188:191], v149 offset:50176
	ds_read_b128 v[192:195], v149 offset:51200
	ds_read_b128 v[196:199], v149 offset:52224
	ds_read_b128 v[200:203], v149 offset:53248
	ds_read_b128 v[204:207], v149 offset:54272
	ds_read_b128 v[208:211], v149 offset:55296
	ds_read_b128 v[212:215], v149 offset:56320
	global_load_lds_dwordx4 v[216:217], off
	s_add_i32 m0, s3, 0x2000
	s_add_u32 s30, s30, 0x40080
	v_lshl_add_u64 v[216:217], v[218:219], 0, s[14:15]
	s_addc_u32 s31, s31, 0
	s_add_i32 s3, s33, s45
	global_load_lds_dwordx4 v[216:217], off
	v_lshl_add_u64 v[216:217], s[30:31], 0, v[128:129]
	s_mov_b32 m0, s3
	s_nop 0
	global_load_lds_dwordx4 v[216:217], off
	v_lshl_add_u64 v[216:217], s[30:31], 0, v[130:131]
	s_add_i32 m0, s3, 0x2000
	s_nop 0
	global_load_lds_dwordx4 v[216:217], off
	v_lshl_add_u64 v[216:217], v[220:221], 0, s[14:15]
	s_mov_b32 m0, s62
	s_nop 0
	global_load_lds_dwordx4 v[216:217], off
	v_lshl_add_u64 v[216:217], v[222:223], 0, s[14:15]
	s_mov_b32 m0, s63
	s_nop 0
	global_load_lds_dwordx4 v[216:217], off
	s_waitcnt vmcnt(8)
	s_waitcnt lgkmcnt(0)
	s_barrier
	s_setprio 1
	s_waitcnt lgkmcnt(0)
	v_mfma_f32_16x16x32_bf16 v[60:63], v[140:143], v[184:187], v[60:63]
	v_mfma_f32_16x16x32_bf16 v[56:59], v[156:159], v[184:187], v[56:59]
	v_mfma_f32_16x16x32_bf16 v[48:51], v[140:143], v[192:195], v[48:51]
	v_mfma_f32_16x16x32_bf16 v[40:43], v[156:159], v[192:195], v[40:43]
	v_mfma_f32_16x16x32_bf16 v[32:35], v[140:143], v[200:203], v[32:35]
	v_mfma_f32_16x16x32_bf16 v[24:27], v[156:159], v[200:203], v[24:27]
	v_mfma_f32_16x16x32_bf16 v[16:19], v[140:143], v[208:211], v[16:19]
	v_mfma_f32_16x16x32_bf16 v[8:11], v[156:159], v[208:211], v[8:11]
	v_mfma_f32_16x16x32_bf16 v[60:63], v[152:155], v[188:191], v[60:63]
	v_mfma_f32_16x16x32_bf16 v[56:59], v[160:163], v[188:191], v[56:59]
	v_mfma_f32_16x16x32_bf16 v[48:51], v[152:155], v[196:199], v[48:51]
	v_mfma_f32_16x16x32_bf16 v[40:43], v[160:163], v[196:199], v[40:43]
	v_mfma_f32_16x16x32_bf16 v[32:35], v[152:155], v[204:207], v[32:35]
	v_mfma_f32_16x16x32_bf16 v[24:27], v[160:163], v[204:207], v[24:27]
	v_mfma_f32_16x16x32_bf16 v[16:19], v[152:155], v[212:215], v[16:19]
	v_mfma_f32_16x16x32_bf16 v[8:11], v[160:163], v[212:215], v[8:11]
	s_setprio 0
	s_setprio 1
	v_mfma_f32_16x16x32_bf16 v[52:55], v[164:167], v[184:187], v[52:55]
	v_mfma_f32_16x16x32_bf16 v[44:47], v[172:175], v[184:187], v[44:47]
	v_mfma_f32_16x16x32_bf16 v[36:39], v[164:167], v[192:195], v[36:39]
	v_mfma_f32_16x16x32_bf16 v[28:31], v[172:175], v[192:195], v[28:31]
	v_mfma_f32_16x16x32_bf16 v[20:23], v[164:167], v[200:203], v[20:23]
	v_mfma_f32_16x16x32_bf16 v[12:15], v[172:175], v[200:203], v[12:15]
	v_mfma_f32_16x16x32_bf16 v[4:7], v[164:167], v[208:211], v[4:7]
	v_mfma_f32_16x16x32_bf16 v[0:3], v[172:175], v[208:211], v[0:3]
	v_mfma_f32_16x16x32_bf16 v[52:55], v[168:171], v[188:191], v[52:55]
	v_mfma_f32_16x16x32_bf16 v[44:47], v[180:183], v[188:191], v[44:47]
	v_mfma_f32_16x16x32_bf16 v[36:39], v[168:171], v[196:199], v[36:39]
	v_mfma_f32_16x16x32_bf16 v[28:31], v[180:183], v[196:199], v[28:31]
	v_mfma_f32_16x16x32_bf16 v[20:23], v[168:171], v[204:207], v[20:23]
	v_mfma_f32_16x16x32_bf16 v[12:15], v[180:183], v[204:207], v[12:15]
	v_mfma_f32_16x16x32_bf16 v[4:7], v[168:171], v[212:215], v[4:7]
	v_mfma_f32_16x16x32_bf16 v[0:3], v[180:183], v[212:215], v[0:3]
	s_setprio 0
	s_barrier
	s_add_i32 s72, s72, 2
	s_add_u32 s28, s28, 0x100
	s_addc_u32 s29, s29, 0
	s_add_u32 s70, s70, 0x100
	s_addc_u32 s71, s71, 0
	s_cmp_gt_u32 s72, 13
	s_cbranch_scc0 .LBB0_914
	v_and_b32_e32 v151, 64, v150
	v_xor_b32_e32 v143, 16, v150
	v_add_u32_e32 v151, 64, v151
	v_cmp_lt_i32_e32 vcc, v143, v151
	v_lshl_add_u32 v142, s24, 8, v144
	v_lshl_or_b32 v140, s26, 8, v146
	v_cndmask_b32_e32 v143, v150, v143, vcc
	v_lshlrev_b32_e32 v152, 2, v143
	v_xor_b32_e32 v143, 32, v150
	v_cmp_lt_i32_e32 vcc, v143, v151
	v_mul_f32_e32 v153, v125, v125
	v_mul_f32_e32 v156, v127, v127
	v_cndmask_b32_e32 v143, v150, v143, vcc
	v_lshlrev_b32_e32 v151, 2, v143
	v_ashrrev_i32_e32 v143, 31, v142
	v_lshlrev_b64 v[154:155], 11, v[142:143]
	v_ashrrev_i32_e32 v141, 31, v140
	v_fmac_f32_e32 v153, v124, v124
	v_fmac_f32_e32 v156, v126, v126
	v_cvt_pk_bf16_f32 v124, v124, v125
	v_cvt_pk_bf16_f32 v125, v126, v127
	v_lshl_add_u64 v[126:127], s[8:9], 0, v[154:155]
	v_lshl_add_u64 v[126:127], v[140:141], 1, v[126:127]
	global_store_dwordx2 v[126:127], v[124:125], off
	v_mul_f32_e32 v124, v121, v121
	v_mul_f32_e32 v125, v123, v123
	v_fmac_f32_e32 v124, v120, v120
	v_fmac_f32_e32 v125, v122, v122
	v_add_f32_e32 v124, v124, v125
	v_cvt_pk_bf16_f32 v120, v120, v121
	v_mul_f32_e32 v121, v117, v117
	v_mul_f32_e32 v125, v119, v119
	v_add_f32_e32 v153, v153, v156
	v_fmac_f32_e32 v121, v116, v116
	v_fmac_f32_e32 v125, v118, v118
	v_add_f32_e32 v124, v153, v124
	v_add_f32_e32 v121, v121, v125
	v_add_f32_e32 v121, v124, v121
	v_mul_f32_e32 v124, v109, v109
	v_mul_f32_e32 v125, v111, v111
	v_fmac_f32_e32 v124, v108, v108
	v_fmac_f32_e32 v125, v110, v110
	v_add_f32_e32 v124, v124, v125
	v_add_f32_e32 v124, v121, v124
	v_mov_b32_e32 v125, v124
	s_nop 1
	v_permlane16_swap_b32_e32 v124, v125
	v_cvt_pk_bf16_f32 v121, v122, v123
	global_store_dwordx2 v[126:127], v[120:121], off offset:32
	v_cvt_pk_bf16_f32 v120, v116, v117
	v_cvt_pk_bf16_f32 v121, v118, v119
	s_waitcnt lgkmcnt(0)
	v_add_f32_e32 v116, v124, v125
	v_mov_b32_e32 v117, v116
	s_nop 1
	v_permlane32_swap_b32_e32 v116, v117
	v_cvt_pk_bf16_f32 v108, v108, v109
	v_cvt_pk_bf16_f32 v109, v110, v111
	global_store_dwordx2 v[126:127], v[120:121], off offset:256
	global_store_dwordx2 v[126:127], v[108:109], off offset:288
	s_and_saveexec_b64 s[24:25], s[0:1]
	s_cbranch_execz .LBB0_917
	v_lshl_add_u64 v[108:109], v[142:143], 2, s[10:11]
	s_waitcnt lgkmcnt(0)
	v_add_f32_e32 v110, v116, v117
	global_atomic_add_f32 v[108:109], v110, off
; __device__ __forceinline__ u32x2 pk4(f32x4 v) { u32x2 w; w.x = cvt_pk_bf16(v[0], v[1]); w.y = cvt_pk_bf16(v[2], v[3]); return w; }
; __device__ __forceinline__ f32x4 up4(u32x2 w) { return (f32x4){bf_lo(w.x), bf_hi(w.x), bf_lo(w.y), bf_hi(w.y)}; }
;     __device__ __forceinline__ void operator()(const AccT& acc, const pg8::Unit& u, int wr, int wc, int fr, int fq) const {
;     ...
;             for (int m = 0; m < 4; ++m) { const int row = row0 + ai * 128 + m * 16; float ss = 0.f;
; #pragma unroll
;                 for (int bj = 0; bj < 2; ++bj)
; #pragma unroll
;                     for (int n = 0; n < 2; ++n) { f32x4 v = acc[ai][bj][m][n]; const size_t idx = (size_t)row * 1024 + col0 + bj * 128 + n * 16;
;                         if (MODE == 0) v = v * up4(*(const u32x2*)(io + idx));
;                         else if (MODE == 1) v = up4(*(const u32x2*)(io + idx)) + up4(*(const u32x2*)(g2 + idx)) * v;
;                         else ss += (v[0] * v[0] + v[1] * v[1]) + (v[2] * v[2] + v[3] * v[3]);
;                         if (!DRYE || v[0] == 123.456f) *(u32x2*)(io + idx) = pk4(v); }
;                 if (MODE == 2 && !DRYE) { ss += __shfl_xor(ss, 16); ss += __shfl_xor(ss, 32); if (fq == 0) atomicAdd(rowss + row, ss); } }
.LBB0_917:
	s_or_b64 exec, exec, s[24:25]
	v_or_b32_e32 v108, 16, v142
	v_ashrrev_i32_e32 v109, 31, v108
	v_lshlrev_b64 v[110:111], 11, v[108:109]
	v_mul_f32_e32 v116, v113, v113
	v_lshl_add_u64 v[110:111], s[8:9], 0, v[110:111]
	v_fmac_f32_e32 v116, v112, v112
	v_cvt_pk_bf16_f32 v112, v112, v113
	v_cvt_pk_bf16_f32 v113, v114, v115
	v_lshl_add_u64 v[110:111], v[140:141], 1, v[110:111]
	global_store_dwordx2 v[110:111], v[112:113], off
	v_mul_f32_e32 v112, v105, v105
	v_mul_f32_e32 v113, v107, v107
	s_waitcnt lgkmcnt(0)
	v_mul_f32_e32 v117, v115, v115
	v_fmac_f32_e32 v112, v104, v104
	v_fmac_f32_e32 v113, v106, v106
	v_fmac_f32_e32 v117, v114, v114
	v_add_f32_e32 v112, v112, v113
	v_cvt_pk_bf16_f32 v104, v104, v105
	v_mul_f32_e32 v105, v101, v101
	v_mul_f32_e32 v113, v103, v103
	v_add_f32_e32 v116, v116, v117
	v_fmac_f32_e32 v105, v100, v100
	v_fmac_f32_e32 v113, v102, v102
	v_add_f32_e32 v112, v116, v112
	v_add_f32_e32 v105, v105, v113
	v_add_f32_e32 v105, v112, v105
	v_mul_f32_e32 v112, v93, v93
	v_mul_f32_e32 v113, v95, v95
	v_fmac_f32_e32 v112, v92, v92
	v_fmac_f32_e32 v113, v94, v94
	v_add_f32_e32 v112, v112, v113
	v_add_f32_e32 v112, v105, v112
	v_mov_b32_e32 v113, v112
	s_nop 1
	v_permlane16_swap_b32_e32 v112, v113
	v_cvt_pk_bf16_f32 v105, v106, v107
	global_store_dwordx2 v[110:111], v[104:105], off offset:32
	v_cvt_pk_bf16_f32 v104, v100, v101
	v_cvt_pk_bf16_f32 v105, v102, v103
	s_waitcnt lgkmcnt(0)
	v_add_f32_e32 v100, v112, v113
	v_mov_b32_e32 v101, v100
	s_nop 1
	v_permlane32_swap_b32_e32 v100, v101
	v_cvt_pk_bf16_f32 v92, v92, v93
	v_cvt_pk_bf16_f32 v93, v94, v95
	global_store_dwordx2 v[110:111], v[104:105], off offset:256
	global_store_dwordx2 v[110:111], v[92:93], off offset:288
	s_and_saveexec_b64 s[24:25], s[0:1]
	s_cbranch_execz .LBB0_919
	v_lshl_add_u64 v[92:93], v[108:109], 2, s[10:11]
	s_waitcnt lgkmcnt(0)
	v_add_f32_e32 v94, v100, v101
	global_atomic_add_f32 v[92:93], v94, off
.LBB0_919:
	s_or_b64 exec, exec, s[24:25]
	v_or_b32_e32 v92, 32, v142
	v_ashrrev_i32_e32 v93, 31, v92
	v_lshlrev_b64 v[94:95], 11, v[92:93]
	v_mul_f32_e32 v100, v97, v97
	v_lshl_add_u64 v[94:95], s[8:9], 0, v[94:95]
	v_fmac_f32_e32 v100, v96, v96
	v_cvt_pk_bf16_f32 v96, v96, v97
	v_cvt_pk_bf16_f32 v97, v98, v99
	v_lshl_add_u64 v[94:95], v[140:141], 1, v[94:95]
	global_store_dwordx2 v[94:95], v[96:97], off
	v_mul_f32_e32 v96, v89, v89
	v_mul_f32_e32 v97, v91, v91
	s_waitcnt lgkmcnt(0)
	v_mul_f32_e32 v101, v99, v99
	v_fmac_f32_e32 v96, v88, v88
	v_fmac_f32_e32 v97, v90, v90
	v_fmac_f32_e32 v101, v98, v98
	v_add_f32_e32 v96, v96, v97
	v_cvt_pk_bf16_f32 v88, v88, v89
	v_mul_f32_e32 v89, v85, v85
	v_mul_f32_e32 v97, v87, v87
	v_add_f32_e32 v100, v100, v101
	v_fmac_f32_e32 v89, v84, v84
	v_fmac_f32_e32 v97, v86, v86
	v_add_f32_e32 v96, v100, v96
	v_add_f32_e32 v89, v89, v97
	v_add_f32_e32 v89, v96, v89
	v_mul_f32_e32 v96, v77, v77
	v_mul_f32_e32 v97, v79, v79
	v_fmac_f32_e32 v96, v76, v76
	v_fmac_f32_e32 v97, v78, v78
	v_add_f32_e32 v96, v96, v97
	v_add_f32_e32 v96, v89, v96
	v_mov_b32_e32 v97, v96
	s_nop 1
	v_permlane16_swap_b32_e32 v96, v97
	v_cvt_pk_bf16_f32 v89, v90, v91
	global_store_dwordx2 v[94:95], v[88:89], off offset:32
	v_cvt_pk_bf16_f32 v88, v84, v85
	v_cvt_pk_bf16_f32 v89, v86, v87
	s_waitcnt lgkmcnt(0)
	v_add_f32_e32 v84, v96, v97
	v_mov_b32_e32 v85, v84
	s_nop 1
	v_permlane32_swap_b32_e32 v84, v85
	v_cvt_pk_bf16_f32 v76, v76, v77
	v_cvt_pk_bf16_f32 v77, v78, v79
	global_store_dwordx2 v[94:95], v[88:89], off offset:256
	global_store_dwordx2 v[94:95], v[76:77], off offset:288
	s_and_saveexec_b64 s[24:25], s[0:1]
	s_cbranch_execz .LBB0_921
	v_lshl_add_u64 v[76:77], v[92:93], 2, s[10:11]
	s_waitcnt lgkmcnt(0)
	v_add_f32_e32 v78, v84, v85
	global_atomic_add_f32 v[76:77], v78, off
.LBB0_921:
	s_or_b64 exec, exec, s[24:25]
	v_or_b32_e32 v76, 48, v142
	v_ashrrev_i32_e32 v77, 31, v76
	v_lshlrev_b64 v[78:79], 11, v[76:77]
	v_mul_f32_e32 v84, v81, v81
	v_lshl_add_u64 v[78:79], s[8:9], 0, v[78:79]
	v_fmac_f32_e32 v84, v80, v80
	v_cvt_pk_bf16_f32 v80, v80, v81
	v_cvt_pk_bf16_f32 v81, v82, v83
	v_lshl_add_u64 v[78:79], v[140:141], 1, v[78:79]
	global_store_dwordx2 v[78:79], v[80:81], off
	v_mul_f32_e32 v80, v73, v73
	v_mul_f32_e32 v81, v75, v75
	s_waitcnt lgkmcnt(0)
	v_mul_f32_e32 v85, v83, v83
	v_fmac_f32_e32 v80, v72, v72
	v_fmac_f32_e32 v81, v74, v74
	v_fmac_f32_e32 v85, v82, v82
	v_add_f32_e32 v80, v80, v81
	v_cvt_pk_bf16_f32 v72, v72, v73
	v_mul_f32_e32 v73, v69, v69
	v_mul_f32_e32 v81, v71, v71
	v_add_f32_e32 v84, v84, v85
	v_fmac_f32_e32 v73, v68, v68
	v_fmac_f32_e32 v81, v70, v70
	v_add_f32_e32 v80, v84, v80
	v_add_f32_e32 v73, v73, v81
	v_add_f32_e32 v73, v80, v73
	v_mul_f32_e32 v80, v65, v65
	v_mul_f32_e32 v81, v67, v67
	v_fmac_f32_e32 v80, v64, v64
	v_fmac_f32_e32 v81, v66, v66
	v_add_f32_e32 v80, v80, v81
	v_add_f32_e32 v80, v73, v80
	v_mov_b32_e32 v81, v80
	s_nop 1
	v_permlane16_swap_b32_e32 v80, v81
	v_cvt_pk_bf16_f32 v73, v74, v75
	global_store_dwordx2 v[78:79], v[72:73], off offset:32
	v_cvt_pk_bf16_f32 v72, v68, v69
	v_cvt_pk_bf16_f32 v73, v70, v71
	s_waitcnt lgkmcnt(0)
	v_add_f32_e32 v68, v80, v81
	v_mov_b32_e32 v69, v68
	s_nop 1
	v_permlane32_swap_b32_e32 v68, v69
	v_cvt_pk_bf16_f32 v64, v64, v65
	v_cvt_pk_bf16_f32 v65, v66, v67
	global_store_dwordx2 v[78:79], v[72:73], off offset:256
	global_store_dwordx2 v[78:79], v[64:65], off offset:288
	s_and_saveexec_b64 s[24:25], s[0:1]
	s_cbranch_execz .LBB0_923
	v_lshl_add_u64 v[64:65], v[76:77], 2, s[10:11]
	s_waitcnt lgkmcnt(0)
	v_add_f32_e32 v66, v68, v69
	global_atomic_add_f32 v[64:65], v66, off
; __device__ __forceinline__ u32x2 pk4(f32x4 v) { u32x2 w; w.x = cvt_pk_bf16(v[0], v[1]); w.y = cvt_pk_bf16(v[2], v[3]); return w; }
; __device__ __forceinline__ f32x4 up4(u32x2 w) { return (f32x4){bf_lo(w.x), bf_hi(w.x), bf_lo(w.y), bf_hi(w.y)}; }
;     __device__ __forceinline__ void operator()(const AccT& acc, const pg8::Unit& u, int wr, int wc, int fr, int fq) const {
;     ...
;             for (int m = 0; m < 4; ++m) { const int row = row0 + ai * 128 + m * 16; float ss = 0.f;
; #pragma unroll
;                 for (int bj = 0; bj < 2; ++bj)
; #pragma unroll
;                     for (int n = 0; n < 2; ++n) { f32x4 v = acc[ai][bj][m][n]; const size_t idx = (size_t)row * 1024 + col0 + bj * 128 + n * 16;
;                         if (MODE == 0) v = v * up4(*(const u32x2*)(io + idx));
;                         else if (MODE == 1) v = up4(*(const u32x2*)(io + idx)) + up4(*(const u32x2*)(g2 + idx)) * v;
;                         else ss += (v[0] * v[0] + v[1] * v[1]) + (v[2] * v[2] + v[3] * v[3]);
;                         if (!DRYE || v[0] == 123.456f) *(u32x2*)(io + idx) = pk4(v); }
;                 if (MODE == 2 && !DRYE) { ss += __shfl_xor(ss, 16); ss += __shfl_xor(ss, 32); if (fq == 0) atomicAdd(rowss + row, ss); } }
.LBB0_923:
	s_or_b64 exec, exec, s[24:25]
	v_add_u32_e32 v64, 0x80, v142
	v_ashrrev_i32_e32 v65, 31, v64
	v_lshlrev_b64 v[66:67], 11, v[64:65]
	v_mul_f32_e32 v68, v61, v61
	s_waitcnt lgkmcnt(0)
	v_mul_f32_e32 v69, v63, v63
	v_fmac_f32_e32 v68, v60, v60
	v_fmac_f32_e32 v69, v62, v62
	v_cvt_pk_bf16_f32 v60, v60, v61
	v_cvt_pk_bf16_f32 v61, v62, v63
	v_lshl_add_u64 v[62:63], s[8:9], 0, v[66:67]
	v_lshl_add_u64 v[62:63], v[140:141], 1, v[62:63]
	global_store_dwordx2 v[62:63], v[60:61], off
	v_mul_f32_e32 v60, v57, v57
	v_mul_f32_e32 v61, v59, v59
	v_fmac_f32_e32 v60, v56, v56
	v_fmac_f32_e32 v61, v58, v58
	v_add_f32_e32 v60, v60, v61
	v_cvt_pk_bf16_f32 v56, v56, v57
	v_mul_f32_e32 v57, v53, v53
	v_mul_f32_e32 v61, v55, v55
	v_add_f32_e32 v68, v68, v69
	v_fmac_f32_e32 v57, v52, v52
	v_fmac_f32_e32 v61, v54, v54
	v_add_f32_e32 v60, v68, v60
	v_add_f32_e32 v57, v57, v61
	v_add_f32_e32 v57, v60, v57
	v_mul_f32_e32 v60, v45, v45
	v_mul_f32_e32 v61, v47, v47
	v_fmac_f32_e32 v60, v44, v44
	v_fmac_f32_e32 v61, v46, v46
	v_add_f32_e32 v60, v60, v61
	v_add_f32_e32 v60, v57, v60
	v_mov_b32_e32 v61, v60
	s_nop 1
	v_permlane16_swap_b32_e32 v60, v61
	v_cvt_pk_bf16_f32 v57, v58, v59
	global_store_dwordx2 v[62:63], v[56:57], off offset:32
	v_cvt_pk_bf16_f32 v56, v52, v53
	v_cvt_pk_bf16_f32 v57, v54, v55
	s_waitcnt lgkmcnt(0)
	v_add_f32_e32 v52, v60, v61
	v_mov_b32_e32 v53, v52
	s_nop 1
	v_permlane32_swap_b32_e32 v52, v53
	v_cvt_pk_bf16_f32 v44, v44, v45
	v_cvt_pk_bf16_f32 v45, v46, v47
	global_store_dwordx2 v[62:63], v[56:57], off offset:256
	global_store_dwordx2 v[62:63], v[44:45], off offset:288
	s_and_saveexec_b64 s[24:25], s[0:1]
	s_cbranch_execz .LBB0_925
	v_lshl_add_u64 v[44:45], v[64:65], 2, s[10:11]
	s_waitcnt lgkmcnt(0)
	v_add_f32_e32 v46, v52, v53
	global_atomic_add_f32 v[44:45], v46, off
.LBB0_925:
	s_or_b64 exec, exec, s[24:25]
	v_add_u32_e32 v44, 0x90, v142
	v_ashrrev_i32_e32 v45, 31, v44
	v_lshlrev_b64 v[46:47], 11, v[44:45]
	v_mul_f32_e32 v52, v49, v49
	v_lshl_add_u64 v[46:47], s[8:9], 0, v[46:47]
	v_fmac_f32_e32 v52, v48, v48
	v_cvt_pk_bf16_f32 v48, v48, v49
	v_cvt_pk_bf16_f32 v49, v50, v51
	v_lshl_add_u64 v[46:47], v[140:141], 1, v[46:47]
	global_store_dwordx2 v[46:47], v[48:49], off
	v_mul_f32_e32 v48, v41, v41
	v_mul_f32_e32 v49, v43, v43
	s_waitcnt lgkmcnt(0)
	v_mul_f32_e32 v53, v51, v51
	v_fmac_f32_e32 v48, v40, v40
	v_fmac_f32_e32 v49, v42, v42
	v_fmac_f32_e32 v53, v50, v50
	v_add_f32_e32 v48, v48, v49
	v_cvt_pk_bf16_f32 v40, v40, v41
	v_mul_f32_e32 v41, v37, v37
	v_mul_f32_e32 v49, v39, v39
	v_add_f32_e32 v52, v52, v53
	v_fmac_f32_e32 v41, v36, v36
	v_fmac_f32_e32 v49, v38, v38
	v_add_f32_e32 v48, v52, v48
	v_add_f32_e32 v41, v41, v49
	v_add_f32_e32 v41, v48, v41
	v_mul_f32_e32 v48, v29, v29
	v_mul_f32_e32 v49, v31, v31
	v_fmac_f32_e32 v48, v28, v28
	v_fmac_f32_e32 v49, v30, v30
	v_add_f32_e32 v48, v48, v49
	v_add_f32_e32 v48, v41, v48
	v_mov_b32_e32 v49, v48
	s_nop 1
	v_permlane16_swap_b32_e32 v48, v49
	v_cvt_pk_bf16_f32 v41, v42, v43
	global_store_dwordx2 v[46:47], v[40:41], off offset:32
	v_cvt_pk_bf16_f32 v40, v36, v37
	v_cvt_pk_bf16_f32 v41, v38, v39
	s_waitcnt lgkmcnt(0)
	v_add_f32_e32 v36, v48, v49
	v_mov_b32_e32 v37, v36
	s_nop 1
	v_permlane32_swap_b32_e32 v36, v37
	v_cvt_pk_bf16_f32 v28, v28, v29
	v_cvt_pk_bf16_f32 v29, v30, v31
	global_store_dwordx2 v[46:47], v[40:41], off offset:256
	global_store_dwordx2 v[46:47], v[28:29], off offset:288
	s_and_saveexec_b64 s[24:25], s[0:1]
	s_cbranch_execz .LBB0_927
	v_lshl_add_u64 v[28:29], v[44:45], 2, s[10:11]
	s_waitcnt lgkmcnt(0)
	v_add_f32_e32 v30, v36, v37
	global_atomic_add_f32 v[28:29], v30, off
; __device__ __forceinline__ u32x2 pk4(f32x4 v) { u32x2 w; w.x = cvt_pk_bf16(v[0], v[1]); w.y = cvt_pk_bf16(v[2], v[3]); return w; }
; __device__ __forceinline__ f32x4 up4(u32x2 w) { return (f32x4){bf_lo(w.x), bf_hi(w.x), bf_lo(w.y), bf_hi(w.y)}; }
;     __device__ __forceinline__ void operator()(const AccT& acc, const pg8::Unit& u, int wr, int wc, int fr, int fq) const {
;     ...
;             for (int m = 0; m < 4; ++m) { const int row = row0 + ai * 128 + m * 16; float ss = 0.f;
; #pragma unroll
;                 for (int bj = 0; bj < 2; ++bj)
; #pragma unroll
;                     for (int n = 0; n < 2; ++n) { f32x4 v = acc[ai][bj][m][n]; const size_t idx = (size_t)row * 1024 + col0 + bj * 128 + n * 16;
;                         if (MODE == 0) v = v * up4(*(const u32x2*)(io + idx));
;                         else if (MODE == 1) v = up4(*(const u32x2*)(io + idx)) + up4(*(const u32x2*)(g2 + idx)) * v;
;                         else ss += (v[0] * v[0] + v[1] * v[1]) + (v[2] * v[2] + v[3] * v[3]);
;                         if (!DRYE || v[0] == 123.456f) *(u32x2*)(io + idx) = pk4(v); }
;                 if (MODE == 2 && !DRYE) { ss += __shfl_xor(ss, 16); ss += __shfl_xor(ss, 32); if (fq == 0) atomicAdd(rowss + row, ss); } }
.LBB0_927:
	s_or_b64 exec, exec, s[24:25]
	v_add_u32_e32 v28, 0xa0, v142
	v_ashrrev_i32_e32 v29, 31, v28
	v_lshlrev_b64 v[30:31], 11, v[28:29]
	v_mul_f32_e32 v36, v33, v33
	v_lshl_add_u64 v[30:31], s[8:9], 0, v[30:31]
	v_fmac_f32_e32 v36, v32, v32
	v_cvt_pk_bf16_f32 v32, v32, v33
	v_cvt_pk_bf16_f32 v33, v34, v35
	v_lshl_add_u64 v[30:31], v[140:141], 1, v[30:31]
	global_store_dwordx2 v[30:31], v[32:33], off
	v_mul_f32_e32 v32, v25, v25
	v_mul_f32_e32 v33, v27, v27
	s_waitcnt lgkmcnt(0)
	v_mul_f32_e32 v37, v35, v35
	v_fmac_f32_e32 v32, v24, v24
	v_fmac_f32_e32 v33, v26, v26
	v_fmac_f32_e32 v37, v34, v34
	v_add_f32_e32 v32, v32, v33
	v_cvt_pk_bf16_f32 v24, v24, v25
	v_mul_f32_e32 v25, v21, v21
	v_mul_f32_e32 v33, v23, v23
	v_add_f32_e32 v36, v36, v37
	v_fmac_f32_e32 v25, v20, v20
	v_fmac_f32_e32 v33, v22, v22
	v_add_f32_e32 v32, v36, v32
	v_add_f32_e32 v25, v25, v33
	v_add_f32_e32 v25, v32, v25
	v_mul_f32_e32 v32, v13, v13
	v_mul_f32_e32 v33, v15, v15
	v_fmac_f32_e32 v32, v12, v12
	v_fmac_f32_e32 v33, v14, v14
	v_add_f32_e32 v32, v32, v33
	v_add_f32_e32 v32, v25, v32
	v_mov_b32_e32 v33, v32
	s_nop 1
	v_permlane16_swap_b32_e32 v32, v33
	v_cvt_pk_bf16_f32 v25, v26, v27
	global_store_dwordx2 v[30:31], v[24:25], off offset:32
	v_cvt_pk_bf16_f32 v24, v20, v21
	v_cvt_pk_bf16_f32 v25, v22, v23
	s_waitcnt lgkmcnt(0)
	v_add_f32_e32 v20, v32, v33
	v_mov_b32_e32 v21, v20
	s_nop 1
	v_permlane32_swap_b32_e32 v20, v21
	v_cvt_pk_bf16_f32 v12, v12, v13
	v_cvt_pk_bf16_f32 v13, v14, v15
	global_store_dwordx2 v[30:31], v[24:25], off offset:256
	global_store_dwordx2 v[30:31], v[12:13], off offset:288
	s_and_saveexec_b64 s[24:25], s[0:1]
	s_cbranch_execz .LBB0_929
	v_lshl_add_u64 v[12:13], v[28:29], 2, s[10:11]
	s_waitcnt lgkmcnt(0)
	v_add_f32_e32 v14, v20, v21
	global_atomic_add_f32 v[12:13], v14, off
.LBB0_929:
	s_or_b64 exec, exec, s[24:25]
	v_add_u32_e32 v12, 0xb0, v142
	v_ashrrev_i32_e32 v13, 31, v12
	v_lshlrev_b64 v[14:15], 11, v[12:13]
	v_mul_f32_e32 v20, v17, v17
	v_lshl_add_u64 v[14:15], s[8:9], 0, v[14:15]
	v_fmac_f32_e32 v20, v16, v16
	v_cvt_pk_bf16_f32 v16, v16, v17
	v_cvt_pk_bf16_f32 v17, v18, v19
	v_lshl_add_u64 v[14:15], v[140:141], 1, v[14:15]
	global_store_dwordx2 v[14:15], v[16:17], off
	v_mul_f32_e32 v16, v9, v9
	v_mul_f32_e32 v17, v11, v11
	s_waitcnt lgkmcnt(0)
	v_mul_f32_e32 v21, v19, v19
	v_fmac_f32_e32 v16, v8, v8
	v_fmac_f32_e32 v17, v10, v10
	v_fmac_f32_e32 v21, v18, v18
	v_add_f32_e32 v16, v16, v17
	v_cvt_pk_bf16_f32 v8, v8, v9
	v_mul_f32_e32 v9, v5, v5
	v_mul_f32_e32 v17, v7, v7
	v_add_f32_e32 v20, v20, v21
	v_fmac_f32_e32 v9, v4, v4
	v_fmac_f32_e32 v17, v6, v6
	v_add_f32_e32 v16, v20, v16
	v_add_f32_e32 v9, v9, v17
	v_add_f32_e32 v9, v16, v9
	v_mul_f32_e32 v16, v1, v1
	v_mul_f32_e32 v17, v3, v3
	v_fmac_f32_e32 v16, v0, v0
	v_fmac_f32_e32 v17, v2, v2
	v_add_f32_e32 v16, v16, v17
	v_add_f32_e32 v16, v9, v16
	v_mov_b32_e32 v17, v16
	s_nop 1
	v_permlane16_swap_b32_e32 v16, v17
	v_cvt_pk_bf16_f32 v9, v10, v11
	global_store_dwordx2 v[14:15], v[8:9], off offset:32
	v_cvt_pk_bf16_f32 v8, v4, v5
	v_cvt_pk_bf16_f32 v9, v6, v7
	s_waitcnt lgkmcnt(0)
	v_add_f32_e32 v4, v16, v17
	v_mov_b32_e32 v5, v4
	s_nop 1
	v_permlane32_swap_b32_e32 v4, v5
	v_cvt_pk_bf16_f32 v0, v0, v1
	v_cvt_pk_bf16_f32 v1, v2, v3
	global_store_dwordx2 v[14:15], v[8:9], off offset:256
	global_store_dwordx2 v[14:15], v[0:1], off offset:288
	s_and_saveexec_b64 s[24:25], s[0:1]
	s_cbranch_execz .LBB0_906
	v_lshl_add_u64 v[0:1], v[12:13], 2, s[10:11]
	s_waitcnt lgkmcnt(0)
	v_add_f32_e32 v2, v4, v5
	global_atomic_add_f32 v[0:1], v2, off
	s_branch .LBB0_906

; #define PG8_STAGE(bufoff, gbase, voff) do { _Pragma("unroll") for (int _i = 0; _i < 2; ++_i) \
;         __builtin_amdgcn_global_load_lds((const unsigned*)((const char*)(gbase) + (voff)[_i]), (PG8_LAS unsigned*)(lds + (bufoff) + ldsw + _i * 8192), 16, 0, 0); } while (0)
; #define PG8_LDA(dst, b, h) do { _Pragma("unroll") for (int m = 0; m < 4; ++m) _Pragma("unroll") for (int k = 0; k < 2; ++k) dst[m][k] = *(const PG8_LAS bf16x8*)(lds + PG8_SA(b, h) + aoff + m * 2048 + k * 1024); } while (0)
; #define PG8_LDB(dst, b, h) do { _Pragma("unroll") for (int n = 0; n < 2; ++n) _Pragma("unroll") for (int k = 0; k < 2; ++k) dst[n][k] = *(const PG8_LAS bf16x8*)(lds + PG8_SB(b, h) + boff + n * 2048 + k * 1024); } while (0)
; #define PG8_MMA(ai, bj, At, Bt) do { __builtin_amdgcn_s_setprio(1); _Pragma("unroll") for (int m = 0; m < 4; ++m) _Pragma("unroll") for (int n = 0; n < 2; ++n) _Pragma("unroll") for (int k = 0; k < 2; ++k) \
;         acc[ai][bj][m][n] = __builtin_amdgcn_mfma_f32_16x16x32_bf16(Bt[n][k], At[m][k], acc[ai][bj][m][n], 0, 0, 0); __builtin_amdgcn_s_setprio(0); } while (0)
; #define PG8_WAIT_V(n) asm volatile("s_waitcnt vmcnt(" #n ")" ::: "memory")
; #define PG8_WAIT_L(n) asm volatile("s_waitcnt lgkmcnt(" #n ")" ::: "memory")
; #define PG8_BAR __builtin_amdgcn_s_barrier()
; #define PG8_SCHED __builtin_amdgcn_sched_barrier(0)
; template <class Epi, class Sched, bool ALIGN_EPI = false, bool SP2 = false>
; __device__ __forceinline__ void gemm_phase(PG8_LAS unsigned char* lds, const Gemm g, const Sched& S, const Epi& E) {
;     ...
;             PG8_LDB(B0, 0, 0); PG8_LDB(B1, 0, 1); PG8_SCHED; PG8_LDA(At, 0, 0); PG8_STAGE(PG8_SA(1, 1), a1 + hstep, voffA);
;             PG8_WAIT_V(8); PG8_WAIT_L(0); PG8_BAR; PG8_MMA(0, 0, At, B0); PG8_MMA(0, 1, At, B1); PG8_BAR; PG8_SCHED;
;             PG8_LDA(At, 0, 1); PG8_STAGE(PG8_SB(0, 0), b2, voffB); PG8_STAGE(PG8_SB(0, 1), b2 + hstep, voffB); PG8_STAGE(PG8_SA(0, 0), a2, voffA);
;             PG8_WAIT_V(8); PG8_WAIT_L(0); PG8_BAR; PG8_MMA(1, 0, At, B0); PG8_MMA(1, 1, At, B1); PG8_BAR; PG8_SCHED;
.LBB0_1059:
	ds_read_b128 v[136:139], v143
	ds_read_b128 v[148:151], v143 offset:1024
	ds_read_b128 v[152:155], v143 offset:2048
	ds_read_b128 v[156:159], v143 offset:3072
	ds_read_b128 v[160:163], v144
	ds_read_b128 v[164:167], v144 offset:1024
	ds_read_b128 v[168:171], v144 offset:2048
	ds_read_b128 v[172:175], v144 offset:3072
	s_add_u32 s3, s28, 0xfffc0080
	s_addc_u32 s30, s29, -1
	s_cmp_eq_u32 s71, 12
	s_cselect_b32 s35, s21, s30
	s_cselect_b32 s34, s67, s3
	s_cselect_b32 s31, s19, s70
	s_cselect_b32 s30, s68, s69
	v_lshl_add_u64 v[212:213], s[28:29], 0, v[132:133]
	s_add_i32 m0, s47, 0xc000
	ds_read_b128 v[180:183], v145
	ds_read_b128 v[184:187], v145 offset:1024
	ds_read_b128 v[188:191], v145 offset:2048
	ds_read_b128 v[192:195], v145 offset:3072
	ds_read_b128 v[196:199], v145 offset:4096
	ds_read_b128 v[200:203], v145 offset:5120
	ds_read_b128 v[204:207], v145 offset:6144
	ds_read_b128 v[208:211], v145 offset:7168
	global_load_lds_dwordx4 v[212:213], off
	v_lshl_add_u64 v[212:213], s[28:29], 0, v[134:135]
	s_add_i32 m0, s47, 0xe000
	s_nop 0
	global_load_lds_dwordx4 v[212:213], off
	s_waitcnt vmcnt(8)
	s_waitcnt lgkmcnt(0)
	s_barrier
	s_setprio 1
	s_waitcnt lgkmcnt(0)
	v_mfma_f32_16x16x32_bf16 v[124:127], v[136:139], v[180:183], v[124:127]
	v_mfma_f32_16x16x32_bf16 v[120:123], v[152:155], v[180:183], v[120:123]
	v_mfma_f32_16x16x32_bf16 v[112:115], v[136:139], v[188:191], v[112:115]
	v_mfma_f32_16x16x32_bf16 v[104:107], v[152:155], v[188:191], v[104:107]
	v_mfma_f32_16x16x32_bf16 v[96:99], v[136:139], v[196:199], v[96:99]
	v_mfma_f32_16x16x32_bf16 v[88:91], v[152:155], v[196:199], v[88:91]
	v_mfma_f32_16x16x32_bf16 v[80:83], v[136:139], v[204:207], v[80:83]
	v_mfma_f32_16x16x32_bf16 v[72:75], v[152:155], v[204:207], v[72:75]
	v_mfma_f32_16x16x32_bf16 v[124:127], v[148:151], v[184:187], v[124:127]
	v_mfma_f32_16x16x32_bf16 v[120:123], v[156:159], v[184:187], v[120:123]
	v_mfma_f32_16x16x32_bf16 v[112:115], v[148:151], v[192:195], v[112:115]
	v_mfma_f32_16x16x32_bf16 v[104:107], v[156:159], v[192:195], v[104:107]
	v_mfma_f32_16x16x32_bf16 v[96:99], v[148:151], v[200:203], v[96:99]
	v_mfma_f32_16x16x32_bf16 v[88:91], v[156:159], v[200:203], v[88:91]
	v_mfma_f32_16x16x32_bf16 v[80:83], v[148:151], v[208:211], v[80:83]
	v_mfma_f32_16x16x32_bf16 v[72:75], v[156:159], v[208:211], v[72:75]
	s_setprio 0
	s_setprio 1
	v_mfma_f32_16x16x32_bf16 v[116:119], v[160:163], v[180:183], v[116:119]
	v_mfma_f32_16x16x32_bf16 v[108:111], v[168:171], v[180:183], v[108:111]
	v_mfma_f32_16x16x32_bf16 v[100:103], v[160:163], v[188:191], v[100:103]
	v_mfma_f32_16x16x32_bf16 v[92:95], v[168:171], v[188:191], v[92:95]
	v_mfma_f32_16x16x32_bf16 v[84:87], v[160:163], v[196:199], v[84:87]
	v_mfma_f32_16x16x32_bf16 v[76:79], v[168:171], v[196:199], v[76:79]
	v_mfma_f32_16x16x32_bf16 v[68:71], v[160:163], v[204:207], v[68:71]
	v_mfma_f32_16x16x32_bf16 v[64:67], v[168:171], v[204:207], v[64:67]
	v_mfma_f32_16x16x32_bf16 v[116:119], v[164:167], v[184:187], v[116:119]
	v_mfma_f32_16x16x32_bf16 v[108:111], v[172:175], v[184:187], v[108:111]
	v_mfma_f32_16x16x32_bf16 v[100:103], v[164:167], v[192:195], v[100:103]
	v_mfma_f32_16x16x32_bf16 v[92:95], v[172:175], v[192:195], v[92:95]
	v_mfma_f32_16x16x32_bf16 v[84:87], v[164:167], v[200:203], v[84:87]
	v_mfma_f32_16x16x32_bf16 v[76:79], v[172:175], v[200:203], v[76:79]
	v_mfma_f32_16x16x32_bf16 v[68:71], v[164:167], v[208:211], v[68:71]
	v_mfma_f32_16x16x32_bf16 v[64:67], v[172:175], v[208:211], v[64:67]
	s_setprio 0
	s_barrier
	s_add_i32 s3, s65, s46
	v_lshl_add_u64 v[212:213], s[30:31], 0, v[128:129]
	s_mov_b32 m0, s3
	ds_read_b128 v[180:183], v145 offset:16384
	ds_read_b128 v[184:187], v145 offset:17408
	ds_read_b128 v[188:191], v145 offset:18432
	ds_read_b128 v[192:195], v145 offset:19456
	ds_read_b128 v[196:199], v145 offset:20480
	ds_read_b128 v[200:203], v145 offset:21504
	ds_read_b128 v[204:207], v145 offset:22528
	ds_read_b128 v[208:211], v145 offset:23552
	global_load_lds_dwordx4 v[212:213], off
	s_add_i32 m0, s3, 0x2000
	s_add_u32 s36, s30, 0x40000
	v_lshl_add_u64 v[214:215], s[30:31], 0, v[130:131]
	s_addc_u32 s37, s31, 0
	s_add_i32 s3, s66, s46
	global_load_lds_dwordx4 v[214:215], off
	v_lshl_add_u64 v[216:217], s[36:37], 0, v[128:129]
	s_mov_b32 m0, s3
	v_lshl_add_u64 v[218:219], s[34:35], 0, v[130:131]
	global_load_lds_dwordx4 v[216:217], off
	v_lshl_add_u64 v[216:217], s[36:37], 0, v[130:131]
	s_add_i32 m0, s3, 0x2000
	s_nop 0
	global_load_lds_dwordx4 v[216:217], off
	v_lshl_add_u64 v[216:217], s[34:35], 0, v[128:129]
	s_mov_b32 m0, s47
	s_nop 0
	global_load_lds_dwordx4 v[216:217], off
	s_mov_b32 m0, s60
	s_nop 0
	global_load_lds_dwordx4 v[218:219], off
	s_waitcnt vmcnt(8)
	s_waitcnt lgkmcnt(0)
	s_barrier
; #define PG8_STAGE(bufoff, gbase, voff) do { _Pragma("unroll") for (int _i = 0; _i < 2; ++_i) \
;         __builtin_amdgcn_global_load_lds((const unsigned*)((const char*)(gbase) + (voff)[_i]), (PG8_LAS unsigned*)(lds + (bufoff) + ldsw + _i * 8192), 16, 0, 0); } while (0)
; #define PG8_LDA(dst, b, h) do { _Pragma("unroll") for (int m = 0; m < 4; ++m) _Pragma("unroll") for (int k = 0; k < 2; ++k) dst[m][k] = *(const PG8_LAS bf16x8*)(lds + PG8_SA(b, h) + aoff + m * 2048 + k * 1024); } while (0)
; #define PG8_LDB(dst, b, h) do { _Pragma("unroll") for (int n = 0; n < 2; ++n) _Pragma("unroll") for (int k = 0; k < 2; ++k) dst[n][k] = *(const PG8_LAS bf16x8*)(lds + PG8_SB(b, h) + boff + n * 2048 + k * 1024); } while (0)
; #define PG8_MMA(ai, bj, At, Bt) do { __builtin_amdgcn_s_setprio(1); _Pragma("unroll") for (int m = 0; m < 4; ++m) _Pragma("unroll") for (int n = 0; n < 2; ++n) _Pragma("unroll") for (int k = 0; k < 2; ++k) \
;         acc[ai][bj][m][n] = __builtin_amdgcn_mfma_f32_16x16x32_bf16(Bt[n][k], At[m][k], acc[ai][bj][m][n], 0, 0, 0); __builtin_amdgcn_s_setprio(0); } while (0)
; #define PG8_WAIT_V(n) asm volatile("s_waitcnt vmcnt(" #n ")" ::: "memory")
; #define PG8_WAIT_L(n) asm volatile("s_waitcnt lgkmcnt(" #n ")" ::: "memory")
; #define PG8_BAR __builtin_amdgcn_s_barrier()
; #define PG8_SCHED __builtin_amdgcn_sched_barrier(0)
; template <class Epi, class Sched, bool ALIGN_EPI = false, bool SP2 = false>
; __device__ __forceinline__ void gemm_phase(PG8_LAS unsigned char* lds, const Gemm g, const Sched& S, const Epi& E) {
;     ...
;             PG8_WAIT_V(8); PG8_WAIT_L(0); PG8_BAR; PG8_MMA(1, 0, At, B0); PG8_MMA(1, 1, At, B1); PG8_BAR; PG8_SCHED;
;             PG8_LDB(B0, 1, 0); PG8_LDB(B1, 1, 1); PG8_SCHED; PG8_LDA(At, 1, 0); PG8_STAGE(PG8_SA(0, 1), a2 + hstep, voffA);
;             PG8_WAIT_V(8); PG8_WAIT_L(0); PG8_BAR; PG8_MMA(0, 0, At, B0); PG8_MMA(0, 1, At, B1); PG8_BAR; PG8_SCHED;
	s_setprio 1
	s_waitcnt lgkmcnt(0)
	v_mfma_f32_16x16x32_bf16 v[60:63], v[136:139], v[180:183], v[60:63]
	v_mfma_f32_16x16x32_bf16 v[56:59], v[152:155], v[180:183], v[56:59]
	v_mfma_f32_16x16x32_bf16 v[48:51], v[136:139], v[188:191], v[48:51]
	v_mfma_f32_16x16x32_bf16 v[40:43], v[152:155], v[188:191], v[40:43]
	v_mfma_f32_16x16x32_bf16 v[32:35], v[136:139], v[196:199], v[32:35]
	v_mfma_f32_16x16x32_bf16 v[24:27], v[152:155], v[196:199], v[24:27]
	v_mfma_f32_16x16x32_bf16 v[16:19], v[136:139], v[204:207], v[16:19]
	v_mfma_f32_16x16x32_bf16 v[8:11], v[152:155], v[204:207], v[8:11]
	v_mfma_f32_16x16x32_bf16 v[60:63], v[148:151], v[184:187], v[60:63]
	v_mfma_f32_16x16x32_bf16 v[56:59], v[156:159], v[184:187], v[56:59]
	v_mfma_f32_16x16x32_bf16 v[48:51], v[148:151], v[192:195], v[48:51]
	v_mfma_f32_16x16x32_bf16 v[40:43], v[156:159], v[192:195], v[40:43]
	v_mfma_f32_16x16x32_bf16 v[32:35], v[148:151], v[200:203], v[32:35]
	v_mfma_f32_16x16x32_bf16 v[24:27], v[156:159], v[200:203], v[24:27]
	v_mfma_f32_16x16x32_bf16 v[16:19], v[148:151], v[208:211], v[16:19]
	v_mfma_f32_16x16x32_bf16 v[8:11], v[156:159], v[208:211], v[8:11]
	s_setprio 0
	s_setprio 1
	v_mfma_f32_16x16x32_bf16 v[52:55], v[160:163], v[180:183], v[52:55]
	v_mfma_f32_16x16x32_bf16 v[44:47], v[168:171], v[180:183], v[44:47]
	v_mfma_f32_16x16x32_bf16 v[36:39], v[160:163], v[188:191], v[36:39]
	v_mfma_f32_16x16x32_bf16 v[28:31], v[168:171], v[188:191], v[28:31]
	v_mfma_f32_16x16x32_bf16 v[20:23], v[160:163], v[196:199], v[20:23]
	v_mfma_f32_16x16x32_bf16 v[12:15], v[168:171], v[196:199], v[12:15]
	v_mfma_f32_16x16x32_bf16 v[4:7], v[160:163], v[204:207], v[4:7]
	v_mfma_f32_16x16x32_bf16 v[0:3], v[168:171], v[204:207], v[0:3]
	v_mfma_f32_16x16x32_bf16 v[52:55], v[164:167], v[184:187], v[52:55]
	v_mfma_f32_16x16x32_bf16 v[44:47], v[172:175], v[184:187], v[44:47]
	v_mfma_f32_16x16x32_bf16 v[36:39], v[164:167], v[192:195], v[36:39]
	v_mfma_f32_16x16x32_bf16 v[28:31], v[172:175], v[192:195], v[28:31]
	v_mfma_f32_16x16x32_bf16 v[20:23], v[164:167], v[200:203], v[20:23]
	v_mfma_f32_16x16x32_bf16 v[12:15], v[172:175], v[200:203], v[12:15]
	v_mfma_f32_16x16x32_bf16 v[4:7], v[164:167], v[208:211], v[4:7]
	v_mfma_f32_16x16x32_bf16 v[0:3], v[172:175], v[208:211], v[0:3]
	s_setprio 0
	s_barrier
	s_add_i32 s3, 0, 0x18000
	v_add_u32_e32 v147, s3, v141
	s_add_i32 s33, 0, 0x1c000
	ds_read_b128 v[136:139], v147
	ds_read_b128 v[148:151], v147 offset:1024
	ds_read_b128 v[152:155], v147 offset:2048
	ds_read_b128 v[156:159], v147 offset:3072
	v_add_u32_e32 v147, s33, v141
	ds_read_b128 v[160:163], v147
	ds_read_b128 v[164:167], v147 offset:1024
	ds_read_b128 v[168:171], v147 offset:2048
	ds_read_b128 v[172:175], v147 offset:3072
	s_add_u32 s34, s34, 0x40000
	s_addc_u32 s35, s35, 0
	s_mov_b32 m0, s61
	v_lshl_add_u64 v[220:221], s[34:35], 0, v[128:129]
	ds_read_b128 v[180:183], v145 offset:32768
	ds_read_b128 v[184:187], v145 offset:33792
	ds_read_b128 v[188:191], v145 offset:34816
	ds_read_b128 v[192:195], v145 offset:35840
	ds_read_b128 v[196:199], v145 offset:36864
	ds_read_b128 v[200:203], v145 offset:37888
	ds_read_b128 v[204:207], v145 offset:38912
	ds_read_b128 v[208:211], v145 offset:39936
	global_load_lds_dwordx4 v[220:221], off
	v_lshl_add_u64 v[220:221], s[34:35], 0, v[130:131]
	s_mov_b32 m0, s62
	s_nop 0
	global_load_lds_dwordx4 v[220:221], off
	s_waitcnt vmcnt(8)
	s_waitcnt lgkmcnt(0)
	s_barrier
	s_setprio 1
	s_waitcnt lgkmcnt(0)
	v_mfma_f32_16x16x32_bf16 v[124:127], v[136:139], v[180:183], v[124:127]
	v_mfma_f32_16x16x32_bf16 v[120:123], v[152:155], v[180:183], v[120:123]
	v_mfma_f32_16x16x32_bf16 v[112:115], v[136:139], v[188:191], v[112:115]
	v_mfma_f32_16x16x32_bf16 v[104:107], v[152:155], v[188:191], v[104:107]
	v_mfma_f32_16x16x32_bf16 v[96:99], v[136:139], v[196:199], v[96:99]
	v_mfma_f32_16x16x32_bf16 v[88:91], v[152:155], v[196:199], v[88:91]
	v_mfma_f32_16x16x32_bf16 v[80:83], v[136:139], v[204:207], v[80:83]
	v_mfma_f32_16x16x32_bf16 v[72:75], v[152:155], v[204:207], v[72:75]
	v_mfma_f32_16x16x32_bf16 v[124:127], v[148:151], v[184:187], v[124:127]
	v_mfma_f32_16x16x32_bf16 v[120:123], v[156:159], v[184:187], v[120:123]
	v_mfma_f32_16x16x32_bf16 v[112:115], v[148:151], v[192:195], v[112:115]
	v_mfma_f32_16x16x32_bf16 v[104:107], v[156:159], v[192:195], v[104:107]
	v_mfma_f32_16x16x32_bf16 v[96:99], v[148:151], v[200:203], v[96:99]
	v_mfma_f32_16x16x32_bf16 v[88:91], v[156:159], v[200:203], v[88:91]
	v_mfma_f32_16x16x32_bf16 v[80:83], v[148:151], v[208:211], v[80:83]
	v_mfma_f32_16x16x32_bf16 v[72:75], v[156:159], v[208:211], v[72:75]
	s_setprio 0
	s_setprio 1
	v_mfma_f32_16x16x32_bf16 v[116:119], v[160:163], v[180:183], v[116:119]
	v_mfma_f32_16x16x32_bf16 v[108:111], v[168:171], v[180:183], v[108:111]
	v_mfma_f32_16x16x32_bf16 v[100:103], v[160:163], v[188:191], v[100:103]
	v_mfma_f32_16x16x32_bf16 v[92:95], v[168:171], v[188:191], v[92:95]
	v_mfma_f32_16x16x32_bf16 v[84:87], v[160:163], v[196:199], v[84:87]
	v_mfma_f32_16x16x32_bf16 v[76:79], v[168:171], v[196:199], v[76:79]
	v_mfma_f32_16x16x32_bf16 v[68:71], v[160:163], v[204:207], v[68:71]
	v_mfma_f32_16x16x32_bf16 v[64:67], v[168:171], v[204:207], v[64:67]
	v_mfma_f32_16x16x32_bf16 v[116:119], v[164:167], v[184:187], v[116:119]
	v_mfma_f32_16x16x32_bf16 v[108:111], v[172:175], v[184:187], v[108:111]
	v_mfma_f32_16x16x32_bf16 v[100:103], v[164:167], v[192:195], v[100:103]
	v_mfma_f32_16x16x32_bf16 v[92:95], v[172:175], v[192:195], v[92:95]
	v_mfma_f32_16x16x32_bf16 v[84:87], v[164:167], v[200:203], v[84:87]
	v_mfma_f32_16x16x32_bf16 v[76:79], v[172:175], v[200:203], v[76:79]
	v_mfma_f32_16x16x32_bf16 v[68:71], v[164:167], v[208:211], v[68:71]
	v_mfma_f32_16x16x32_bf16 v[64:67], v[172:175], v[208:211], v[64:67]
	s_setprio 0
	s_barrier
; #define PG8_STAGE(bufoff, gbase, voff) do { _Pragma("unroll") for (int _i = 0; _i < 2; ++_i) \
;         __builtin_amdgcn_global_load_lds((const unsigned*)((const char*)(gbase) + (voff)[_i]), (PG8_LAS unsigned*)(lds + (bufoff) + ldsw + _i * 8192), 16, 0, 0); } while (0)
; #define PG8_LDA(dst, b, h) do { _Pragma("unroll") for (int m = 0; m < 4; ++m) _Pragma("unroll") for (int k = 0; k < 2; ++k) dst[m][k] = *(const PG8_LAS bf16x8*)(lds + PG8_SA(b, h) + aoff + m * 2048 + k * 1024); } while (0)
; #define PG8_WAIT_V(n) asm volatile("s_waitcnt vmcnt(" #n ")" ::: "memory")
; #define PG8_WAIT_L(n) asm volatile("s_waitcnt lgkmcnt(" #n ")" ::: "memory")
; #define PG8_BAR __builtin_amdgcn_s_barrier()
; #define PG8_SCHED __builtin_amdgcn_sched_barrier(0)
; template <class Epi, class Sched, bool ALIGN_EPI = false, bool SP2 = false>
; __device__ __forceinline__ void gemm_phase(PG8_LAS unsigned char* lds, const Gemm g, const Sched& S, const Epi& E) {
;     ...
;             PG8_LDA(At, 1, 1); PG8_STAGE(PG8_SB(1, 0), b3, voffB); PG8_STAGE(PG8_SB(1, 1), b3 + hstep, voffB); PG8_STAGE(PG8_SA(1, 0), a3, voffA);
;             PG8_WAIT_V(8); PG8_WAIT_L(0); PG8_BAR; PG8_MMA(1, 0, At, B0); PG8_MMA(1, 1, At, B1); PG8_BAR; PG8_SCHED;
;     __device__ __forceinline__ void operator()(const AccT& acc, const pg8::Unit& u, int wr, int wc, int fr, int fq) const {
;         const int col0 = u.pn * 256 + wc * 32 + 4 * fq, row0 = row_base + u.pm * 256 + wr * 64 + fr;
; #pragma unroll
;         for (int ai = 0; ai < 2; ++ai)
; #pragma unroll
;             for (int m = 0; m < 4; ++m) { const int row = row0 + ai * 128 + m * 16; float ss = 0.f;
; #pragma unroll
;                 for (int bj = 0; bj < 2; ++bj)
; #pragma unroll
;                     for (int n = 0; n < 2; ++n) { f32x4 v = acc[ai][bj][m][n]; const size_t idx = (size_t)row * 1024 + col0 + bj * 128 + n * 16;
;                         if (MODE == 0) v = v * up4(*(const u32x2*)(io + idx));
;                         else if (MODE == 1) v = up4(*(const u32x2*)(io + idx)) + up4(*(const u32x2*)(g2 + idx)) * v;
;                         else ss += (v[0] * v[0] + v[1] * v[1]) + (v[2] * v[2] + v[3] * v[3]);
;                         if (!DRYE || v[0] == 123.456f) *(u32x2*)(io + idx) = pk4(v); }
;                 if (MODE == 2 && !DRYE) { ss += __shfl_xor(ss, 16); ss += __shfl_xor(ss, 32); if (fq == 0) atomicAdd(rowss + row, ss); } }
	s_add_i32 s3, s3, s46
	v_lshl_add_u64 v[212:213], v[212:213], 0, s[14:15]
	s_mov_b32 m0, s3
	ds_read_b128 v[180:183], v145 offset:49152
	ds_read_b128 v[184:187], v145 offset:50176
	ds_read_b128 v[188:191], v145 offset:51200
	ds_read_b128 v[192:195], v145 offset:52224
	ds_read_b128 v[196:199], v145 offset:53248
	ds_read_b128 v[200:203], v145 offset:54272
	ds_read_b128 v[204:207], v145 offset:55296
	ds_read_b128 v[208:211], v145 offset:56320
	global_load_lds_dwordx4 v[212:213], off
	s_add_i32 m0, s3, 0x2000
	s_add_u32 s30, s30, 0x40080
	v_lshl_add_u64 v[212:213], v[214:215], 0, s[14:15]
	s_addc_u32 s31, s31, 0
	s_add_i32 s3, s33, s46
	global_load_lds_dwordx4 v[212:213], off
	v_lshl_add_u64 v[212:213], s[30:31], 0, v[128:129]
	s_mov_b32 m0, s3
	s_nop 0
	global_load_lds_dwordx4 v[212:213], off
	v_lshl_add_u64 v[212:213], s[30:31], 0, v[130:131]
	s_add_i32 m0, s3, 0x2000
	s_nop 0
	global_load_lds_dwordx4 v[212:213], off
	v_lshl_add_u64 v[212:213], v[216:217], 0, s[14:15]
	s_mov_b32 m0, s63
	s_nop 0
	global_load_lds_dwordx4 v[212:213], off
	v_lshl_add_u64 v[212:213], v[218:219], 0, s[14:15]
	s_mov_b32 m0, s64
	s_nop 0
	global_load_lds_dwordx4 v[212:213], off
	s_waitcnt vmcnt(8)
	s_waitcnt lgkmcnt(0)
	s_barrier
	s_setprio 1
	s_waitcnt lgkmcnt(0)
	v_mfma_f32_16x16x32_bf16 v[60:63], v[136:139], v[180:183], v[60:63]
	v_mfma_f32_16x16x32_bf16 v[56:59], v[152:155], v[180:183], v[56:59]
	v_mfma_f32_16x16x32_bf16 v[48:51], v[136:139], v[188:191], v[48:51]
	v_mfma_f32_16x16x32_bf16 v[40:43], v[152:155], v[188:191], v[40:43]
	v_mfma_f32_16x16x32_bf16 v[32:35], v[136:139], v[196:199], v[32:35]
	v_mfma_f32_16x16x32_bf16 v[24:27], v[152:155], v[196:199], v[24:27]
	v_mfma_f32_16x16x32_bf16 v[16:19], v[136:139], v[204:207], v[16:19]
	v_mfma_f32_16x16x32_bf16 v[8:11], v[152:155], v[204:207], v[8:11]
	v_mfma_f32_16x16x32_bf16 v[60:63], v[148:151], v[184:187], v[60:63]
	v_mfma_f32_16x16x32_bf16 v[56:59], v[156:159], v[184:187], v[56:59]
	v_mfma_f32_16x16x32_bf16 v[48:51], v[148:151], v[192:195], v[48:51]
	v_mfma_f32_16x16x32_bf16 v[40:43], v[156:159], v[192:195], v[40:43]
	v_mfma_f32_16x16x32_bf16 v[32:35], v[148:151], v[200:203], v[32:35]
	v_mfma_f32_16x16x32_bf16 v[24:27], v[156:159], v[200:203], v[24:27]
	v_mfma_f32_16x16x32_bf16 v[16:19], v[148:151], v[208:211], v[16:19]
	v_mfma_f32_16x16x32_bf16 v[8:11], v[156:159], v[208:211], v[8:11]
	s_setprio 0
	s_setprio 1
	v_mfma_f32_16x16x32_bf16 v[52:55], v[160:163], v[180:183], v[52:55]
	v_mfma_f32_16x16x32_bf16 v[44:47], v[168:171], v[180:183], v[44:47]
	v_mfma_f32_16x16x32_bf16 v[36:39], v[160:163], v[188:191], v[36:39]
	v_mfma_f32_16x16x32_bf16 v[28:31], v[168:171], v[188:191], v[28:31]
	v_mfma_f32_16x16x32_bf16 v[20:23], v[160:163], v[196:199], v[20:23]
	v_mfma_f32_16x16x32_bf16 v[12:15], v[168:171], v[196:199], v[12:15]
	v_mfma_f32_16x16x32_bf16 v[4:7], v[160:163], v[204:207], v[4:7]
	v_mfma_f32_16x16x32_bf16 v[0:3], v[168:171], v[204:207], v[0:3]
	v_mfma_f32_16x16x32_bf16 v[52:55], v[164:167], v[184:187], v[52:55]
	v_mfma_f32_16x16x32_bf16 v[44:47], v[172:175], v[184:187], v[44:47]
	v_mfma_f32_16x16x32_bf16 v[36:39], v[164:167], v[192:195], v[36:39]
	v_mfma_f32_16x16x32_bf16 v[28:31], v[172:175], v[192:195], v[28:31]
	v_mfma_f32_16x16x32_bf16 v[20:23], v[164:167], v[200:203], v[20:23]
	v_mfma_f32_16x16x32_bf16 v[12:15], v[172:175], v[200:203], v[12:15]
	v_mfma_f32_16x16x32_bf16 v[4:7], v[164:167], v[208:211], v[4:7]
	v_mfma_f32_16x16x32_bf16 v[0:3], v[172:175], v[208:211], v[0:3]
	s_setprio 0
	s_barrier
	s_add_i32 s71, s71, 2
	s_add_u32 s28, s28, 0x100
	s_addc_u32 s29, s29, 0
	s_add_u32 s69, s69, 0x100
	s_addc_u32 s70, s70, 0
	s_cmp_gt_u32 s71, 13
	s_cbranch_scc0 .LBB0_1059
	v_and_b32_e32 v147, 64, v146
	v_xor_b32_e32 v139, 16, v146
	v_add_u32_e32 v147, 64, v147
	v_cmp_lt_i32_e32 vcc, v139, v147
	v_lshl_add_u32 v149, s26, 8, v140
	v_add_u32_e32 v138, 0x4000, v149
	v_cndmask_b32_e32 v139, v146, v139, vcc
	v_lshlrev_b32_e32 v148, 2, v139
	v_xor_b32_e32 v139, 32, v146
	v_cmp_lt_i32_e32 vcc, v139, v147
	v_lshl_or_b32 v136, s27, 8, v142
	v_mul_f32_e32 v152, v125, v125
	v_cndmask_b32_e32 v139, v146, v139, vcc
	v_lshlrev_b32_e32 v147, 2, v139
	v_ashrrev_i32_e32 v139, 31, v138
	v_lshlrev_b64 v[150:151], 11, v[138:139]
	v_mul_f32_e32 v153, v127, v127
	v_ashrrev_i32_e32 v137, 31, v136
	v_fmac_f32_e32 v152, v124, v124
	v_fmac_f32_e32 v153, v126, v126
	v_cvt_pk_bf16_f32 v124, v124, v125
	v_cvt_pk_bf16_f32 v125, v126, v127
	v_lshl_add_u64 v[126:127], s[8:9], 0, v[150:151]
	v_lshl_add_u64 v[126:127], v[136:137], 1, v[126:127]
	global_store_dwordx2 v[126:127], v[124:125], off
	v_mul_f32_e32 v124, v121, v121
	v_mul_f32_e32 v125, v123, v123
	v_fmac_f32_e32 v124, v120, v120
	v_fmac_f32_e32 v125, v122, v122
	v_add_f32_e32 v124, v124, v125
	v_cvt_pk_bf16_f32 v120, v120, v121
	v_mul_f32_e32 v121, v117, v117
	v_mul_f32_e32 v125, v119, v119
	v_add_f32_e32 v152, v152, v153
	v_fmac_f32_e32 v121, v116, v116
	v_fmac_f32_e32 v125, v118, v118
	v_add_f32_e32 v124, v152, v124
	v_add_f32_e32 v121, v121, v125
	v_add_f32_e32 v121, v124, v121
	v_mul_f32_e32 v124, v109, v109
	v_mul_f32_e32 v125, v111, v111
	v_fmac_f32_e32 v124, v108, v108
	v_fmac_f32_e32 v125, v110, v110
	v_add_f32_e32 v124, v124, v125
	v_add_f32_e32 v124, v121, v124
	v_mov_b32_e32 v125, v124
	s_nop 1
	v_permlane16_swap_b32_e32 v124, v125
	v_cvt_pk_bf16_f32 v121, v122, v123
	global_store_dwordx2 v[126:127], v[120:121], off offset:32
	v_cvt_pk_bf16_f32 v120, v116, v117
	v_cvt_pk_bf16_f32 v121, v118, v119
	s_waitcnt lgkmcnt(0)
	v_add_f32_e32 v116, v124, v125
	v_mov_b32_e32 v117, v116
	s_nop 1
	v_permlane32_swap_b32_e32 v116, v117
	v_cvt_pk_bf16_f32 v108, v108, v109
	v_cvt_pk_bf16_f32 v109, v110, v111
	global_store_dwordx2 v[126:127], v[120:121], off offset:256
	global_store_dwordx2 v[126:127], v[108:109], off offset:288
	s_and_saveexec_b64 s[26:27], s[0:1]
	s_cbranch_execz .LBB0_1062
	v_lshl_add_u64 v[108:109], v[138:139], 2, s[10:11]
	s_waitcnt lgkmcnt(0)
	v_add_f32_e32 v110, v116, v117
	global_atomic_add_f32 v[108:109], v110, off
; __device__ __forceinline__ u32x2 pk4(f32x4 v) { u32x2 w; w.x = cvt_pk_bf16(v[0], v[1]); w.y = cvt_pk_bf16(v[2], v[3]); return w; }
; __device__ __forceinline__ f32x4 up4(u32x2 w) { return (f32x4){bf_lo(w.x), bf_hi(w.x), bf_lo(w.y), bf_hi(w.y)}; }
;     __device__ __forceinline__ void operator()(const AccT& acc, const pg8::Unit& u, int wr, int wc, int fr, int fq) const {
;     ...
;             for (int m = 0; m < 4; ++m) { const int row = row0 + ai * 128 + m * 16; float ss = 0.f;
; #pragma unroll
;                 for (int bj = 0; bj < 2; ++bj)
; #pragma unroll
;                     for (int n = 0; n < 2; ++n) { f32x4 v = acc[ai][bj][m][n]; const size_t idx = (size_t)row * 1024 + col0 + bj * 128 + n * 16;
;                         if (MODE == 0) v = v * up4(*(const u32x2*)(io + idx));
;                         else if (MODE == 1) v = up4(*(const u32x2*)(io + idx)) + up4(*(const u32x2*)(g2 + idx)) * v;
;                         else ss += (v[0] * v[0] + v[1] * v[1]) + (v[2] * v[2] + v[3] * v[3]);
;                         if (!DRYE || v[0] == 123.456f) *(u32x2*)(io + idx) = pk4(v); }
;                 if (MODE == 2 && !DRYE) { ss += __shfl_xor(ss, 16); ss += __shfl_xor(ss, 32); if (fq == 0) atomicAdd(rowss + row, ss); } }
.LBB0_1062:
	s_or_b64 exec, exec, s[26:27]
	v_add_u32_e32 v108, 0x4010, v149
	v_ashrrev_i32_e32 v109, 31, v108
	v_lshlrev_b64 v[110:111], 11, v[108:109]
	v_mul_f32_e32 v116, v113, v113
	v_lshl_add_u64 v[110:111], s[8:9], 0, v[110:111]
	v_fmac_f32_e32 v116, v112, v112
	v_cvt_pk_bf16_f32 v112, v112, v113
	v_cvt_pk_bf16_f32 v113, v114, v115
	v_lshl_add_u64 v[110:111], v[136:137], 1, v[110:111]
	global_store_dwordx2 v[110:111], v[112:113], off
	v_mul_f32_e32 v112, v105, v105
	v_mul_f32_e32 v113, v107, v107
	s_waitcnt lgkmcnt(0)
	v_mul_f32_e32 v117, v115, v115
	v_fmac_f32_e32 v112, v104, v104
	v_fmac_f32_e32 v113, v106, v106
	v_fmac_f32_e32 v117, v114, v114
	v_add_f32_e32 v112, v112, v113
	v_cvt_pk_bf16_f32 v104, v104, v105
	v_mul_f32_e32 v105, v101, v101
	v_mul_f32_e32 v113, v103, v103
	v_add_f32_e32 v116, v116, v117
	v_fmac_f32_e32 v105, v100, v100
	v_fmac_f32_e32 v113, v102, v102
	v_add_f32_e32 v112, v116, v112
	v_add_f32_e32 v105, v105, v113
	v_add_f32_e32 v105, v112, v105
	v_mul_f32_e32 v112, v93, v93
	v_mul_f32_e32 v113, v95, v95
	v_fmac_f32_e32 v112, v92, v92
	v_fmac_f32_e32 v113, v94, v94
	v_add_f32_e32 v112, v112, v113
	v_add_f32_e32 v112, v105, v112
	v_mov_b32_e32 v113, v112
	s_nop 1
	v_permlane16_swap_b32_e32 v112, v113
	v_cvt_pk_bf16_f32 v105, v106, v107
	global_store_dwordx2 v[110:111], v[104:105], off offset:32
	v_cvt_pk_bf16_f32 v104, v100, v101
	v_cvt_pk_bf16_f32 v105, v102, v103
	s_waitcnt lgkmcnt(0)
	v_add_f32_e32 v100, v112, v113
	v_mov_b32_e32 v101, v100
	s_nop 1
	v_permlane32_swap_b32_e32 v100, v101
	v_cvt_pk_bf16_f32 v92, v92, v93
	v_cvt_pk_bf16_f32 v93, v94, v95
	global_store_dwordx2 v[110:111], v[104:105], off offset:256
	global_store_dwordx2 v[110:111], v[92:93], off offset:288
	s_and_saveexec_b64 s[26:27], s[0:1]
	s_cbranch_execz .LBB0_1064
	v_lshl_add_u64 v[92:93], v[108:109], 2, s[10:11]
	s_waitcnt lgkmcnt(0)
	v_add_f32_e32 v94, v100, v101
	global_atomic_add_f32 v[92:93], v94, off
.LBB0_1064:
	s_or_b64 exec, exec, s[26:27]
	v_add_u32_e32 v92, 0x4020, v149
	v_ashrrev_i32_e32 v93, 31, v92
	v_lshlrev_b64 v[94:95], 11, v[92:93]
	v_mul_f32_e32 v100, v97, v97
	v_lshl_add_u64 v[94:95], s[8:9], 0, v[94:95]
	v_fmac_f32_e32 v100, v96, v96
	v_cvt_pk_bf16_f32 v96, v96, v97
	v_cvt_pk_bf16_f32 v97, v98, v99
	v_lshl_add_u64 v[94:95], v[136:137], 1, v[94:95]
	global_store_dwordx2 v[94:95], v[96:97], off
	v_mul_f32_e32 v96, v89, v89
	v_mul_f32_e32 v97, v91, v91
	s_waitcnt lgkmcnt(0)
	v_mul_f32_e32 v101, v99, v99
	v_fmac_f32_e32 v96, v88, v88
	v_fmac_f32_e32 v97, v90, v90
	v_fmac_f32_e32 v101, v98, v98
	v_add_f32_e32 v96, v96, v97
	v_cvt_pk_bf16_f32 v88, v88, v89
	v_mul_f32_e32 v89, v85, v85
	v_mul_f32_e32 v97, v87, v87
	v_add_f32_e32 v100, v100, v101
	v_fmac_f32_e32 v89, v84, v84
	v_fmac_f32_e32 v97, v86, v86
	v_add_f32_e32 v96, v100, v96
	v_add_f32_e32 v89, v89, v97
	v_add_f32_e32 v89, v96, v89
	v_mul_f32_e32 v96, v77, v77
	v_mul_f32_e32 v97, v79, v79
	v_fmac_f32_e32 v96, v76, v76
	v_fmac_f32_e32 v97, v78, v78
	v_add_f32_e32 v96, v96, v97
	v_add_f32_e32 v96, v89, v96
	v_mov_b32_e32 v97, v96
	s_nop 1
	v_permlane16_swap_b32_e32 v96, v97
	v_cvt_pk_bf16_f32 v89, v90, v91
	global_store_dwordx2 v[94:95], v[88:89], off offset:32
	v_cvt_pk_bf16_f32 v88, v84, v85
	v_cvt_pk_bf16_f32 v89, v86, v87
	s_waitcnt lgkmcnt(0)
	v_add_f32_e32 v84, v96, v97
	v_mov_b32_e32 v85, v84
	s_nop 1
	v_permlane32_swap_b32_e32 v84, v85
	v_cvt_pk_bf16_f32 v76, v76, v77
	v_cvt_pk_bf16_f32 v77, v78, v79
	global_store_dwordx2 v[94:95], v[88:89], off offset:256
	global_store_dwordx2 v[94:95], v[76:77], off offset:288
	s_and_saveexec_b64 s[26:27], s[0:1]
	s_cbranch_execz .LBB0_1066
	v_lshl_add_u64 v[76:77], v[92:93], 2, s[10:11]
	s_waitcnt lgkmcnt(0)
	v_add_f32_e32 v78, v84, v85
	global_atomic_add_f32 v[76:77], v78, off
.LBB0_1066:
	s_or_b64 exec, exec, s[26:27]
	v_add_u32_e32 v76, 0x4030, v149
	v_ashrrev_i32_e32 v77, 31, v76
	v_lshlrev_b64 v[78:79], 11, v[76:77]
	v_mul_f32_e32 v84, v81, v81
	v_lshl_add_u64 v[78:79], s[8:9], 0, v[78:79]
	v_fmac_f32_e32 v84, v80, v80
	v_cvt_pk_bf16_f32 v80, v80, v81
	v_cvt_pk_bf16_f32 v81, v82, v83
	v_lshl_add_u64 v[78:79], v[136:137], 1, v[78:79]
	global_store_dwordx2 v[78:79], v[80:81], off
	v_mul_f32_e32 v80, v73, v73
	v_mul_f32_e32 v81, v75, v75
	s_waitcnt lgkmcnt(0)
	v_mul_f32_e32 v85, v83, v83
	v_fmac_f32_e32 v80, v72, v72
	v_fmac_f32_e32 v81, v74, v74
	v_fmac_f32_e32 v85, v82, v82
	v_add_f32_e32 v80, v80, v81
	v_cvt_pk_bf16_f32 v72, v72, v73
	v_mul_f32_e32 v73, v69, v69
	v_mul_f32_e32 v81, v71, v71
	v_add_f32_e32 v84, v84, v85
	v_fmac_f32_e32 v73, v68, v68
	v_fmac_f32_e32 v81, v70, v70
	v_add_f32_e32 v80, v84, v80
	v_add_f32_e32 v73, v73, v81
	v_add_f32_e32 v73, v80, v73
	v_mul_f32_e32 v80, v65, v65
	v_mul_f32_e32 v81, v67, v67
	v_fmac_f32_e32 v80, v64, v64
	v_fmac_f32_e32 v81, v66, v66
	v_add_f32_e32 v80, v80, v81
	v_add_f32_e32 v80, v73, v80
	v_mov_b32_e32 v81, v80
	s_nop 1
	v_permlane16_swap_b32_e32 v80, v81
	v_cvt_pk_bf16_f32 v73, v74, v75
	global_store_dwordx2 v[78:79], v[72:73], off offset:32
	v_cvt_pk_bf16_f32 v72, v68, v69
	v_cvt_pk_bf16_f32 v73, v70, v71
	s_waitcnt lgkmcnt(0)
	v_add_f32_e32 v68, v80, v81
	v_mov_b32_e32 v69, v68
	s_nop 1
	v_permlane32_swap_b32_e32 v68, v69
	v_cvt_pk_bf16_f32 v64, v64, v65
	v_cvt_pk_bf16_f32 v65, v66, v67
	global_store_dwordx2 v[78:79], v[72:73], off offset:256
	global_store_dwordx2 v[78:79], v[64:65], off offset:288
	s_and_saveexec_b64 s[26:27], s[0:1]
	s_cbranch_execz .LBB0_1068
	v_lshl_add_u64 v[64:65], v[76:77], 2, s[10:11]
	s_waitcnt lgkmcnt(0)
	v_add_f32_e32 v66, v68, v69
	global_atomic_add_f32 v[64:65], v66, off
; __device__ __forceinline__ u32x2 pk4(f32x4 v) { u32x2 w; w.x = cvt_pk_bf16(v[0], v[1]); w.y = cvt_pk_bf16(v[2], v[3]); return w; }
; __device__ __forceinline__ f32x4 up4(u32x2 w) { return (f32x4){bf_lo(w.x), bf_hi(w.x), bf_lo(w.y), bf_hi(w.y)}; }
;     __device__ __forceinline__ void operator()(const AccT& acc, const pg8::Unit& u, int wr, int wc, int fr, int fq) const {
;     ...
;             for (int m = 0; m < 4; ++m) { const int row = row0 + ai * 128 + m * 16; float ss = 0.f;
; #pragma unroll
;                 for (int bj = 0; bj < 2; ++bj)
; #pragma unroll
;                     for (int n = 0; n < 2; ++n) { f32x4 v = acc[ai][bj][m][n]; const size_t idx = (size_t)row * 1024 + col0 + bj * 128 + n * 16;
;                         if (MODE == 0) v = v * up4(*(const u32x2*)(io + idx));
;                         else if (MODE == 1) v = up4(*(const u32x2*)(io + idx)) + up4(*(const u32x2*)(g2 + idx)) * v;
;                         else ss += (v[0] * v[0] + v[1] * v[1]) + (v[2] * v[2] + v[3] * v[3]);
;                         if (!DRYE || v[0] == 123.456f) *(u32x2*)(io + idx) = pk4(v); }
;                 if (MODE == 2 && !DRYE) { ss += __shfl_xor(ss, 16); ss += __shfl_xor(ss, 32); if (fq == 0) atomicAdd(rowss + row, ss); } }
.LBB0_1068:
	s_or_b64 exec, exec, s[26:27]
	v_add_u32_e32 v64, 0x4080, v149
	v_ashrrev_i32_e32 v65, 31, v64
	v_lshlrev_b64 v[66:67], 11, v[64:65]
	v_mul_f32_e32 v68, v61, v61
	s_waitcnt lgkmcnt(0)
	v_mul_f32_e32 v69, v63, v63
	v_fmac_f32_e32 v68, v60, v60
	v_fmac_f32_e32 v69, v62, v62
	v_cvt_pk_bf16_f32 v60, v60, v61
	v_cvt_pk_bf16_f32 v61, v62, v63
	v_lshl_add_u64 v[62:63], s[8:9], 0, v[66:67]
	v_lshl_add_u64 v[62:63], v[136:137], 1, v[62:63]
	global_store_dwordx2 v[62:63], v[60:61], off
	v_mul_f32_e32 v60, v57, v57
	v_mul_f32_e32 v61, v59, v59
	v_fmac_f32_e32 v60, v56, v56
	v_fmac_f32_e32 v61, v58, v58
	v_add_f32_e32 v60, v60, v61
	v_cvt_pk_bf16_f32 v56, v56, v57
	v_mul_f32_e32 v57, v53, v53
	v_mul_f32_e32 v61, v55, v55
	v_add_f32_e32 v68, v68, v69
	v_fmac_f32_e32 v57, v52, v52
	v_fmac_f32_e32 v61, v54, v54
	v_add_f32_e32 v60, v68, v60
	v_add_f32_e32 v57, v57, v61
	v_add_f32_e32 v57, v60, v57
	v_mul_f32_e32 v60, v45, v45
	v_mul_f32_e32 v61, v47, v47
	v_fmac_f32_e32 v60, v44, v44
	v_fmac_f32_e32 v61, v46, v46
	v_add_f32_e32 v60, v60, v61
	v_add_f32_e32 v60, v57, v60
	v_mov_b32_e32 v61, v60
	s_nop 1
	v_permlane16_swap_b32_e32 v60, v61
	v_cvt_pk_bf16_f32 v57, v58, v59
	global_store_dwordx2 v[62:63], v[56:57], off offset:32
	v_cvt_pk_bf16_f32 v56, v52, v53
	v_cvt_pk_bf16_f32 v57, v54, v55
	s_waitcnt lgkmcnt(0)
	v_add_f32_e32 v52, v60, v61
	v_mov_b32_e32 v53, v52
	s_nop 1
	v_permlane32_swap_b32_e32 v52, v53
	v_cvt_pk_bf16_f32 v44, v44, v45
	v_cvt_pk_bf16_f32 v45, v46, v47
	global_store_dwordx2 v[62:63], v[56:57], off offset:256
	global_store_dwordx2 v[62:63], v[44:45], off offset:288
	s_and_saveexec_b64 s[26:27], s[0:1]
	s_cbranch_execz .LBB0_1070
	v_lshl_add_u64 v[44:45], v[64:65], 2, s[10:11]
	s_waitcnt lgkmcnt(0)
	v_add_f32_e32 v46, v52, v53
	global_atomic_add_f32 v[44:45], v46, off
.LBB0_1070:
	s_or_b64 exec, exec, s[26:27]
	v_add_u32_e32 v44, 0x4090, v149
	v_ashrrev_i32_e32 v45, 31, v44
	v_lshlrev_b64 v[46:47], 11, v[44:45]
	v_mul_f32_e32 v52, v49, v49
	v_lshl_add_u64 v[46:47], s[8:9], 0, v[46:47]
	v_fmac_f32_e32 v52, v48, v48
	v_cvt_pk_bf16_f32 v48, v48, v49
	v_cvt_pk_bf16_f32 v49, v50, v51
	v_lshl_add_u64 v[46:47], v[136:137], 1, v[46:47]
	global_store_dwordx2 v[46:47], v[48:49], off
	v_mul_f32_e32 v48, v41, v41
	v_mul_f32_e32 v49, v43, v43
	s_waitcnt lgkmcnt(0)
	v_mul_f32_e32 v53, v51, v51
	v_fmac_f32_e32 v48, v40, v40
	v_fmac_f32_e32 v49, v42, v42
	v_fmac_f32_e32 v53, v50, v50
	v_add_f32_e32 v48, v48, v49
	v_cvt_pk_bf16_f32 v40, v40, v41
	v_mul_f32_e32 v41, v37, v37
	v_mul_f32_e32 v49, v39, v39
	v_add_f32_e32 v52, v52, v53
	v_fmac_f32_e32 v41, v36, v36
	v_fmac_f32_e32 v49, v38, v38
	v_add_f32_e32 v48, v52, v48
	v_add_f32_e32 v41, v41, v49
	v_add_f32_e32 v41, v48, v41
	v_mul_f32_e32 v48, v29, v29
	v_mul_f32_e32 v49, v31, v31
	v_fmac_f32_e32 v48, v28, v28
	v_fmac_f32_e32 v49, v30, v30
	v_add_f32_e32 v48, v48, v49
	v_add_f32_e32 v48, v41, v48
	v_mov_b32_e32 v49, v48
	s_nop 1
	v_permlane16_swap_b32_e32 v48, v49
	v_cvt_pk_bf16_f32 v41, v42, v43
	global_store_dwordx2 v[46:47], v[40:41], off offset:32
	v_cvt_pk_bf16_f32 v40, v36, v37
	v_cvt_pk_bf16_f32 v41, v38, v39
	s_waitcnt lgkmcnt(0)
	v_add_f32_e32 v36, v48, v49
	v_mov_b32_e32 v37, v36
	s_nop 1
	v_permlane32_swap_b32_e32 v36, v37
	v_cvt_pk_bf16_f32 v28, v28, v29
	v_cvt_pk_bf16_f32 v29, v30, v31
	global_store_dwordx2 v[46:47], v[40:41], off offset:256
	global_store_dwordx2 v[46:47], v[28:29], off offset:288
	s_and_saveexec_b64 s[26:27], s[0:1]
	s_cbranch_execz .LBB0_1072
	v_lshl_add_u64 v[28:29], v[44:45], 2, s[10:11]
	s_waitcnt lgkmcnt(0)
	v_add_f32_e32 v30, v36, v37
	global_atomic_add_f32 v[28:29], v30, off
; __device__ __forceinline__ u32x2 pk4(f32x4 v) { u32x2 w; w.x = cvt_pk_bf16(v[0], v[1]); w.y = cvt_pk_bf16(v[2], v[3]); return w; }
; __device__ __forceinline__ f32x4 up4(u32x2 w) { return (f32x4){bf_lo(w.x), bf_hi(w.x), bf_lo(w.y), bf_hi(w.y)}; }
;     __device__ __forceinline__ void operator()(const AccT& acc, const pg8::Unit& u, int wr, int wc, int fr, int fq) const {
;     ...
;             for (int m = 0; m < 4; ++m) { const int row = row0 + ai * 128 + m * 16; float ss = 0.f;
; #pragma unroll
;                 for (int bj = 0; bj < 2; ++bj)
; #pragma unroll
;                     for (int n = 0; n < 2; ++n) { f32x4 v = acc[ai][bj][m][n]; const size_t idx = (size_t)row * 1024 + col0 + bj * 128 + n * 16;
;                         if (MODE == 0) v = v * up4(*(const u32x2*)(io + idx));
;                         else if (MODE == 1) v = up4(*(const u32x2*)(io + idx)) + up4(*(const u32x2*)(g2 + idx)) * v;
;                         else ss += (v[0] * v[0] + v[1] * v[1]) + (v[2] * v[2] + v[3] * v[3]);
;                         if (!DRYE || v[0] == 123.456f) *(u32x2*)(io + idx) = pk4(v); }
;                 if (MODE == 2 && !DRYE) { ss += __shfl_xor(ss, 16); ss += __shfl_xor(ss, 32); if (fq == 0) atomicAdd(rowss + row, ss); } }
.LBB0_1072:
	s_or_b64 exec, exec, s[26:27]
	v_add_u32_e32 v28, 0x40a0, v149
	v_ashrrev_i32_e32 v29, 31, v28
	v_lshlrev_b64 v[30:31], 11, v[28:29]
	v_mul_f32_e32 v36, v33, v33
	v_lshl_add_u64 v[30:31], s[8:9], 0, v[30:31]
	v_fmac_f32_e32 v36, v32, v32
	v_cvt_pk_bf16_f32 v32, v32, v33
	v_cvt_pk_bf16_f32 v33, v34, v35
	v_lshl_add_u64 v[30:31], v[136:137], 1, v[30:31]
	global_store_dwordx2 v[30:31], v[32:33], off
	v_mul_f32_e32 v32, v25, v25
	v_mul_f32_e32 v33, v27, v27
	s_waitcnt lgkmcnt(0)
	v_mul_f32_e32 v37, v35, v35
	v_fmac_f32_e32 v32, v24, v24
	v_fmac_f32_e32 v33, v26, v26
	v_fmac_f32_e32 v37, v34, v34
	v_add_f32_e32 v32, v32, v33
	v_cvt_pk_bf16_f32 v24, v24, v25
	v_mul_f32_e32 v25, v21, v21
	v_mul_f32_e32 v33, v23, v23
	v_add_f32_e32 v36, v36, v37
	v_fmac_f32_e32 v25, v20, v20
	v_fmac_f32_e32 v33, v22, v22
	v_add_f32_e32 v32, v36, v32
	v_add_f32_e32 v25, v25, v33
	v_add_f32_e32 v25, v32, v25
	v_mul_f32_e32 v32, v13, v13
	v_mul_f32_e32 v33, v15, v15
	v_fmac_f32_e32 v32, v12, v12
	v_fmac_f32_e32 v33, v14, v14
	v_add_f32_e32 v32, v32, v33
	v_add_f32_e32 v32, v25, v32
	v_mov_b32_e32 v33, v32
	s_nop 1
	v_permlane16_swap_b32_e32 v32, v33
	v_cvt_pk_bf16_f32 v25, v26, v27
	global_store_dwordx2 v[30:31], v[24:25], off offset:32
	v_cvt_pk_bf16_f32 v24, v20, v21
	v_cvt_pk_bf16_f32 v25, v22, v23
	s_waitcnt lgkmcnt(0)
	v_add_f32_e32 v20, v32, v33
	v_mov_b32_e32 v21, v20
	s_nop 1
	v_permlane32_swap_b32_e32 v20, v21
	v_cvt_pk_bf16_f32 v12, v12, v13
	v_cvt_pk_bf16_f32 v13, v14, v15
	global_store_dwordx2 v[30:31], v[24:25], off offset:256
	global_store_dwordx2 v[30:31], v[12:13], off offset:288
	s_and_saveexec_b64 s[26:27], s[0:1]
	s_cbranch_execz .LBB0_1074
	v_lshl_add_u64 v[12:13], v[28:29], 2, s[10:11]
	s_waitcnt lgkmcnt(0)
	v_add_f32_e32 v14, v20, v21
	global_atomic_add_f32 v[12:13], v14, off
.LBB0_1074:
	s_or_b64 exec, exec, s[26:27]
	v_add_u32_e32 v12, 0x40b0, v149
	v_ashrrev_i32_e32 v13, 31, v12
	v_lshlrev_b64 v[14:15], 11, v[12:13]
	v_mul_f32_e32 v20, v17, v17
	v_lshl_add_u64 v[14:15], s[8:9], 0, v[14:15]
	v_fmac_f32_e32 v20, v16, v16
	v_cvt_pk_bf16_f32 v16, v16, v17
	v_cvt_pk_bf16_f32 v17, v18, v19
	v_lshl_add_u64 v[14:15], v[136:137], 1, v[14:15]
	global_store_dwordx2 v[14:15], v[16:17], off
	v_mul_f32_e32 v16, v9, v9
	v_mul_f32_e32 v17, v11, v11
	s_waitcnt lgkmcnt(0)
	v_mul_f32_e32 v21, v19, v19
	v_fmac_f32_e32 v16, v8, v8
	v_fmac_f32_e32 v17, v10, v10
	v_fmac_f32_e32 v21, v18, v18
	v_add_f32_e32 v16, v16, v17
	v_cvt_pk_bf16_f32 v8, v8, v9
	v_mul_f32_e32 v9, v5, v5
	v_mul_f32_e32 v17, v7, v7
	v_add_f32_e32 v20, v20, v21
	v_fmac_f32_e32 v9, v4, v4
	v_fmac_f32_e32 v17, v6, v6
	v_add_f32_e32 v16, v20, v16
	v_add_f32_e32 v9, v9, v17
	v_add_f32_e32 v9, v16, v9
	v_mul_f32_e32 v16, v1, v1
	v_mul_f32_e32 v17, v3, v3
	v_fmac_f32_e32 v16, v0, v0
	v_fmac_f32_e32 v17, v2, v2
	v_add_f32_e32 v16, v16, v17
	v_add_f32_e32 v16, v9, v16
	v_mov_b32_e32 v17, v16
	s_nop 1
	v_permlane16_swap_b32_e32 v16, v17
	v_cvt_pk_bf16_f32 v9, v10, v11
	global_store_dwordx2 v[14:15], v[8:9], off offset:32
	v_cvt_pk_bf16_f32 v8, v4, v5
	v_cvt_pk_bf16_f32 v9, v6, v7
	s_waitcnt lgkmcnt(0)
	v_add_f32_e32 v4, v16, v17
	v_mov_b32_e32 v5, v4
	s_nop 1
	v_permlane32_swap_b32_e32 v4, v5
	v_cvt_pk_bf16_f32 v0, v0, v1
	v_cvt_pk_bf16_f32 v1, v2, v3
	global_store_dwordx2 v[14:15], v[8:9], off offset:256
	global_store_dwordx2 v[14:15], v[0:1], off offset:288
	s_and_saveexec_b64 s[26:27], s[0:1]
	s_cbranch_execz .LBB0_1051
	v_lshl_add_u64 v[0:1], v[12:13], 2, s[10:11]
	s_waitcnt lgkmcnt(0)
	v_add_f32_e32 v2, v4, v5
	global_atomic_add_f32 v[0:1], v2, off
	s_branch .LBB0_1051

; #define PG8_STAGE(bufoff, gbase, voff) do { _Pragma("unroll") for (int _i = 0; _i < 2; ++_i) \
;         __builtin_amdgcn_global_load_lds((const unsigned*)((const char*)(gbase) + (voff)[_i]), (PG8_LAS unsigned*)(lds + (bufoff) + ldsw + _i * 8192), 16, 0, 0); } while (0)
; #define PG8_LDA(dst, b, h) do { _Pragma("unroll") for (int m = 0; m < 4; ++m) _Pragma("unroll") for (int k = 0; k < 2; ++k) dst[m][k] = *(const PG8_LAS bf16x8*)(lds + PG8_SA(b, h) + aoff + m * 2048 + k * 1024); } while (0)
; #define PG8_LDB(dst, b, h) do { _Pragma("unroll") for (int n = 0; n < 2; ++n) _Pragma("unroll") for (int k = 0; k < 2; ++k) dst[n][k] = *(const PG8_LAS bf16x8*)(lds + PG8_SB(b, h) + boff + n * 2048 + k * 1024); } while (0)
; #define PG8_MMA(ai, bj, At, Bt) do { __builtin_amdgcn_s_setprio(1); _Pragma("unroll") for (int m = 0; m < 4; ++m) _Pragma("unroll") for (int n = 0; n < 2; ++n) _Pragma("unroll") for (int k = 0; k < 2; ++k) \
;         acc[ai][bj][m][n] = __builtin_amdgcn_mfma_f32_16x16x32_bf16(Bt[n][k], At[m][k], acc[ai][bj][m][n], 0, 0, 0); __builtin_amdgcn_s_setprio(0); } while (0)
; #define PG8_WAIT_V(n) asm volatile("s_waitcnt vmcnt(" #n ")" ::: "memory")
; #define PG8_WAIT_L(n) asm volatile("s_waitcnt lgkmcnt(" #n ")" ::: "memory")
; #define PG8_BAR __builtin_amdgcn_s_barrier()
; #define PG8_SCHED __builtin_amdgcn_sched_barrier(0)
; template <class Epi, class Sched, bool ALIGN_EPI = false, bool SP2 = false>
; __device__ __forceinline__ void gemm_phase(PG8_LAS unsigned char* lds, const Gemm g, const Sched& S, const Epi& E) {
;     ...
;             PG8_LDB(B0, 0, 0); PG8_LDB(B1, 0, 1); PG8_SCHED; PG8_LDA(At, 0, 0); PG8_STAGE(PG8_SA(1, 1), a1 + hstep, voffA);
;             PG8_WAIT_V(8); PG8_WAIT_L(0); PG8_BAR; PG8_MMA(0, 0, At, B0); PG8_MMA(0, 1, At, B1); PG8_BAR; PG8_SCHED;
;             PG8_LDA(At, 0, 1); PG8_STAGE(PG8_SB(0, 0), b2, voffB); PG8_STAGE(PG8_SB(0, 1), b2 + hstep, voffB); PG8_STAGE(PG8_SA(0, 0), a2, voffA);
;             PG8_WAIT_V(8); PG8_WAIT_L(0); PG8_BAR; PG8_MMA(1, 0, At, B0); PG8_MMA(1, 1, At, B1); PG8_BAR; PG8_SCHED;
.LBB0_1287:
	ds_read_b128 v[140:143], v147
	ds_read_b128 v[152:155], v147 offset:1024
	ds_read_b128 v[156:159], v147 offset:2048
	ds_read_b128 v[160:163], v147 offset:3072
	ds_read_b128 v[164:167], v148
	ds_read_b128 v[168:171], v148 offset:1024
	ds_read_b128 v[172:175], v148 offset:2048
	ds_read_b128 v[180:183], v148 offset:3072
	s_add_u32 s3, s20, 0xfff50080
	s_addc_u32 s22, s21, -1
	s_cmp_eq_u32 s60, 40
	s_cselect_b32 s25, s5, s22
	s_cselect_b32 s24, s4, s3
	s_cselect_b32 s23, s7, s51
	s_cselect_b32 s22, s6, s50
	v_lshl_add_u64 v[216:217], s[20:21], 0, v[132:133]
	s_add_i32 m0, s34, 0xc000
	ds_read_b128 v[184:187], v149
	ds_read_b128 v[188:191], v149 offset:1024
	ds_read_b128 v[192:195], v149 offset:2048
	ds_read_b128 v[196:199], v149 offset:3072
	ds_read_b128 v[200:203], v149 offset:4096
	ds_read_b128 v[204:207], v149 offset:5120
	ds_read_b128 v[208:211], v149 offset:6144
	ds_read_b128 v[212:215], v149 offset:7168
	global_load_lds_dwordx4 v[216:217], off
	v_lshl_add_u64 v[216:217], s[20:21], 0, v[134:135]
	s_add_i32 m0, s34, 0xe000
	s_nop 0
	global_load_lds_dwordx4 v[216:217], off
	s_waitcnt vmcnt(8)
	s_waitcnt lgkmcnt(0)
	s_barrier
	s_setprio 1
	s_waitcnt lgkmcnt(0)
	v_mfma_f32_16x16x32_bf16 v[124:127], v[140:143], v[184:187], v[124:127]
	v_mfma_f32_16x16x32_bf16 v[120:123], v[156:159], v[184:187], v[120:123]
	v_mfma_f32_16x16x32_bf16 v[112:115], v[140:143], v[192:195], v[112:115]
	v_mfma_f32_16x16x32_bf16 v[104:107], v[156:159], v[192:195], v[104:107]
	v_mfma_f32_16x16x32_bf16 v[96:99], v[140:143], v[200:203], v[96:99]
	v_mfma_f32_16x16x32_bf16 v[88:91], v[156:159], v[200:203], v[88:91]
	v_mfma_f32_16x16x32_bf16 v[80:83], v[140:143], v[208:211], v[80:83]
	v_mfma_f32_16x16x32_bf16 v[72:75], v[156:159], v[208:211], v[72:75]
	v_mfma_f32_16x16x32_bf16 v[124:127], v[152:155], v[188:191], v[124:127]
	v_mfma_f32_16x16x32_bf16 v[120:123], v[160:163], v[188:191], v[120:123]
	v_mfma_f32_16x16x32_bf16 v[112:115], v[152:155], v[196:199], v[112:115]
	v_mfma_f32_16x16x32_bf16 v[104:107], v[160:163], v[196:199], v[104:107]
	v_mfma_f32_16x16x32_bf16 v[96:99], v[152:155], v[204:207], v[96:99]
	v_mfma_f32_16x16x32_bf16 v[88:91], v[160:163], v[204:207], v[88:91]
	v_mfma_f32_16x16x32_bf16 v[80:83], v[152:155], v[212:215], v[80:83]
	v_mfma_f32_16x16x32_bf16 v[72:75], v[160:163], v[212:215], v[72:75]
	s_setprio 0
	s_setprio 1
	v_mfma_f32_16x16x32_bf16 v[116:119], v[164:167], v[184:187], v[116:119]
	v_mfma_f32_16x16x32_bf16 v[108:111], v[172:175], v[184:187], v[108:111]
	v_mfma_f32_16x16x32_bf16 v[100:103], v[164:167], v[192:195], v[100:103]
	v_mfma_f32_16x16x32_bf16 v[92:95], v[172:175], v[192:195], v[92:95]
	v_mfma_f32_16x16x32_bf16 v[84:87], v[164:167], v[200:203], v[84:87]
	v_mfma_f32_16x16x32_bf16 v[76:79], v[172:175], v[200:203], v[76:79]
	v_mfma_f32_16x16x32_bf16 v[68:71], v[164:167], v[208:211], v[68:71]
	v_mfma_f32_16x16x32_bf16 v[64:67], v[172:175], v[208:211], v[64:67]
	v_mfma_f32_16x16x32_bf16 v[116:119], v[168:171], v[188:191], v[116:119]
	v_mfma_f32_16x16x32_bf16 v[108:111], v[180:183], v[188:191], v[108:111]
	v_mfma_f32_16x16x32_bf16 v[100:103], v[168:171], v[196:199], v[100:103]
	v_mfma_f32_16x16x32_bf16 v[92:95], v[180:183], v[196:199], v[92:95]
	v_mfma_f32_16x16x32_bf16 v[84:87], v[168:171], v[204:207], v[84:87]
	v_mfma_f32_16x16x32_bf16 v[76:79], v[180:183], v[204:207], v[76:79]
	v_mfma_f32_16x16x32_bf16 v[68:71], v[168:171], v[212:215], v[68:71]
	v_mfma_f32_16x16x32_bf16 v[64:67], v[180:183], v[212:215], v[64:67]
	s_setprio 0
	s_barrier
	s_add_i32 s3, s44, s31
	v_lshl_add_u64 v[216:217], s[22:23], 0, v[128:129]
	s_mov_b32 m0, s3
	ds_read_b128 v[184:187], v149 offset:16384
	ds_read_b128 v[188:191], v149 offset:17408
	ds_read_b128 v[192:195], v149 offset:18432
	ds_read_b128 v[196:199], v149 offset:19456
	ds_read_b128 v[200:203], v149 offset:20480
	ds_read_b128 v[204:207], v149 offset:21504
	ds_read_b128 v[208:211], v149 offset:22528
	ds_read_b128 v[212:215], v149 offset:23552
	global_load_lds_dwordx4 v[216:217], off
	s_add_i32 m0, s3, 0x2000
	s_add_u32 s62, s22, 0xb0000
	v_lshl_add_u64 v[218:219], s[22:23], 0, v[130:131]
	s_addc_u32 s63, s23, 0
	s_add_i32 s3, s45, s31
	global_load_lds_dwordx4 v[218:219], off
	v_lshl_add_u64 v[220:221], s[62:63], 0, v[128:129]
	s_mov_b32 m0, s3
	v_lshl_add_u64 v[222:223], s[24:25], 0, v[130:131]
	global_load_lds_dwordx4 v[220:221], off
	v_lshl_add_u64 v[220:221], s[62:63], 0, v[130:131]
	s_add_i32 m0, s3, 0x2000
	s_nop 0
	global_load_lds_dwordx4 v[220:221], off
	v_lshl_add_u64 v[220:221], s[24:25], 0, v[128:129]
	s_mov_b32 m0, s34
	s_nop 0
	global_load_lds_dwordx4 v[220:221], off
	s_mov_b32 m0, s35
	s_nop 0
	global_load_lds_dwordx4 v[222:223], off
	s_waitcnt vmcnt(8)
	s_waitcnt lgkmcnt(0)
	s_barrier
; #define PG8_STAGE(bufoff, gbase, voff) do { _Pragma("unroll") for (int _i = 0; _i < 2; ++_i) \
;         __builtin_amdgcn_global_load_lds((const unsigned*)((const char*)(gbase) + (voff)[_i]), (PG8_LAS unsigned*)(lds + (bufoff) + ldsw + _i * 8192), 16, 0, 0); } while (0)
; #define PG8_LDA(dst, b, h) do { _Pragma("unroll") for (int m = 0; m < 4; ++m) _Pragma("unroll") for (int k = 0; k < 2; ++k) dst[m][k] = *(const PG8_LAS bf16x8*)(lds + PG8_SA(b, h) + aoff + m * 2048 + k * 1024); } while (0)
; #define PG8_LDB(dst, b, h) do { _Pragma("unroll") for (int n = 0; n < 2; ++n) _Pragma("unroll") for (int k = 0; k < 2; ++k) dst[n][k] = *(const PG8_LAS bf16x8*)(lds + PG8_SB(b, h) + boff + n * 2048 + k * 1024); } while (0)
; #define PG8_MMA(ai, bj, At, Bt) do { __builtin_amdgcn_s_setprio(1); _Pragma("unroll") for (int m = 0; m < 4; ++m) _Pragma("unroll") for (int n = 0; n < 2; ++n) _Pragma("unroll") for (int k = 0; k < 2; ++k) \
;         acc[ai][bj][m][n] = __builtin_amdgcn_mfma_f32_16x16x32_bf16(Bt[n][k], At[m][k], acc[ai][bj][m][n], 0, 0, 0); __builtin_amdgcn_s_setprio(0); } while (0)
; #define PG8_WAIT_V(n) asm volatile("s_waitcnt vmcnt(" #n ")" ::: "memory")
; #define PG8_WAIT_L(n) asm volatile("s_waitcnt lgkmcnt(" #n ")" ::: "memory")
; #define PG8_BAR __builtin_amdgcn_s_barrier()
; #define PG8_SCHED __builtin_amdgcn_sched_barrier(0)
; template <class Epi, class Sched, bool ALIGN_EPI = false, bool SP2 = false>
; __device__ __forceinline__ void gemm_phase(PG8_LAS unsigned char* lds, const Gemm g, const Sched& S, const Epi& E) {
;     ...
;             PG8_WAIT_V(8); PG8_WAIT_L(0); PG8_BAR; PG8_MMA(1, 0, At, B0); PG8_MMA(1, 1, At, B1); PG8_BAR; PG8_SCHED;
;             PG8_LDB(B0, 1, 0); PG8_LDB(B1, 1, 1); PG8_SCHED; PG8_LDA(At, 1, 0); PG8_STAGE(PG8_SA(0, 1), a2 + hstep, voffA);
;             PG8_WAIT_V(8); PG8_WAIT_L(0); PG8_BAR; PG8_MMA(0, 0, At, B0); PG8_MMA(0, 1, At, B1); PG8_BAR; PG8_SCHED;
	s_setprio 1
	s_waitcnt lgkmcnt(0)
	v_mfma_f32_16x16x32_bf16 v[60:63], v[140:143], v[184:187], v[60:63]
	v_mfma_f32_16x16x32_bf16 v[56:59], v[156:159], v[184:187], v[56:59]
	v_mfma_f32_16x16x32_bf16 v[48:51], v[140:143], v[192:195], v[48:51]
	v_mfma_f32_16x16x32_bf16 v[40:43], v[156:159], v[192:195], v[40:43]
	v_mfma_f32_16x16x32_bf16 v[32:35], v[140:143], v[200:203], v[32:35]
	v_mfma_f32_16x16x32_bf16 v[24:27], v[156:159], v[200:203], v[24:27]
	v_mfma_f32_16x16x32_bf16 v[16:19], v[140:143], v[208:211], v[16:19]
	v_mfma_f32_16x16x32_bf16 v[8:11], v[156:159], v[208:211], v[8:11]
	v_mfma_f32_16x16x32_bf16 v[60:63], v[152:155], v[188:191], v[60:63]
	v_mfma_f32_16x16x32_bf16 v[56:59], v[160:163], v[188:191], v[56:59]
	v_mfma_f32_16x16x32_bf16 v[48:51], v[152:155], v[196:199], v[48:51]
	v_mfma_f32_16x16x32_bf16 v[40:43], v[160:163], v[196:199], v[40:43]
	v_mfma_f32_16x16x32_bf16 v[32:35], v[152:155], v[204:207], v[32:35]
	v_mfma_f32_16x16x32_bf16 v[24:27], v[160:163], v[204:207], v[24:27]
	v_mfma_f32_16x16x32_bf16 v[16:19], v[152:155], v[212:215], v[16:19]
	v_mfma_f32_16x16x32_bf16 v[8:11], v[160:163], v[212:215], v[8:11]
	s_setprio 0
	s_setprio 1
	v_mfma_f32_16x16x32_bf16 v[52:55], v[164:167], v[184:187], v[52:55]
	v_mfma_f32_16x16x32_bf16 v[44:47], v[172:175], v[184:187], v[44:47]
	v_mfma_f32_16x16x32_bf16 v[36:39], v[164:167], v[192:195], v[36:39]
	v_mfma_f32_16x16x32_bf16 v[28:31], v[172:175], v[192:195], v[28:31]
	v_mfma_f32_16x16x32_bf16 v[20:23], v[164:167], v[200:203], v[20:23]
	v_mfma_f32_16x16x32_bf16 v[12:15], v[172:175], v[200:203], v[12:15]
	v_mfma_f32_16x16x32_bf16 v[4:7], v[164:167], v[208:211], v[4:7]
	v_mfma_f32_16x16x32_bf16 v[0:3], v[172:175], v[208:211], v[0:3]
	v_mfma_f32_16x16x32_bf16 v[52:55], v[168:171], v[188:191], v[52:55]
	v_mfma_f32_16x16x32_bf16 v[44:47], v[180:183], v[188:191], v[44:47]
	v_mfma_f32_16x16x32_bf16 v[36:39], v[168:171], v[196:199], v[36:39]
	v_mfma_f32_16x16x32_bf16 v[28:31], v[180:183], v[196:199], v[28:31]
	v_mfma_f32_16x16x32_bf16 v[20:23], v[168:171], v[204:207], v[20:23]
	v_mfma_f32_16x16x32_bf16 v[12:15], v[180:183], v[204:207], v[12:15]
	v_mfma_f32_16x16x32_bf16 v[4:7], v[168:171], v[212:215], v[4:7]
	v_mfma_f32_16x16x32_bf16 v[0:3], v[180:183], v[212:215], v[0:3]
	s_setprio 0
	s_barrier
	s_add_i32 s3, 0, 0x18000
	v_add_u32_e32 v151, s3, v145
	s_add_i32 s33, 0, 0x1c000
	ds_read_b128 v[140:143], v151
	ds_read_b128 v[152:155], v151 offset:1024
	ds_read_b128 v[156:159], v151 offset:2048
	ds_read_b128 v[160:163], v151 offset:3072
	v_add_u32_e32 v151, s33, v145
	ds_read_b128 v[164:167], v151
	ds_read_b128 v[168:171], v151 offset:1024
	ds_read_b128 v[172:175], v151 offset:2048
	ds_read_b128 v[180:183], v151 offset:3072
	s_add_u32 s24, s24, 0xb0000
	s_addc_u32 s25, s25, 0
	s_mov_b32 m0, s36
	v_lshl_add_u64 v[224:225], s[24:25], 0, v[128:129]
	ds_read_b128 v[184:187], v149 offset:32768
	ds_read_b128 v[188:191], v149 offset:33792
	ds_read_b128 v[192:195], v149 offset:34816
	ds_read_b128 v[196:199], v149 offset:35840
	ds_read_b128 v[200:203], v149 offset:36864
	ds_read_b128 v[204:207], v149 offset:37888
	ds_read_b128 v[208:211], v149 offset:38912
	ds_read_b128 v[212:215], v149 offset:39936
	global_load_lds_dwordx4 v[224:225], off
	v_lshl_add_u64 v[224:225], s[24:25], 0, v[130:131]
	s_mov_b32 m0, s37
	s_nop 0
	global_load_lds_dwordx4 v[224:225], off
	s_waitcnt vmcnt(8)
	s_waitcnt lgkmcnt(0)
	s_barrier
	s_setprio 1
	s_waitcnt lgkmcnt(0)
	v_mfma_f32_16x16x32_bf16 v[124:127], v[140:143], v[184:187], v[124:127]
	v_mfma_f32_16x16x32_bf16 v[120:123], v[156:159], v[184:187], v[120:123]
	v_mfma_f32_16x16x32_bf16 v[112:115], v[140:143], v[192:195], v[112:115]
	v_mfma_f32_16x16x32_bf16 v[104:107], v[156:159], v[192:195], v[104:107]
	v_mfma_f32_16x16x32_bf16 v[96:99], v[140:143], v[200:203], v[96:99]
	v_mfma_f32_16x16x32_bf16 v[88:91], v[156:159], v[200:203], v[88:91]
	v_mfma_f32_16x16x32_bf16 v[80:83], v[140:143], v[208:211], v[80:83]
	v_mfma_f32_16x16x32_bf16 v[72:75], v[156:159], v[208:211], v[72:75]
	v_mfma_f32_16x16x32_bf16 v[124:127], v[152:155], v[188:191], v[124:127]
	v_mfma_f32_16x16x32_bf16 v[120:123], v[160:163], v[188:191], v[120:123]
	v_mfma_f32_16x16x32_bf16 v[112:115], v[152:155], v[196:199], v[112:115]
	v_mfma_f32_16x16x32_bf16 v[104:107], v[160:163], v[196:199], v[104:107]
	v_mfma_f32_16x16x32_bf16 v[96:99], v[152:155], v[204:207], v[96:99]
	v_mfma_f32_16x16x32_bf16 v[88:91], v[160:163], v[204:207], v[88:91]
	v_mfma_f32_16x16x32_bf16 v[80:83], v[152:155], v[212:215], v[80:83]
	v_mfma_f32_16x16x32_bf16 v[72:75], v[160:163], v[212:215], v[72:75]
	s_setprio 0
	s_setprio 1
	v_mfma_f32_16x16x32_bf16 v[116:119], v[164:167], v[184:187], v[116:119]
	v_mfma_f32_16x16x32_bf16 v[108:111], v[172:175], v[184:187], v[108:111]
	v_mfma_f32_16x16x32_bf16 v[100:103], v[164:167], v[192:195], v[100:103]
	v_mfma_f32_16x16x32_bf16 v[92:95], v[172:175], v[192:195], v[92:95]
	v_mfma_f32_16x16x32_bf16 v[84:87], v[164:167], v[200:203], v[84:87]
	v_mfma_f32_16x16x32_bf16 v[76:79], v[172:175], v[200:203], v[76:79]
	v_mfma_f32_16x16x32_bf16 v[68:71], v[164:167], v[208:211], v[68:71]
	v_mfma_f32_16x16x32_bf16 v[64:67], v[172:175], v[208:211], v[64:67]
	v_mfma_f32_16x16x32_bf16 v[116:119], v[168:171], v[188:191], v[116:119]
	v_mfma_f32_16x16x32_bf16 v[108:111], v[180:183], v[188:191], v[108:111]
	v_mfma_f32_16x16x32_bf16 v[100:103], v[168:171], v[196:199], v[100:103]
	v_mfma_f32_16x16x32_bf16 v[92:95], v[180:183], v[196:199], v[92:95]
	v_mfma_f32_16x16x32_bf16 v[84:87], v[168:171], v[204:207], v[84:87]
	v_mfma_f32_16x16x32_bf16 v[76:79], v[180:183], v[204:207], v[76:79]
	v_mfma_f32_16x16x32_bf16 v[68:71], v[168:171], v[212:215], v[68:71]
	v_mfma_f32_16x16x32_bf16 v[64:67], v[180:183], v[212:215], v[64:67]
	s_setprio 0
	s_barrier
; #define PG8_STAGE(bufoff, gbase, voff) do { _Pragma("unroll") for (int _i = 0; _i < 2; ++_i) \
;         __builtin_amdgcn_global_load_lds((const unsigned*)((const char*)(gbase) + (voff)[_i]), (PG8_LAS unsigned*)(lds + (bufoff) + ldsw + _i * 8192), 16, 0, 0); } while (0)
; #define PG8_LDA(dst, b, h) do { _Pragma("unroll") for (int m = 0; m < 4; ++m) _Pragma("unroll") for (int k = 0; k < 2; ++k) dst[m][k] = *(const PG8_LAS bf16x8*)(lds + PG8_SA(b, h) + aoff + m * 2048 + k * 1024); } while (0)
; #define PG8_WAIT_V(n) asm volatile("s_waitcnt vmcnt(" #n ")" ::: "memory")
; #define PG8_WAIT_L(n) asm volatile("s_waitcnt lgkmcnt(" #n ")" ::: "memory")
; #define PG8_BAR __builtin_amdgcn_s_barrier()
; #define PG8_SCHED __builtin_amdgcn_sched_barrier(0)
; template <class Epi, class Sched, bool ALIGN_EPI = false, bool SP2 = false>
; __device__ __forceinline__ void gemm_phase(PG8_LAS unsigned char* lds, const Gemm g, const Sched& S, const Epi& E) {
;     ...
;             PG8_LDA(At, 1, 1); PG8_STAGE(PG8_SB(1, 0), b3, voffB); PG8_STAGE(PG8_SB(1, 1), b3 + hstep, voffB); PG8_STAGE(PG8_SA(1, 0), a3, voffA);
;             PG8_WAIT_V(8); PG8_WAIT_L(0); PG8_BAR; PG8_MMA(1, 0, At, B0); PG8_MMA(1, 1, At, B1); PG8_BAR; PG8_SCHED;
;     __device__ __forceinline__ void operator()(const AccT& acc, const pg8::Unit& u, int wr, int wc, int fr, int fq) const {
;         const int col0 = u.pn * 256 + wc * 32 + 4 * fq, row0 = row_base + u.pm * 256 + wr * 64 + fr;
; #pragma unroll
;         for (int ai = 0; ai < 2; ++ai)
; #pragma unroll
;             for (int m = 0; m < 4; ++m) { const int row = row0 + ai * 128 + m * 16; float ss = 0.f;
; #pragma unroll
;                 for (int bj = 0; bj < 2; ++bj)
; #pragma unroll
;                     for (int n = 0; n < 2; ++n) { f32x4 v = acc[ai][bj][m][n]; const size_t idx = (size_t)row * 1024 + col0 + bj * 128 + n * 16;
;                         if (MODE == 0) v = v * up4(*(const u32x2*)(io + idx));
;                         else if (MODE == 1) v = up4(*(const u32x2*)(io + idx)) + up4(*(const u32x2*)(g2 + idx)) * v;
;                         else ss += (v[0] * v[0] + v[1] * v[1]) + (v[2] * v[2] + v[3] * v[3]);
;                         if (!DRYE || v[0] == 123.456f) *(u32x2*)(io + idx) = pk4(v); }
;                 if (MODE == 2 && !DRYE) { ss += __shfl_xor(ss, 16); ss += __shfl_xor(ss, 32); if (fq == 0) atomicAdd(rowss + row, ss); } }
	s_add_i32 s3, s3, s31
	v_lshl_add_u64 v[216:217], v[216:217], 0, s[18:19]
	s_mov_b32 m0, s3
	ds_read_b128 v[184:187], v149 offset:49152
	ds_read_b128 v[188:191], v149 offset:50176
	ds_read_b128 v[192:195], v149 offset:51200
	ds_read_b128 v[196:199], v149 offset:52224
	ds_read_b128 v[200:203], v149 offset:53248
	ds_read_b128 v[204:207], v149 offset:54272
	ds_read_b128 v[208:211], v149 offset:55296
	ds_read_b128 v[212:215], v149 offset:56320
	global_load_lds_dwordx4 v[216:217], off
	s_add_i32 m0, s3, 0x2000
	s_add_u32 s22, s22, 0xb0080
	v_lshl_add_u64 v[216:217], v[218:219], 0, s[18:19]
	s_addc_u32 s23, s23, 0
	s_add_i32 s3, s33, s31
	global_load_lds_dwordx4 v[216:217], off
	v_lshl_add_u64 v[216:217], s[22:23], 0, v[128:129]
	s_mov_b32 m0, s3
	s_nop 0
	global_load_lds_dwordx4 v[216:217], off
	v_lshl_add_u64 v[216:217], s[22:23], 0, v[130:131]
	s_add_i32 m0, s3, 0x2000
	s_nop 0
	global_load_lds_dwordx4 v[216:217], off
	v_lshl_add_u64 v[216:217], v[220:221], 0, s[18:19]
	s_mov_b32 m0, s39
	s_nop 0
	global_load_lds_dwordx4 v[216:217], off
	v_lshl_add_u64 v[216:217], v[222:223], 0, s[18:19]
	s_mov_b32 m0, s40
	s_nop 0
	global_load_lds_dwordx4 v[216:217], off
	s_waitcnt vmcnt(8)
	s_waitcnt lgkmcnt(0)
	s_barrier
	s_setprio 1
	s_waitcnt lgkmcnt(0)
	v_mfma_f32_16x16x32_bf16 v[60:63], v[140:143], v[184:187], v[60:63]
	v_mfma_f32_16x16x32_bf16 v[56:59], v[156:159], v[184:187], v[56:59]
	v_mfma_f32_16x16x32_bf16 v[48:51], v[140:143], v[192:195], v[48:51]
	v_mfma_f32_16x16x32_bf16 v[40:43], v[156:159], v[192:195], v[40:43]
	v_mfma_f32_16x16x32_bf16 v[32:35], v[140:143], v[200:203], v[32:35]
	v_mfma_f32_16x16x32_bf16 v[24:27], v[156:159], v[200:203], v[24:27]
	v_mfma_f32_16x16x32_bf16 v[16:19], v[140:143], v[208:211], v[16:19]
	v_mfma_f32_16x16x32_bf16 v[8:11], v[156:159], v[208:211], v[8:11]
	v_mfma_f32_16x16x32_bf16 v[60:63], v[152:155], v[188:191], v[60:63]
	v_mfma_f32_16x16x32_bf16 v[56:59], v[160:163], v[188:191], v[56:59]
	v_mfma_f32_16x16x32_bf16 v[48:51], v[152:155], v[196:199], v[48:51]
	v_mfma_f32_16x16x32_bf16 v[40:43], v[160:163], v[196:199], v[40:43]
	v_mfma_f32_16x16x32_bf16 v[32:35], v[152:155], v[204:207], v[32:35]
	v_mfma_f32_16x16x32_bf16 v[24:27], v[160:163], v[204:207], v[24:27]
	v_mfma_f32_16x16x32_bf16 v[16:19], v[152:155], v[212:215], v[16:19]
	v_mfma_f32_16x16x32_bf16 v[8:11], v[160:163], v[212:215], v[8:11]
	s_setprio 0
	s_setprio 1
	v_mfma_f32_16x16x32_bf16 v[52:55], v[164:167], v[184:187], v[52:55]
	v_mfma_f32_16x16x32_bf16 v[44:47], v[172:175], v[184:187], v[44:47]
	v_mfma_f32_16x16x32_bf16 v[36:39], v[164:167], v[192:195], v[36:39]
	v_mfma_f32_16x16x32_bf16 v[28:31], v[172:175], v[192:195], v[28:31]
	v_mfma_f32_16x16x32_bf16 v[20:23], v[164:167], v[200:203], v[20:23]
	v_mfma_f32_16x16x32_bf16 v[12:15], v[172:175], v[200:203], v[12:15]
	v_mfma_f32_16x16x32_bf16 v[4:7], v[164:167], v[208:211], v[4:7]
	v_mfma_f32_16x16x32_bf16 v[0:3], v[172:175], v[208:211], v[0:3]
	v_mfma_f32_16x16x32_bf16 v[52:55], v[168:171], v[188:191], v[52:55]
	v_mfma_f32_16x16x32_bf16 v[44:47], v[180:183], v[188:191], v[44:47]
	v_mfma_f32_16x16x32_bf16 v[36:39], v[168:171], v[196:199], v[36:39]
	v_mfma_f32_16x16x32_bf16 v[28:31], v[180:183], v[196:199], v[28:31]
	v_mfma_f32_16x16x32_bf16 v[20:23], v[168:171], v[204:207], v[20:23]
	v_mfma_f32_16x16x32_bf16 v[12:15], v[180:183], v[204:207], v[12:15]
	v_mfma_f32_16x16x32_bf16 v[4:7], v[168:171], v[212:215], v[4:7]
	v_mfma_f32_16x16x32_bf16 v[0:3], v[180:183], v[212:215], v[0:3]
	s_setprio 0
	s_barrier
	s_add_i32 s60, s60, 2
	s_add_u32 s20, s20, 0x100
	s_addc_u32 s21, s21, 0
	s_add_u32 s50, s50, 0x100
	s_addc_u32 s51, s51, 0
	s_cmp_gt_u32 s60, 41
	s_cbranch_scc0 .LBB0_1287
	v_and_b32_e32 v151, 64, v150
	v_xor_b32_e32 v143, 16, v150
	v_add_u32_e32 v151, 64, v151
	v_cmp_lt_i32_e32 vcc, v143, v151
	v_lshl_add_u32 v142, s48, 8, v144
	v_lshl_or_b32 v140, s49, 8, v146
	v_cndmask_b32_e32 v143, v150, v143, vcc
	v_lshlrev_b32_e32 v152, 2, v143
	v_xor_b32_e32 v143, 32, v150
	v_cmp_lt_i32_e32 vcc, v143, v151
	v_mul_f32_e32 v153, v125, v125
	v_mul_f32_e32 v156, v127, v127
	v_cndmask_b32_e32 v143, v150, v143, vcc
	v_lshlrev_b32_e32 v151, 2, v143
	v_ashrrev_i32_e32 v143, 31, v142
	v_lshlrev_b64 v[154:155], 11, v[142:143]
	v_ashrrev_i32_e32 v141, 31, v140
	v_fmac_f32_e32 v153, v124, v124
	v_fmac_f32_e32 v156, v126, v126
	v_cvt_pk_bf16_f32 v124, v124, v125
	v_cvt_pk_bf16_f32 v125, v126, v127
	v_lshl_add_u64 v[126:127], s[14:15], 0, v[154:155]
	v_lshl_add_u64 v[126:127], v[140:141], 1, v[126:127]
	global_store_dwordx2 v[126:127], v[124:125], off
	v_mul_f32_e32 v124, v121, v121
	v_mul_f32_e32 v125, v123, v123
	v_fmac_f32_e32 v124, v120, v120
	v_fmac_f32_e32 v125, v122, v122
	v_add_f32_e32 v124, v124, v125
	v_cvt_pk_bf16_f32 v120, v120, v121
	v_mul_f32_e32 v121, v117, v117
	v_mul_f32_e32 v125, v119, v119
	v_add_f32_e32 v153, v153, v156
	v_fmac_f32_e32 v121, v116, v116
	v_fmac_f32_e32 v125, v118, v118
	v_add_f32_e32 v124, v153, v124
	v_add_f32_e32 v121, v121, v125
	v_add_f32_e32 v121, v124, v121
	v_mul_f32_e32 v124, v109, v109
	v_mul_f32_e32 v125, v111, v111
	v_fmac_f32_e32 v124, v108, v108
	v_fmac_f32_e32 v125, v110, v110
	v_add_f32_e32 v124, v124, v125
	v_add_f32_e32 v124, v121, v124
	v_mov_b32_e32 v125, v124
	s_nop 1
	v_permlane16_swap_b32_e32 v124, v125
	v_cvt_pk_bf16_f32 v121, v122, v123
	global_store_dwordx2 v[126:127], v[120:121], off offset:32
	v_cvt_pk_bf16_f32 v120, v116, v117
	v_cvt_pk_bf16_f32 v121, v118, v119
	s_waitcnt lgkmcnt(0)
	v_add_f32_e32 v116, v124, v125
	v_mov_b32_e32 v117, v116
	s_nop 1
	v_permlane32_swap_b32_e32 v116, v117
	v_cvt_pk_bf16_f32 v108, v108, v109
	v_cvt_pk_bf16_f32 v109, v110, v111
	global_store_dwordx2 v[126:127], v[120:121], off offset:256
	global_store_dwordx2 v[126:127], v[108:109], off offset:288
	s_and_saveexec_b64 s[20:21], s[0:1]
	s_cbranch_execz .LBB0_1290
	v_lshl_add_u64 v[108:109], v[142:143], 2, s[16:17]
	s_waitcnt lgkmcnt(0)
	v_add_f32_e32 v110, v116, v117
	global_atomic_add_f32 v[108:109], v110, off
; __device__ __forceinline__ u32x2 pk4(f32x4 v) { u32x2 w; w.x = cvt_pk_bf16(v[0], v[1]); w.y = cvt_pk_bf16(v[2], v[3]); return w; }
; __device__ __forceinline__ f32x4 up4(u32x2 w) { return (f32x4){bf_lo(w.x), bf_hi(w.x), bf_lo(w.y), bf_hi(w.y)}; }
;     __device__ __forceinline__ void operator()(const AccT& acc, const pg8::Unit& u, int wr, int wc, int fr, int fq) const {
;     ...
;             for (int m = 0; m < 4; ++m) { const int row = row0 + ai * 128 + m * 16; float ss = 0.f;
; #pragma unroll
;                 for (int bj = 0; bj < 2; ++bj)
; #pragma unroll
;                     for (int n = 0; n < 2; ++n) { f32x4 v = acc[ai][bj][m][n]; const size_t idx = (size_t)row * 1024 + col0 + bj * 128 + n * 16;
;                         if (MODE == 0) v = v * up4(*(const u32x2*)(io + idx));
;                         else if (MODE == 1) v = up4(*(const u32x2*)(io + idx)) + up4(*(const u32x2*)(g2 + idx)) * v;
;                         else ss += (v[0] * v[0] + v[1] * v[1]) + (v[2] * v[2] + v[3] * v[3]);
;                         if (!DRYE || v[0] == 123.456f) *(u32x2*)(io + idx) = pk4(v); }
;                 if (MODE == 2 && !DRYE) { ss += __shfl_xor(ss, 16); ss += __shfl_xor(ss, 32); if (fq == 0) atomicAdd(rowss + row, ss); } }
.LBB0_1290:
	s_or_b64 exec, exec, s[20:21]
	v_or_b32_e32 v108, 16, v142
	v_ashrrev_i32_e32 v109, 31, v108
	v_lshlrev_b64 v[110:111], 11, v[108:109]
	v_mul_f32_e32 v116, v113, v113
	v_lshl_add_u64 v[110:111], s[14:15], 0, v[110:111]
	v_fmac_f32_e32 v116, v112, v112
	v_cvt_pk_bf16_f32 v112, v112, v113
	v_cvt_pk_bf16_f32 v113, v114, v115
	v_lshl_add_u64 v[110:111], v[140:141], 1, v[110:111]
	global_store_dwordx2 v[110:111], v[112:113], off
	v_mul_f32_e32 v112, v105, v105
	v_mul_f32_e32 v113, v107, v107
	s_waitcnt lgkmcnt(0)
	v_mul_f32_e32 v117, v115, v115
	v_fmac_f32_e32 v112, v104, v104
	v_fmac_f32_e32 v113, v106, v106
	v_fmac_f32_e32 v117, v114, v114
	v_add_f32_e32 v112, v112, v113
	v_cvt_pk_bf16_f32 v104, v104, v105
	v_mul_f32_e32 v105, v101, v101
	v_mul_f32_e32 v113, v103, v103
	v_add_f32_e32 v116, v116, v117
	v_fmac_f32_e32 v105, v100, v100
	v_fmac_f32_e32 v113, v102, v102
	v_add_f32_e32 v112, v116, v112
	v_add_f32_e32 v105, v105, v113
	v_add_f32_e32 v105, v112, v105
	v_mul_f32_e32 v112, v93, v93
	v_mul_f32_e32 v113, v95, v95
	v_fmac_f32_e32 v112, v92, v92
	v_fmac_f32_e32 v113, v94, v94
	v_add_f32_e32 v112, v112, v113
	v_add_f32_e32 v112, v105, v112
	v_mov_b32_e32 v113, v112
	s_nop 1
	v_permlane16_swap_b32_e32 v112, v113
	v_cvt_pk_bf16_f32 v105, v106, v107
	global_store_dwordx2 v[110:111], v[104:105], off offset:32
	v_cvt_pk_bf16_f32 v104, v100, v101
	v_cvt_pk_bf16_f32 v105, v102, v103
	s_waitcnt lgkmcnt(0)
	v_add_f32_e32 v100, v112, v113
	v_mov_b32_e32 v101, v100
	s_nop 1
	v_permlane32_swap_b32_e32 v100, v101
	v_cvt_pk_bf16_f32 v92, v92, v93
	v_cvt_pk_bf16_f32 v93, v94, v95
	global_store_dwordx2 v[110:111], v[104:105], off offset:256
	global_store_dwordx2 v[110:111], v[92:93], off offset:288
	s_and_saveexec_b64 s[20:21], s[0:1]
	s_cbranch_execz .LBB0_1292
	v_lshl_add_u64 v[92:93], v[108:109], 2, s[16:17]
	s_waitcnt lgkmcnt(0)
	v_add_f32_e32 v94, v100, v101
	global_atomic_add_f32 v[92:93], v94, off
.LBB0_1292:
	s_or_b64 exec, exec, s[20:21]
	v_or_b32_e32 v92, 32, v142
	v_ashrrev_i32_e32 v93, 31, v92
	v_lshlrev_b64 v[94:95], 11, v[92:93]
	v_mul_f32_e32 v100, v97, v97
	v_lshl_add_u64 v[94:95], s[14:15], 0, v[94:95]
	v_fmac_f32_e32 v100, v96, v96
	v_cvt_pk_bf16_f32 v96, v96, v97
	v_cvt_pk_bf16_f32 v97, v98, v99
	v_lshl_add_u64 v[94:95], v[140:141], 1, v[94:95]
	global_store_dwordx2 v[94:95], v[96:97], off
	v_mul_f32_e32 v96, v89, v89
	v_mul_f32_e32 v97, v91, v91
	s_waitcnt lgkmcnt(0)
	v_mul_f32_e32 v101, v99, v99
	v_fmac_f32_e32 v96, v88, v88
	v_fmac_f32_e32 v97, v90, v90
	v_fmac_f32_e32 v101, v98, v98
	v_add_f32_e32 v96, v96, v97
	v_cvt_pk_bf16_f32 v88, v88, v89
	v_mul_f32_e32 v89, v85, v85
	v_mul_f32_e32 v97, v87, v87
	v_add_f32_e32 v100, v100, v101
	v_fmac_f32_e32 v89, v84, v84
	v_fmac_f32_e32 v97, v86, v86
	v_add_f32_e32 v96, v100, v96
	v_add_f32_e32 v89, v89, v97
	v_add_f32_e32 v89, v96, v89
	v_mul_f32_e32 v96, v77, v77
	v_mul_f32_e32 v97, v79, v79
	v_fmac_f32_e32 v96, v76, v76
	v_fmac_f32_e32 v97, v78, v78
	v_add_f32_e32 v96, v96, v97
	v_add_f32_e32 v96, v89, v96
	v_mov_b32_e32 v97, v96
	s_nop 1
	v_permlane16_swap_b32_e32 v96, v97
	v_cvt_pk_bf16_f32 v89, v90, v91
	global_store_dwordx2 v[94:95], v[88:89], off offset:32
	v_cvt_pk_bf16_f32 v88, v84, v85
	v_cvt_pk_bf16_f32 v89, v86, v87
	s_waitcnt lgkmcnt(0)
	v_add_f32_e32 v84, v96, v97
	v_mov_b32_e32 v85, v84
	s_nop 1
	v_permlane32_swap_b32_e32 v84, v85
	v_cvt_pk_bf16_f32 v76, v76, v77
	v_cvt_pk_bf16_f32 v77, v78, v79
	global_store_dwordx2 v[94:95], v[88:89], off offset:256
	global_store_dwordx2 v[94:95], v[76:77], off offset:288
	s_and_saveexec_b64 s[20:21], s[0:1]
	s_cbranch_execz .LBB0_1294
	v_lshl_add_u64 v[76:77], v[92:93], 2, s[16:17]
	s_waitcnt lgkmcnt(0)
	v_add_f32_e32 v78, v84, v85
	global_atomic_add_f32 v[76:77], v78, off
.LBB0_1294:
	s_or_b64 exec, exec, s[20:21]
	v_or_b32_e32 v76, 48, v142
	v_ashrrev_i32_e32 v77, 31, v76
	v_lshlrev_b64 v[78:79], 11, v[76:77]
	v_mul_f32_e32 v84, v81, v81
	v_lshl_add_u64 v[78:79], s[14:15], 0, v[78:79]
	v_fmac_f32_e32 v84, v80, v80
	v_cvt_pk_bf16_f32 v80, v80, v81
	v_cvt_pk_bf16_f32 v81, v82, v83
	v_lshl_add_u64 v[78:79], v[140:141], 1, v[78:79]
	global_store_dwordx2 v[78:79], v[80:81], off
	v_mul_f32_e32 v80, v73, v73
	v_mul_f32_e32 v81, v75, v75
	s_waitcnt lgkmcnt(0)
	v_mul_f32_e32 v85, v83, v83
	v_fmac_f32_e32 v80, v72, v72
	v_fmac_f32_e32 v81, v74, v74
	v_fmac_f32_e32 v85, v82, v82
	v_add_f32_e32 v80, v80, v81
	v_cvt_pk_bf16_f32 v72, v72, v73
	v_mul_f32_e32 v73, v69, v69
	v_mul_f32_e32 v81, v71, v71
	v_add_f32_e32 v84, v84, v85
	v_fmac_f32_e32 v73, v68, v68
	v_fmac_f32_e32 v81, v70, v70
	v_add_f32_e32 v80, v84, v80
	v_add_f32_e32 v73, v73, v81
	v_add_f32_e32 v73, v80, v73
	v_mul_f32_e32 v80, v65, v65
	v_mul_f32_e32 v81, v67, v67
	v_fmac_f32_e32 v80, v64, v64
	v_fmac_f32_e32 v81, v66, v66
	v_add_f32_e32 v80, v80, v81
	v_add_f32_e32 v80, v73, v80
	v_mov_b32_e32 v81, v80
	s_nop 1
	v_permlane16_swap_b32_e32 v80, v81
	v_cvt_pk_bf16_f32 v73, v74, v75
	global_store_dwordx2 v[78:79], v[72:73], off offset:32
	v_cvt_pk_bf16_f32 v72, v68, v69
	v_cvt_pk_bf16_f32 v73, v70, v71
	s_waitcnt lgkmcnt(0)
	v_add_f32_e32 v68, v80, v81
	v_mov_b32_e32 v69, v68
	s_nop 1
	v_permlane32_swap_b32_e32 v68, v69
	v_cvt_pk_bf16_f32 v64, v64, v65
	v_cvt_pk_bf16_f32 v65, v66, v67
	global_store_dwordx2 v[78:79], v[72:73], off offset:256
	global_store_dwordx2 v[78:79], v[64:65], off offset:288
	s_and_saveexec_b64 s[20:21], s[0:1]
	s_cbranch_execz .LBB0_1296
	v_lshl_add_u64 v[64:65], v[76:77], 2, s[16:17]
	s_waitcnt lgkmcnt(0)
	v_add_f32_e32 v66, v68, v69
	global_atomic_add_f32 v[64:65], v66, off
; __device__ __forceinline__ u32x2 pk4(f32x4 v) { u32x2 w; w.x = cvt_pk_bf16(v[0], v[1]); w.y = cvt_pk_bf16(v[2], v[3]); return w; }
; __device__ __forceinline__ f32x4 up4(u32x2 w) { return (f32x4){bf_lo(w.x), bf_hi(w.x), bf_lo(w.y), bf_hi(w.y)}; }
;     __device__ __forceinline__ void operator()(const AccT& acc, const pg8::Unit& u, int wr, int wc, int fr, int fq) const {
;     ...
;             for (int m = 0; m < 4; ++m) { const int row = row0 + ai * 128 + m * 16; float ss = 0.f;
; #pragma unroll
;                 for (int bj = 0; bj < 2; ++bj)
; #pragma unroll
;                     for (int n = 0; n < 2; ++n) { f32x4 v = acc[ai][bj][m][n]; const size_t idx = (size_t)row * 1024 + col0 + bj * 128 + n * 16;
;                         if (MODE == 0) v = v * up4(*(const u32x2*)(io + idx));
;                         else if (MODE == 1) v = up4(*(const u32x2*)(io + idx)) + up4(*(const u32x2*)(g2 + idx)) * v;
;                         else ss += (v[0] * v[0] + v[1] * v[1]) + (v[2] * v[2] + v[3] * v[3]);
;                         if (!DRYE || v[0] == 123.456f) *(u32x2*)(io + idx) = pk4(v); }
;                 if (MODE == 2 && !DRYE) { ss += __shfl_xor(ss, 16); ss += __shfl_xor(ss, 32); if (fq == 0) atomicAdd(rowss + row, ss); } }
.LBB0_1296:
	s_or_b64 exec, exec, s[20:21]
	v_add_u32_e32 v64, 0x80, v142
	v_ashrrev_i32_e32 v65, 31, v64
	v_lshlrev_b64 v[66:67], 11, v[64:65]
	v_mul_f32_e32 v68, v61, v61
	s_waitcnt lgkmcnt(0)
	v_mul_f32_e32 v69, v63, v63
	v_fmac_f32_e32 v68, v60, v60
	v_fmac_f32_e32 v69, v62, v62
	v_cvt_pk_bf16_f32 v60, v60, v61
	v_cvt_pk_bf16_f32 v61, v62, v63
	v_lshl_add_u64 v[62:63], s[14:15], 0, v[66:67]
	v_lshl_add_u64 v[62:63], v[140:141], 1, v[62:63]
	global_store_dwordx2 v[62:63], v[60:61], off
	v_mul_f32_e32 v60, v57, v57
	v_mul_f32_e32 v61, v59, v59
	v_fmac_f32_e32 v60, v56, v56
	v_fmac_f32_e32 v61, v58, v58
	v_add_f32_e32 v60, v60, v61
	v_cvt_pk_bf16_f32 v56, v56, v57
	v_mul_f32_e32 v57, v53, v53
	v_mul_f32_e32 v61, v55, v55
	v_add_f32_e32 v68, v68, v69
	v_fmac_f32_e32 v57, v52, v52
	v_fmac_f32_e32 v61, v54, v54
	v_add_f32_e32 v60, v68, v60
	v_add_f32_e32 v57, v57, v61
	v_add_f32_e32 v57, v60, v57
	v_mul_f32_e32 v60, v45, v45
	v_mul_f32_e32 v61, v47, v47
	v_fmac_f32_e32 v60, v44, v44
	v_fmac_f32_e32 v61, v46, v46
	v_add_f32_e32 v60, v60, v61
	v_add_f32_e32 v60, v57, v60
	v_mov_b32_e32 v61, v60
	s_nop 1
	v_permlane16_swap_b32_e32 v60, v61
	v_cvt_pk_bf16_f32 v57, v58, v59
	global_store_dwordx2 v[62:63], v[56:57], off offset:32
	v_cvt_pk_bf16_f32 v56, v52, v53
	v_cvt_pk_bf16_f32 v57, v54, v55
	s_waitcnt lgkmcnt(0)
	v_add_f32_e32 v52, v60, v61
	v_mov_b32_e32 v53, v52
	s_nop 1
	v_permlane32_swap_b32_e32 v52, v53
	v_cvt_pk_bf16_f32 v44, v44, v45
	v_cvt_pk_bf16_f32 v45, v46, v47
	global_store_dwordx2 v[62:63], v[56:57], off offset:256
	global_store_dwordx2 v[62:63], v[44:45], off offset:288
	s_and_saveexec_b64 s[20:21], s[0:1]
	s_cbranch_execz .LBB0_1298
	v_lshl_add_u64 v[44:45], v[64:65], 2, s[16:17]
	s_waitcnt lgkmcnt(0)
	v_add_f32_e32 v46, v52, v53
	global_atomic_add_f32 v[44:45], v46, off
.LBB0_1298:
	s_or_b64 exec, exec, s[20:21]
	v_add_u32_e32 v44, 0x90, v142
	v_ashrrev_i32_e32 v45, 31, v44
	v_lshlrev_b64 v[46:47], 11, v[44:45]
	v_mul_f32_e32 v52, v49, v49
	v_lshl_add_u64 v[46:47], s[14:15], 0, v[46:47]
	v_fmac_f32_e32 v52, v48, v48
	v_cvt_pk_bf16_f32 v48, v48, v49
	v_cvt_pk_bf16_f32 v49, v50, v51
	v_lshl_add_u64 v[46:47], v[140:141], 1, v[46:47]
	global_store_dwordx2 v[46:47], v[48:49], off
	v_mul_f32_e32 v48, v41, v41
	v_mul_f32_e32 v49, v43, v43
	s_waitcnt lgkmcnt(0)
	v_mul_f32_e32 v53, v51, v51
	v_fmac_f32_e32 v48, v40, v40
	v_fmac_f32_e32 v49, v42, v42
	v_fmac_f32_e32 v53, v50, v50
	v_add_f32_e32 v48, v48, v49
	v_cvt_pk_bf16_f32 v40, v40, v41
	v_mul_f32_e32 v41, v37, v37
	v_mul_f32_e32 v49, v39, v39
	v_add_f32_e32 v52, v52, v53
	v_fmac_f32_e32 v41, v36, v36
	v_fmac_f32_e32 v49, v38, v38
	v_add_f32_e32 v48, v52, v48
	v_add_f32_e32 v41, v41, v49
	v_add_f32_e32 v41, v48, v41
	v_mul_f32_e32 v48, v29, v29
	v_mul_f32_e32 v49, v31, v31
	v_fmac_f32_e32 v48, v28, v28
	v_fmac_f32_e32 v49, v30, v30
	v_add_f32_e32 v48, v48, v49
	v_add_f32_e32 v48, v41, v48
	v_mov_b32_e32 v49, v48
	s_nop 1
	v_permlane16_swap_b32_e32 v48, v49
	v_cvt_pk_bf16_f32 v41, v42, v43
	global_store_dwordx2 v[46:47], v[40:41], off offset:32
	v_cvt_pk_bf16_f32 v40, v36, v37
	v_cvt_pk_bf16_f32 v41, v38, v39
	s_waitcnt lgkmcnt(0)
	v_add_f32_e32 v36, v48, v49
	v_mov_b32_e32 v37, v36
	s_nop 1
	v_permlane32_swap_b32_e32 v36, v37
	v_cvt_pk_bf16_f32 v28, v28, v29
	v_cvt_pk_bf16_f32 v29, v30, v31
	global_store_dwordx2 v[46:47], v[40:41], off offset:256
	global_store_dwordx2 v[46:47], v[28:29], off offset:288
	s_and_saveexec_b64 s[20:21], s[0:1]
	s_cbranch_execz .LBB0_1300
	v_lshl_add_u64 v[28:29], v[44:45], 2, s[16:17]
	s_waitcnt lgkmcnt(0)
	v_add_f32_e32 v30, v36, v37
	global_atomic_add_f32 v[28:29], v30, off
; __device__ __forceinline__ u32x2 pk4(f32x4 v) { u32x2 w; w.x = cvt_pk_bf16(v[0], v[1]); w.y = cvt_pk_bf16(v[2], v[3]); return w; }
; __device__ __forceinline__ f32x4 up4(u32x2 w) { return (f32x4){bf_lo(w.x), bf_hi(w.x), bf_lo(w.y), bf_hi(w.y)}; }
;     __device__ __forceinline__ void operator()(const AccT& acc, const pg8::Unit& u, int wr, int wc, int fr, int fq) const {
;     ...
;             for (int m = 0; m < 4; ++m) { const int row = row0 + ai * 128 + m * 16; float ss = 0.f;
; #pragma unroll
;                 for (int bj = 0; bj < 2; ++bj)
; #pragma unroll
;                     for (int n = 0; n < 2; ++n) { f32x4 v = acc[ai][bj][m][n]; const size_t idx = (size_t)row * 1024 + col0 + bj * 128 + n * 16;
;                         if (MODE == 0) v = v * up4(*(const u32x2*)(io + idx));
;                         else if (MODE == 1) v = up4(*(const u32x2*)(io + idx)) + up4(*(const u32x2*)(g2 + idx)) * v;
;                         else ss += (v[0] * v[0] + v[1] * v[1]) + (v[2] * v[2] + v[3] * v[3]);
;                         if (!DRYE || v[0] == 123.456f) *(u32x2*)(io + idx) = pk4(v); }
;                 if (MODE == 2 && !DRYE) { ss += __shfl_xor(ss, 16); ss += __shfl_xor(ss, 32); if (fq == 0) atomicAdd(rowss + row, ss); } }
.LBB0_1300:
	s_or_b64 exec, exec, s[20:21]
	v_add_u32_e32 v28, 0xa0, v142
	v_ashrrev_i32_e32 v29, 31, v28
	v_lshlrev_b64 v[30:31], 11, v[28:29]
	v_mul_f32_e32 v36, v33, v33
	v_lshl_add_u64 v[30:31], s[14:15], 0, v[30:31]
	v_fmac_f32_e32 v36, v32, v32
	v_cvt_pk_bf16_f32 v32, v32, v33
	v_cvt_pk_bf16_f32 v33, v34, v35
	v_lshl_add_u64 v[30:31], v[140:141], 1, v[30:31]
	global_store_dwordx2 v[30:31], v[32:33], off
	v_mul_f32_e32 v32, v25, v25
	v_mul_f32_e32 v33, v27, v27
	s_waitcnt lgkmcnt(0)
	v_mul_f32_e32 v37, v35, v35
	v_fmac_f32_e32 v32, v24, v24
	v_fmac_f32_e32 v33, v26, v26
	v_fmac_f32_e32 v37, v34, v34
	v_add_f32_e32 v32, v32, v33
	v_cvt_pk_bf16_f32 v24, v24, v25
	v_mul_f32_e32 v25, v21, v21
	v_mul_f32_e32 v33, v23, v23
	v_add_f32_e32 v36, v36, v37
	v_fmac_f32_e32 v25, v20, v20
	v_fmac_f32_e32 v33, v22, v22
	v_add_f32_e32 v32, v36, v32
	v_add_f32_e32 v25, v25, v33
	v_add_f32_e32 v25, v32, v25
	v_mul_f32_e32 v32, v13, v13
	v_mul_f32_e32 v33, v15, v15
	v_fmac_f32_e32 v32, v12, v12
	v_fmac_f32_e32 v33, v14, v14
	v_add_f32_e32 v32, v32, v33
	v_add_f32_e32 v32, v25, v32
	v_mov_b32_e32 v33, v32
	s_nop 1
	v_permlane16_swap_b32_e32 v32, v33
	v_cvt_pk_bf16_f32 v25, v26, v27
	global_store_dwordx2 v[30:31], v[24:25], off offset:32
	v_cvt_pk_bf16_f32 v24, v20, v21
	v_cvt_pk_bf16_f32 v25, v22, v23
	s_waitcnt lgkmcnt(0)
	v_add_f32_e32 v20, v32, v33
	v_mov_b32_e32 v21, v20
	s_nop 1
	v_permlane32_swap_b32_e32 v20, v21
	v_cvt_pk_bf16_f32 v12, v12, v13
	v_cvt_pk_bf16_f32 v13, v14, v15
	global_store_dwordx2 v[30:31], v[24:25], off offset:256
	global_store_dwordx2 v[30:31], v[12:13], off offset:288
	s_and_saveexec_b64 s[20:21], s[0:1]
	s_cbranch_execz .LBB0_1302
	v_lshl_add_u64 v[12:13], v[28:29], 2, s[16:17]
	s_waitcnt lgkmcnt(0)
	v_add_f32_e32 v14, v20, v21
	global_atomic_add_f32 v[12:13], v14, off
.LBB0_1302:
	s_or_b64 exec, exec, s[20:21]
	v_add_u32_e32 v12, 0xb0, v142
	v_ashrrev_i32_e32 v13, 31, v12
	v_lshlrev_b64 v[14:15], 11, v[12:13]
	v_mul_f32_e32 v20, v17, v17
	v_lshl_add_u64 v[14:15], s[14:15], 0, v[14:15]
	v_fmac_f32_e32 v20, v16, v16
	v_cvt_pk_bf16_f32 v16, v16, v17
	v_cvt_pk_bf16_f32 v17, v18, v19
	v_lshl_add_u64 v[14:15], v[140:141], 1, v[14:15]
	global_store_dwordx2 v[14:15], v[16:17], off
	v_mul_f32_e32 v16, v9, v9
	v_mul_f32_e32 v17, v11, v11
	s_waitcnt lgkmcnt(0)
	v_mul_f32_e32 v21, v19, v19
	v_fmac_f32_e32 v16, v8, v8
	v_fmac_f32_e32 v17, v10, v10
	v_fmac_f32_e32 v21, v18, v18
	v_add_f32_e32 v16, v16, v17
	v_cvt_pk_bf16_f32 v8, v8, v9
	v_mul_f32_e32 v9, v5, v5
	v_mul_f32_e32 v17, v7, v7
	v_add_f32_e32 v20, v20, v21
	v_fmac_f32_e32 v9, v4, v4
	v_fmac_f32_e32 v17, v6, v6
	v_add_f32_e32 v16, v20, v16
	v_add_f32_e32 v9, v9, v17
	v_add_f32_e32 v9, v16, v9
	v_mul_f32_e32 v16, v1, v1
	v_mul_f32_e32 v17, v3, v3
	v_fmac_f32_e32 v16, v0, v0
	v_fmac_f32_e32 v17, v2, v2
	v_add_f32_e32 v16, v16, v17
	v_add_f32_e32 v16, v9, v16
	v_mov_b32_e32 v17, v16
	s_nop 1
	v_permlane16_swap_b32_e32 v16, v17
	v_cvt_pk_bf16_f32 v9, v10, v11
	global_store_dwordx2 v[14:15], v[8:9], off offset:32
	v_cvt_pk_bf16_f32 v8, v4, v5
	v_cvt_pk_bf16_f32 v9, v6, v7
	s_waitcnt lgkmcnt(0)
	v_add_f32_e32 v4, v16, v17
	v_mov_b32_e32 v5, v4
	s_nop 1
	v_permlane32_swap_b32_e32 v4, v5
	v_cvt_pk_bf16_f32 v0, v0, v1
	v_cvt_pk_bf16_f32 v1, v2, v3
	global_store_dwordx2 v[14:15], v[8:9], off offset:256
	global_store_dwordx2 v[14:15], v[0:1], off offset:288
	s_and_saveexec_b64 s[20:21], s[0:1]
	s_cbranch_execz .LBB0_1275
	v_lshl_add_u64 v[0:1], v[12:13], 2, s[16:17]
	s_waitcnt lgkmcnt(0)
	v_add_f32_e32 v2, v4, v5
	global_atomic_add_f32 v[0:1], v2, off
	s_branch .LBB0_1275

; #define GEMM_N1024(EPI, Aoff, Woff, Mrows, Kdim, rowbase, Gn, cid, ...) do { pg8::Gemm g{(const bf16_t*)(a.ws + (Aoff)) + (size_t)(rowbase) * (Kdim), (const bf16_t*)(a.ws + (Woff)), (Mrows), 1024, (Kdim)}; \
;         pg8::StaticOrder S; S.init((Mrows), 1024, (Gn), (cid)); EPI E{__VA_ARGS__, (rowbase)}; pg8::gemm_phase<EPI, pg8::StaticOrder, false, true>(lds, g, S, E); } while (0)
; __global__ void __launch_bounds__(512) fwd_kernel(Args a) {
;     ...
;         if (G >= 32 && bx < 16) GEMM_N1024(EpiN1024<2>, A_HID, WS_WDN, MS, DFF, MP, 16, bx, (bf16_t*)(a.ws + A_GA), nullptr, (float*)(a.ws + WS_RSS2));
.Lsk_go:
	buffer_inv sc1
	s_waitcnt vmcnt(0)
	global_load_dwordx4 v[180:183], v160, s[98:99]
	s_add_u32 s98, s98, 0x400
	s_addc_u32 s99, s99, 0
	global_load_dwordx4 v[184:187], v160, s[98:99]
	s_add_u32 s98, s98, 0x400
	s_addc_u32 s99, s99, 0
	global_load_dwordx4 v[188:191], v160, s[98:99]
	s_add_u32 s98, s98, 0x400
	s_addc_u32 s99, s99, 0
	global_load_dwordx4 v[192:195], v160, s[98:99]
	s_add_u32 s98, s98, 0x400
	s_addc_u32 s99, s99, 0
	global_load_dwordx4 v[196:199], v160, s[98:99]
	s_add_u32 s98, s98, 0x400
	s_addc_u32 s99, s99, 0
	global_load_dwordx4 v[200:203], v160, s[98:99]
	s_add_u32 s98, s98, 0x400
	s_addc_u32 s99, s99, 0
	global_load_dwordx4 v[204:207], v160, s[98:99]
	s_add_u32 s98, s98, 0x400
	s_addc_u32 s99, s99, 0
	global_load_dwordx4 v[208:211], v160, s[98:99]
	s_add_u32 s98, s98, 0x400
	s_addc_u32 s99, s99, 0
	global_load_dwordx4 v[212:215], v160, s[98:99]
	s_add_u32 s98, s98, 0x400
	s_addc_u32 s99, s99, 0
	global_load_dwordx4 v[216:219], v160, s[98:99]
	s_add_u32 s98, s98, 0x400
	s_addc_u32 s99, s99, 0
	global_load_dwordx4 v[220:223], v160, s[98:99]
	s_add_u32 s98, s98, 0x400
	s_addc_u32 s99, s99, 0
	global_load_dwordx4 v[224:227], v160, s[98:99]
	s_add_u32 s98, s98, 0x400
	s_addc_u32 s99, s99, 0
	global_load_dwordx4 v[228:231], v160, s[98:99]
	s_add_u32 s98, s98, 0x400
	s_addc_u32 s99, s99, 0
	global_load_dwordx4 v[232:235], v160, s[98:99]
	s_add_u32 s98, s98, 0x400
	s_addc_u32 s99, s99, 0
	global_load_dwordx4 v[236:239], v160, s[98:99]
	s_add_u32 s98, s98, 0x400
	s_addc_u32 s99, s99, 0
	global_load_dwordx4 v[240:243], v160, s[98:99]
	s_add_u32 s98, s98, 0x400
	s_addc_u32 s99, s99, 0
	s_waitcnt vmcnt(8)
	v_add_f32_e32 v0, v0, v180
	v_add_f32_e32 v1, v1, v181
	v_add_f32_e32 v2, v2, v182
	v_add_f32_e32 v3, v3, v183
	v_add_f32_e32 v4, v4, v184
	v_add_f32_e32 v5, v5, v185
	v_add_f32_e32 v6, v6, v186
	v_add_f32_e32 v7, v7, v187
	v_add_f32_e32 v8, v8, v188
	v_add_f32_e32 v9, v9, v189
	v_add_f32_e32 v10, v10, v190
	v_add_f32_e32 v11, v11, v191
	v_add_f32_e32 v12, v12, v192
	v_add_f32_e32 v13, v13, v193
	v_add_f32_e32 v14, v14, v194
	v_add_f32_e32 v15, v15, v195
	v_add_f32_e32 v16, v16, v196
	v_add_f32_e32 v17, v17, v197
	v_add_f32_e32 v18, v18, v198
	v_add_f32_e32 v19, v19, v199
	v_add_f32_e32 v20, v20, v200
	v_add_f32_e32 v21, v21, v201
	v_add_f32_e32 v22, v22, v202
	v_add_f32_e32 v23, v23, v203
	v_add_f32_e32 v24, v24, v204
	v_add_f32_e32 v25, v25, v205
	v_add_f32_e32 v26, v26, v206
	v_add_f32_e32 v27, v27, v207
	v_add_f32_e32 v28, v28, v208
	v_add_f32_e32 v29, v29, v209
	v_add_f32_e32 v30, v30, v210
	v_add_f32_e32 v31, v31, v211
	global_load_dwordx4 v[180:183], v160, s[98:99]
	s_add_u32 s98, s98, 0x400
	s_addc_u32 s99, s99, 0
	global_load_dwordx4 v[184:187], v160, s[98:99]
	s_add_u32 s98, s98, 0x400
	s_addc_u32 s99, s99, 0
	global_load_dwordx4 v[188:191], v160, s[98:99]
	s_add_u32 s98, s98, 0x400
	s_addc_u32 s99, s99, 0
	global_load_dwordx4 v[192:195], v160, s[98:99]
	s_add_u32 s98, s98, 0x400
	s_addc_u32 s99, s99, 0
	global_load_dwordx4 v[196:199], v160, s[98:99]
	s_add_u32 s98, s98, 0x400
	s_addc_u32 s99, s99, 0
	global_load_dwordx4 v[200:203], v160, s[98:99]
	s_add_u32 s98, s98, 0x400
	s_addc_u32 s99, s99, 0
	global_load_dwordx4 v[204:207], v160, s[98:99]
	s_add_u32 s98, s98, 0x400
	s_addc_u32 s99, s99, 0
	global_load_dwordx4 v[208:211], v160, s[98:99]
	s_add_u32 s98, s98, 0x400
	s_addc_u32 s99, s99, 0
	s_waitcnt vmcnt(8)
	v_add_f32_e32 v32, v32, v212
	v_add_f32_e32 v33, v33, v213
	v_add_f32_e32 v34, v34, v214
	v_add_f32_e32 v35, v35, v215
	v_add_f32_e32 v36, v36, v216
	v_add_f32_e32 v37, v37, v217
	v_add_f32_e32 v38, v38, v218
	v_add_f32_e32 v39, v39, v219
	v_add_f32_e32 v40, v40, v220
	v_add_f32_e32 v41, v41, v221
	v_add_f32_e32 v42, v42, v222
	v_add_f32_e32 v43, v43, v223
	v_add_f32_e32 v44, v44, v224
	v_add_f32_e32 v45, v45, v225
	v_add_f32_e32 v46, v46, v226
	v_add_f32_e32 v47, v47, v227
	v_add_f32_e32 v48, v48, v228
	v_add_f32_e32 v49, v49, v229
	v_add_f32_e32 v50, v50, v230
	v_add_f32_e32 v51, v51, v231
	v_add_f32_e32 v52, v52, v232
	v_add_f32_e32 v53, v53, v233
	v_add_f32_e32 v54, v54, v234
	v_add_f32_e32 v55, v55, v235
	v_add_f32_e32 v56, v56, v236
	v_add_f32_e32 v57, v57, v237
	v_add_f32_e32 v58, v58, v238
	v_add_f32_e32 v59, v59, v239
	v_add_f32_e32 v60, v60, v240
	v_add_f32_e32 v61, v61, v241
	v_add_f32_e32 v62, v62, v242
	v_add_f32_e32 v63, v63, v243
	global_load_dwordx4 v[212:215], v160, s[98:99]
	s_add_u32 s98, s98, 0x400
	s_addc_u32 s99, s99, 0
	global_load_dwordx4 v[216:219], v160, s[98:99]
	s_add_u32 s98, s98, 0x400
	s_addc_u32 s99, s99, 0
	global_load_dwordx4 v[220:223], v160, s[98:99]
	s_add_u32 s98, s98, 0x400
	s_addc_u32 s99, s99, 0
	global_load_dwordx4 v[224:227], v160, s[98:99]
	s_add_u32 s98, s98, 0x400
	s_addc_u32 s99, s99, 0
	global_load_dwordx4 v[228:231], v160, s[98:99]
	s_add_u32 s98, s98, 0x400
	s_addc_u32 s99, s99, 0
	global_load_dwordx4 v[232:235], v160, s[98:99]
	s_add_u32 s98, s98, 0x400
	s_addc_u32 s99, s99, 0
	global_load_dwordx4 v[236:239], v160, s[98:99]
	s_add_u32 s98, s98, 0x400
	s_addc_u32 s99, s99, 0
	global_load_dwordx4 v[240:243], v160, s[98:99]
	s_add_u32 s98, s98, 0x400
	s_addc_u32 s99, s99, 0
	s_waitcnt vmcnt(8)
; __device__ __forceinline__ u32x2 pk4(f32x4 v) { u32x2 w; w.x = cvt_pk_bf16(v[0], v[1]); w.y = cvt_pk_bf16(v[2], v[3]); return w; }
; __device__ __forceinline__ f32x4 up4(u32x2 w) { return (f32x4){bf_lo(w.x), bf_hi(w.x), bf_lo(w.y), bf_hi(w.y)}; }
; #define GEMM_N1024(EPI, Aoff, Woff, Mrows, Kdim, rowbase, Gn, cid, ...) do { pg8::Gemm g{(const bf16_t*)(a.ws + (Aoff)) + (size_t)(rowbase) * (Kdim), (const bf16_t*)(a.ws + (Woff)), (Mrows), 1024, (Kdim)}; \
;         pg8::StaticOrder S; S.init((Mrows), 1024, (Gn), (cid)); EPI E{__VA_ARGS__, (rowbase)}; pg8::gemm_phase<EPI, pg8::StaticOrder, false, true>(lds, g, S, E); } while (0)
;     __device__ __forceinline__ void operator()(const AccT& acc, const pg8::Unit& u, int wr, int wc, int fr, int fq) const {
;     ...
;             for (int m = 0; m < 4; ++m) { const int row = row0 + ai * 128 + m * 16; float ss = 0.f;
; #pragma unroll
;                 for (int bj = 0; bj < 2; ++bj)
; #pragma unroll
;                     for (int n = 0; n < 2; ++n) { f32x4 v = acc[ai][bj][m][n]; const size_t idx = (size_t)row * 1024 + col0 + bj * 128 + n * 16;
;                         if (MODE == 0) v = v * up4(*(const u32x2*)(io + idx));
;                         else if (MODE == 1) v = up4(*(const u32x2*)(io + idx)) + up4(*(const u32x2*)(g2 + idx)) * v;
;                         else ss += (v[0] * v[0] + v[1] * v[1]) + (v[2] * v[2] + v[3] * v[3]);
;                         if (!DRYE || v[0] == 123.456f) *(u32x2*)(io + idx) = pk4(v); }
;                 if (MODE == 2 && !DRYE) { ss += __shfl_xor(ss, 16); ss += __shfl_xor(ss, 32); if (fq == 0) atomicAdd(rowss + row, ss); } }
; __global__ void __launch_bounds__(512) fwd_kernel(Args a) {
;     ...
;         if (G >= 32 && bx < 16) GEMM_N1024(EpiN1024<2>, A_HID, WS_WDN, MS, DFF, MP, 16, bx, (bf16_t*)(a.ws + A_GA), nullptr, (float*)(a.ws + WS_RSS2));
	v_add_f32_e32 v64, v64, v180
	v_add_f32_e32 v65, v65, v181
	v_add_f32_e32 v66, v66, v182
	v_add_f32_e32 v67, v67, v183
	v_add_f32_e32 v68, v68, v184
	v_add_f32_e32 v69, v69, v185
	v_add_f32_e32 v70, v70, v186
	v_add_f32_e32 v71, v71, v187
	v_add_f32_e32 v72, v72, v188
	v_add_f32_e32 v73, v73, v189
	v_add_f32_e32 v74, v74, v190
	v_add_f32_e32 v75, v75, v191
	v_add_f32_e32 v76, v76, v192
	v_add_f32_e32 v77, v77, v193
	v_add_f32_e32 v78, v78, v194
	v_add_f32_e32 v79, v79, v195
	v_add_f32_e32 v80, v80, v196
	v_add_f32_e32 v81, v81, v197
	v_add_f32_e32 v82, v82, v198
	v_add_f32_e32 v83, v83, v199
	v_add_f32_e32 v84, v84, v200
	v_add_f32_e32 v85, v85, v201
	v_add_f32_e32 v86, v86, v202
	v_add_f32_e32 v87, v87, v203
	v_add_f32_e32 v88, v88, v204
	v_add_f32_e32 v89, v89, v205
	v_add_f32_e32 v90, v90, v206
	v_add_f32_e32 v91, v91, v207
	v_add_f32_e32 v92, v92, v208
	v_add_f32_e32 v93, v93, v209
	v_add_f32_e32 v94, v94, v210
	v_add_f32_e32 v95, v95, v211
	s_waitcnt vmcnt(0)
	v_add_f32_e32 v96, v96, v212
	v_add_f32_e32 v97, v97, v213
	v_add_f32_e32 v98, v98, v214
	v_add_f32_e32 v99, v99, v215
	v_add_f32_e32 v100, v100, v216
	v_add_f32_e32 v101, v101, v217
	v_add_f32_e32 v102, v102, v218
	v_add_f32_e32 v103, v103, v219
	v_add_f32_e32 v104, v104, v220
	v_add_f32_e32 v105, v105, v221
	v_add_f32_e32 v106, v106, v222
	v_add_f32_e32 v107, v107, v223
	v_add_f32_e32 v108, v108, v224
	v_add_f32_e32 v109, v109, v225
	v_add_f32_e32 v110, v110, v226
	v_add_f32_e32 v111, v111, v227
	v_add_f32_e32 v112, v112, v228
	v_add_f32_e32 v113, v113, v229
	v_add_f32_e32 v114, v114, v230
	v_add_f32_e32 v115, v115, v231
	v_add_f32_e32 v116, v116, v232
	v_add_f32_e32 v117, v117, v233
	v_add_f32_e32 v118, v118, v234
	v_add_f32_e32 v119, v119, v235
	v_add_f32_e32 v120, v120, v236
	v_add_f32_e32 v121, v121, v237
	v_add_f32_e32 v122, v122, v238
	v_add_f32_e32 v123, v123, v239
	v_add_f32_e32 v124, v124, v240
	v_add_f32_e32 v125, v125, v241
	v_add_f32_e32 v126, v126, v242
	v_add_f32_e32 v127, v127, v243
	v_and_b32_e32 v147, 64, v146
	v_xor_b32_e32 v139, 16, v146
	v_add_u32_e32 v147, 64, v147
	v_cmp_lt_i32_e32 vcc, v139, v147
	v_lshl_add_u32 v149, s47, 8, v140
	v_add_u32_e32 v138, 0x4000, v149
	v_cndmask_b32_e32 v139, v146, v139, vcc
	v_lshlrev_b32_e32 v148, 2, v139
	v_xor_b32_e32 v139, 32, v146
	v_cmp_lt_i32_e32 vcc, v139, v147
	v_lshl_or_b32 v136, s48, 8, v142
	v_mul_f32_e32 v152, v125, v125
	v_cndmask_b32_e32 v139, v146, v139, vcc
	v_lshlrev_b32_e32 v147, 2, v139
	v_ashrrev_i32_e32 v139, 31, v138
	v_lshlrev_b64 v[150:151], 11, v[138:139]
	v_mul_f32_e32 v153, v127, v127
	v_ashrrev_i32_e32 v137, 31, v136
	v_fmac_f32_e32 v152, v124, v124
	v_fmac_f32_e32 v153, v126, v126
	v_cvt_pk_bf16_f32 v124, v124, v125
	v_cvt_pk_bf16_f32 v125, v126, v127
	v_lshl_add_u64 v[126:127], s[10:11], 0, v[150:151]
	v_lshl_add_u64 v[126:127], v[136:137], 1, v[126:127]
	global_store_dwordx2 v[126:127], v[124:125], off
	v_mul_f32_e32 v124, v121, v121
	v_mul_f32_e32 v125, v123, v123
	v_fmac_f32_e32 v124, v120, v120
	v_fmac_f32_e32 v125, v122, v122
	v_add_f32_e32 v124, v124, v125
	v_cvt_pk_bf16_f32 v120, v120, v121
	v_mul_f32_e32 v121, v117, v117
	v_mul_f32_e32 v125, v119, v119
	v_add_f32_e32 v152, v152, v153
	v_fmac_f32_e32 v121, v116, v116
	v_fmac_f32_e32 v125, v118, v118
	v_add_f32_e32 v124, v152, v124
	v_add_f32_e32 v121, v121, v125
	v_add_f32_e32 v121, v124, v121
	v_mul_f32_e32 v124, v109, v109
	v_mul_f32_e32 v125, v111, v111
	v_fmac_f32_e32 v124, v108, v108
	v_fmac_f32_e32 v125, v110, v110
	v_add_f32_e32 v124, v124, v125
	v_add_f32_e32 v124, v121, v124
	v_mov_b32_e32 v125, v124
	s_nop 1
	v_permlane16_swap_b32_e32 v124, v125
	v_cvt_pk_bf16_f32 v121, v122, v123
	global_store_dwordx2 v[126:127], v[120:121], off offset:32
	v_cvt_pk_bf16_f32 v120, v116, v117
	v_cvt_pk_bf16_f32 v121, v118, v119
	s_waitcnt lgkmcnt(0)
	v_add_f32_e32 v116, v124, v125
	v_mov_b32_e32 v117, v116
	s_nop 1
	v_permlane32_swap_b32_e32 v116, v117
	v_cvt_pk_bf16_f32 v108, v108, v109
	v_cvt_pk_bf16_f32 v109, v110, v111
	global_store_dwordx2 v[126:127], v[120:121], off offset:256
	global_store_dwordx2 v[126:127], v[108:109], off offset:288
	s_and_saveexec_b64 s[22:23], s[0:1]
	s_cbranch_execz .LBB0_1443
	v_lshl_add_u64 v[108:109], v[138:139], 2, s[14:15]
	s_waitcnt lgkmcnt(0)
	v_add_f32_e32 v110, v116, v117
	global_atomic_add_f32 v[108:109], v110, off
.LBB0_1443:
	s_or_b64 exec, exec, s[22:23]
	v_add_u32_e32 v108, 0x4010, v149
	v_ashrrev_i32_e32 v109, 31, v108
	v_lshlrev_b64 v[110:111], 11, v[108:109]
	v_mul_f32_e32 v116, v113, v113
	v_lshl_add_u64 v[110:111], s[10:11], 0, v[110:111]
	v_fmac_f32_e32 v116, v112, v112
	v_cvt_pk_bf16_f32 v112, v112, v113
	v_cvt_pk_bf16_f32 v113, v114, v115
	v_lshl_add_u64 v[110:111], v[136:137], 1, v[110:111]
	global_store_dwordx2 v[110:111], v[112:113], off
	v_mul_f32_e32 v112, v105, v105
	v_mul_f32_e32 v113, v107, v107
	s_waitcnt lgkmcnt(0)
	v_mul_f32_e32 v117, v115, v115
	v_fmac_f32_e32 v112, v104, v104
	v_fmac_f32_e32 v113, v106, v106
	v_fmac_f32_e32 v117, v114, v114
	v_add_f32_e32 v112, v112, v113
	v_cvt_pk_bf16_f32 v104, v104, v105
	v_mul_f32_e32 v105, v101, v101
	v_mul_f32_e32 v113, v103, v103
	v_add_f32_e32 v116, v116, v117
	v_fmac_f32_e32 v105, v100, v100
	v_fmac_f32_e32 v113, v102, v102
	v_add_f32_e32 v112, v116, v112
	v_add_f32_e32 v105, v105, v113
	v_add_f32_e32 v105, v112, v105
	v_mul_f32_e32 v112, v93, v93
	v_mul_f32_e32 v113, v95, v95
	v_fmac_f32_e32 v112, v92, v92
	v_fmac_f32_e32 v113, v94, v94
	v_add_f32_e32 v112, v112, v113
	v_add_f32_e32 v112, v105, v112
	v_mov_b32_e32 v113, v112
	s_nop 1
	v_permlane16_swap_b32_e32 v112, v113
	v_cvt_pk_bf16_f32 v105, v106, v107
	global_store_dwordx2 v[110:111], v[104:105], off offset:32
	v_cvt_pk_bf16_f32 v104, v100, v101
	v_cvt_pk_bf16_f32 v105, v102, v103
	s_waitcnt lgkmcnt(0)
	v_add_f32_e32 v100, v112, v113
	v_mov_b32_e32 v101, v100
	s_nop 1
	v_permlane32_swap_b32_e32 v100, v101
	v_cvt_pk_bf16_f32 v92, v92, v93
	v_cvt_pk_bf16_f32 v93, v94, v95
	global_store_dwordx2 v[110:111], v[104:105], off offset:256
	global_store_dwordx2 v[110:111], v[92:93], off offset:288
	s_and_saveexec_b64 s[22:23], s[0:1]
	s_cbranch_execz .LBB0_1445
	v_lshl_add_u64 v[92:93], v[108:109], 2, s[14:15]
	s_waitcnt lgkmcnt(0)
	v_add_f32_e32 v94, v100, v101
	global_atomic_add_f32 v[92:93], v94, off
; __device__ __forceinline__ u32x2 pk4(f32x4 v) { u32x2 w; w.x = cvt_pk_bf16(v[0], v[1]); w.y = cvt_pk_bf16(v[2], v[3]); return w; }
; __device__ __forceinline__ f32x4 up4(u32x2 w) { return (f32x4){bf_lo(w.x), bf_hi(w.x), bf_lo(w.y), bf_hi(w.y)}; }
;     __device__ __forceinline__ void operator()(const AccT& acc, const pg8::Unit& u, int wr, int wc, int fr, int fq) const {
;     ...
;             for (int m = 0; m < 4; ++m) { const int row = row0 + ai * 128 + m * 16; float ss = 0.f;
; #pragma unroll
;                 for (int bj = 0; bj < 2; ++bj)
; #pragma unroll
;                     for (int n = 0; n < 2; ++n) { f32x4 v = acc[ai][bj][m][n]; const size_t idx = (size_t)row * 1024 + col0 + bj * 128 + n * 16;
;                         if (MODE == 0) v = v * up4(*(const u32x2*)(io + idx));
;                         else if (MODE == 1) v = up4(*(const u32x2*)(io + idx)) + up4(*(const u32x2*)(g2 + idx)) * v;
;                         else ss += (v[0] * v[0] + v[1] * v[1]) + (v[2] * v[2] + v[3] * v[3]);
;                         if (!DRYE || v[0] == 123.456f) *(u32x2*)(io + idx) = pk4(v); }
;                 if (MODE == 2 && !DRYE) { ss += __shfl_xor(ss, 16); ss += __shfl_xor(ss, 32); if (fq == 0) atomicAdd(rowss + row, ss); } }
.LBB0_1445:
	s_or_b64 exec, exec, s[22:23]
	v_add_u32_e32 v92, 0x4020, v149
	v_ashrrev_i32_e32 v93, 31, v92
	v_lshlrev_b64 v[94:95], 11, v[92:93]
	v_mul_f32_e32 v100, v97, v97
	v_lshl_add_u64 v[94:95], s[10:11], 0, v[94:95]
	v_fmac_f32_e32 v100, v96, v96
	v_cvt_pk_bf16_f32 v96, v96, v97
	v_cvt_pk_bf16_f32 v97, v98, v99
	v_lshl_add_u64 v[94:95], v[136:137], 1, v[94:95]
	global_store_dwordx2 v[94:95], v[96:97], off
	v_mul_f32_e32 v96, v89, v89
	v_mul_f32_e32 v97, v91, v91
	s_waitcnt lgkmcnt(0)
	v_mul_f32_e32 v101, v99, v99
	v_fmac_f32_e32 v96, v88, v88
	v_fmac_f32_e32 v97, v90, v90
	v_fmac_f32_e32 v101, v98, v98
	v_add_f32_e32 v96, v96, v97
	v_cvt_pk_bf16_f32 v88, v88, v89
	v_mul_f32_e32 v89, v85, v85
	v_mul_f32_e32 v97, v87, v87
	v_add_f32_e32 v100, v100, v101
	v_fmac_f32_e32 v89, v84, v84
	v_fmac_f32_e32 v97, v86, v86
	v_add_f32_e32 v96, v100, v96
	v_add_f32_e32 v89, v89, v97
	v_add_f32_e32 v89, v96, v89
	v_mul_f32_e32 v96, v77, v77
	v_mul_f32_e32 v97, v79, v79
	v_fmac_f32_e32 v96, v76, v76
	v_fmac_f32_e32 v97, v78, v78
	v_add_f32_e32 v96, v96, v97
	v_add_f32_e32 v96, v89, v96
	v_mov_b32_e32 v97, v96
	s_nop 1
	v_permlane16_swap_b32_e32 v96, v97
	v_cvt_pk_bf16_f32 v89, v90, v91
	global_store_dwordx2 v[94:95], v[88:89], off offset:32
	v_cvt_pk_bf16_f32 v88, v84, v85
	v_cvt_pk_bf16_f32 v89, v86, v87
	s_waitcnt lgkmcnt(0)
	v_add_f32_e32 v84, v96, v97
	v_mov_b32_e32 v85, v84
	s_nop 1
	v_permlane32_swap_b32_e32 v84, v85
	v_cvt_pk_bf16_f32 v76, v76, v77
	v_cvt_pk_bf16_f32 v77, v78, v79
	global_store_dwordx2 v[94:95], v[88:89], off offset:256
	global_store_dwordx2 v[94:95], v[76:77], off offset:288
	s_and_saveexec_b64 s[22:23], s[0:1]
	s_cbranch_execz .LBB0_1447
	v_lshl_add_u64 v[76:77], v[92:93], 2, s[14:15]
	s_waitcnt lgkmcnt(0)
	v_add_f32_e32 v78, v84, v85
	global_atomic_add_f32 v[76:77], v78, off
.LBB0_1447:
	s_or_b64 exec, exec, s[22:23]
	v_add_u32_e32 v76, 0x4030, v149
	v_ashrrev_i32_e32 v77, 31, v76
	v_lshlrev_b64 v[78:79], 11, v[76:77]
	v_mul_f32_e32 v84, v81, v81
	v_lshl_add_u64 v[78:79], s[10:11], 0, v[78:79]
	v_fmac_f32_e32 v84, v80, v80
	v_cvt_pk_bf16_f32 v80, v80, v81
	v_cvt_pk_bf16_f32 v81, v82, v83
	v_lshl_add_u64 v[78:79], v[136:137], 1, v[78:79]
	global_store_dwordx2 v[78:79], v[80:81], off
	v_mul_f32_e32 v80, v73, v73
	v_mul_f32_e32 v81, v75, v75
	s_waitcnt lgkmcnt(0)
	v_mul_f32_e32 v85, v83, v83
	v_fmac_f32_e32 v80, v72, v72
	v_fmac_f32_e32 v81, v74, v74
	v_fmac_f32_e32 v85, v82, v82
	v_add_f32_e32 v80, v80, v81
	v_cvt_pk_bf16_f32 v72, v72, v73
	v_mul_f32_e32 v73, v69, v69
	v_mul_f32_e32 v81, v71, v71
	v_add_f32_e32 v84, v84, v85
	v_fmac_f32_e32 v73, v68, v68
	v_fmac_f32_e32 v81, v70, v70
	v_add_f32_e32 v80, v84, v80
	v_add_f32_e32 v73, v73, v81
	v_add_f32_e32 v73, v80, v73
	v_mul_f32_e32 v80, v65, v65
	v_mul_f32_e32 v81, v67, v67
	v_fmac_f32_e32 v80, v64, v64
	v_fmac_f32_e32 v81, v66, v66
	v_add_f32_e32 v80, v80, v81
	v_add_f32_e32 v80, v73, v80
	v_mov_b32_e32 v81, v80
	s_nop 1
	v_permlane16_swap_b32_e32 v80, v81
	v_cvt_pk_bf16_f32 v73, v74, v75
	global_store_dwordx2 v[78:79], v[72:73], off offset:32
	v_cvt_pk_bf16_f32 v72, v68, v69
	v_cvt_pk_bf16_f32 v73, v70, v71
	s_waitcnt lgkmcnt(0)
	v_add_f32_e32 v68, v80, v81
	v_mov_b32_e32 v69, v68
	s_nop 1
	v_permlane32_swap_b32_e32 v68, v69
	v_cvt_pk_bf16_f32 v64, v64, v65
	v_cvt_pk_bf16_f32 v65, v66, v67
	global_store_dwordx2 v[78:79], v[72:73], off offset:256
	global_store_dwordx2 v[78:79], v[64:65], off offset:288
	s_and_saveexec_b64 s[22:23], s[0:1]
	s_cbranch_execz .LBB0_1449
	v_lshl_add_u64 v[64:65], v[76:77], 2, s[14:15]
	s_waitcnt lgkmcnt(0)
	v_add_f32_e32 v66, v68, v69
	global_atomic_add_f32 v[64:65], v66, off
.LBB0_1449:
	s_or_b64 exec, exec, s[22:23]
	v_add_u32_e32 v64, 0x4080, v149
	v_ashrrev_i32_e32 v65, 31, v64
	v_lshlrev_b64 v[66:67], 11, v[64:65]
	v_mul_f32_e32 v68, v61, v61
	s_waitcnt lgkmcnt(0)
	v_mul_f32_e32 v69, v63, v63
	v_fmac_f32_e32 v68, v60, v60
	v_fmac_f32_e32 v69, v62, v62
	v_cvt_pk_bf16_f32 v60, v60, v61
	v_cvt_pk_bf16_f32 v61, v62, v63
	v_lshl_add_u64 v[62:63], s[10:11], 0, v[66:67]
	v_lshl_add_u64 v[62:63], v[136:137], 1, v[62:63]
	global_store_dwordx2 v[62:63], v[60:61], off
	v_mul_f32_e32 v60, v57, v57
	v_mul_f32_e32 v61, v59, v59
	v_fmac_f32_e32 v60, v56, v56
	v_fmac_f32_e32 v61, v58, v58
	v_add_f32_e32 v60, v60, v61
	v_cvt_pk_bf16_f32 v56, v56, v57
	v_mul_f32_e32 v57, v53, v53
	v_mul_f32_e32 v61, v55, v55
	v_add_f32_e32 v68, v68, v69
	v_fmac_f32_e32 v57, v52, v52
	v_fmac_f32_e32 v61, v54, v54
	v_add_f32_e32 v60, v68, v60
	v_add_f32_e32 v57, v57, v61
	v_add_f32_e32 v57, v60, v57
	v_mul_f32_e32 v60, v45, v45
	v_mul_f32_e32 v61, v47, v47
	v_fmac_f32_e32 v60, v44, v44
	v_fmac_f32_e32 v61, v46, v46
	v_add_f32_e32 v60, v60, v61
	v_add_f32_e32 v60, v57, v60
	v_mov_b32_e32 v61, v60
	s_nop 1
	v_permlane16_swap_b32_e32 v60, v61
	v_cvt_pk_bf16_f32 v57, v58, v59
	global_store_dwordx2 v[62:63], v[56:57], off offset:32
	v_cvt_pk_bf16_f32 v56, v52, v53
	v_cvt_pk_bf16_f32 v57, v54, v55
	s_waitcnt lgkmcnt(0)
	v_add_f32_e32 v52, v60, v61
	v_mov_b32_e32 v53, v52
	s_nop 1
	v_permlane32_swap_b32_e32 v52, v53
	v_cvt_pk_bf16_f32 v44, v44, v45
	v_cvt_pk_bf16_f32 v45, v46, v47
	global_store_dwordx2 v[62:63], v[56:57], off offset:256
	global_store_dwordx2 v[62:63], v[44:45], off offset:288
	s_and_saveexec_b64 s[22:23], s[0:1]
	s_cbranch_execz .LBB0_1451
	v_lshl_add_u64 v[44:45], v[64:65], 2, s[14:15]
	s_waitcnt lgkmcnt(0)
	v_add_f32_e32 v46, v52, v53
	global_atomic_add_f32 v[44:45], v46, off
; __device__ __forceinline__ u32x2 pk4(f32x4 v) { u32x2 w; w.x = cvt_pk_bf16(v[0], v[1]); w.y = cvt_pk_bf16(v[2], v[3]); return w; }
; __device__ __forceinline__ f32x4 up4(u32x2 w) { return (f32x4){bf_lo(w.x), bf_hi(w.x), bf_lo(w.y), bf_hi(w.y)}; }
;     __device__ __forceinline__ void operator()(const AccT& acc, const pg8::Unit& u, int wr, int wc, int fr, int fq) const {
;     ...
;             for (int m = 0; m < 4; ++m) { const int row = row0 + ai * 128 + m * 16; float ss = 0.f;
; #pragma unroll
;                 for (int bj = 0; bj < 2; ++bj)
; #pragma unroll
;                     for (int n = 0; n < 2; ++n) { f32x4 v = acc[ai][bj][m][n]; const size_t idx = (size_t)row * 1024 + col0 + bj * 128 + n * 16;
;                         if (MODE == 0) v = v * up4(*(const u32x2*)(io + idx));
;                         else if (MODE == 1) v = up4(*(const u32x2*)(io + idx)) + up4(*(const u32x2*)(g2 + idx)) * v;
;                         else ss += (v[0] * v[0] + v[1] * v[1]) + (v[2] * v[2] + v[3] * v[3]);
;                         if (!DRYE || v[0] == 123.456f) *(u32x2*)(io + idx) = pk4(v); }
;                 if (MODE == 2 && !DRYE) { ss += __shfl_xor(ss, 16); ss += __shfl_xor(ss, 32); if (fq == 0) atomicAdd(rowss + row, ss); } }
.LBB0_1451:
	s_or_b64 exec, exec, s[22:23]
	v_add_u32_e32 v44, 0x4090, v149
	v_ashrrev_i32_e32 v45, 31, v44
	v_lshlrev_b64 v[46:47], 11, v[44:45]
	v_mul_f32_e32 v52, v49, v49
	v_lshl_add_u64 v[46:47], s[10:11], 0, v[46:47]
	v_fmac_f32_e32 v52, v48, v48
	v_cvt_pk_bf16_f32 v48, v48, v49
	v_cvt_pk_bf16_f32 v49, v50, v51
	v_lshl_add_u64 v[46:47], v[136:137], 1, v[46:47]
	global_store_dwordx2 v[46:47], v[48:49], off
	v_mul_f32_e32 v48, v41, v41
	v_mul_f32_e32 v49, v43, v43
	s_waitcnt lgkmcnt(0)
	v_mul_f32_e32 v53, v51, v51
	v_fmac_f32_e32 v48, v40, v40
	v_fmac_f32_e32 v49, v42, v42
	v_fmac_f32_e32 v53, v50, v50
	v_add_f32_e32 v48, v48, v49
	v_cvt_pk_bf16_f32 v40, v40, v41
	v_mul_f32_e32 v41, v37, v37
	v_mul_f32_e32 v49, v39, v39
	v_add_f32_e32 v52, v52, v53
	v_fmac_f32_e32 v41, v36, v36
	v_fmac_f32_e32 v49, v38, v38
	v_add_f32_e32 v48, v52, v48
	v_add_f32_e32 v41, v41, v49
	v_add_f32_e32 v41, v48, v41
	v_mul_f32_e32 v48, v29, v29
	v_mul_f32_e32 v49, v31, v31
	v_fmac_f32_e32 v48, v28, v28
	v_fmac_f32_e32 v49, v30, v30
	v_add_f32_e32 v48, v48, v49
	v_add_f32_e32 v48, v41, v48
	v_mov_b32_e32 v49, v48
	s_nop 1
	v_permlane16_swap_b32_e32 v48, v49
	v_cvt_pk_bf16_f32 v41, v42, v43
	global_store_dwordx2 v[46:47], v[40:41], off offset:32
	v_cvt_pk_bf16_f32 v40, v36, v37
	v_cvt_pk_bf16_f32 v41, v38, v39
	s_waitcnt lgkmcnt(0)
	v_add_f32_e32 v36, v48, v49
	v_mov_b32_e32 v37, v36
	s_nop 1
	v_permlane32_swap_b32_e32 v36, v37
	v_cvt_pk_bf16_f32 v28, v28, v29
	v_cvt_pk_bf16_f32 v29, v30, v31
	global_store_dwordx2 v[46:47], v[40:41], off offset:256
	global_store_dwordx2 v[46:47], v[28:29], off offset:288
	s_and_saveexec_b64 s[22:23], s[0:1]
	s_cbranch_execz .LBB0_1453
	v_lshl_add_u64 v[28:29], v[44:45], 2, s[14:15]
	s_waitcnt lgkmcnt(0)
	v_add_f32_e32 v30, v36, v37
	global_atomic_add_f32 v[28:29], v30, off
.LBB0_1453:
	s_or_b64 exec, exec, s[22:23]
	v_add_u32_e32 v28, 0x40a0, v149
	v_ashrrev_i32_e32 v29, 31, v28
	v_lshlrev_b64 v[30:31], 11, v[28:29]
	v_mul_f32_e32 v36, v33, v33
	v_lshl_add_u64 v[30:31], s[10:11], 0, v[30:31]
	v_fmac_f32_e32 v36, v32, v32
	v_cvt_pk_bf16_f32 v32, v32, v33
	v_cvt_pk_bf16_f32 v33, v34, v35
	v_lshl_add_u64 v[30:31], v[136:137], 1, v[30:31]
	global_store_dwordx2 v[30:31], v[32:33], off
	v_mul_f32_e32 v32, v25, v25
	v_mul_f32_e32 v33, v27, v27
	s_waitcnt lgkmcnt(0)
	v_mul_f32_e32 v37, v35, v35
	v_fmac_f32_e32 v32, v24, v24
	v_fmac_f32_e32 v33, v26, v26
	v_fmac_f32_e32 v37, v34, v34
	v_add_f32_e32 v32, v32, v33
	v_cvt_pk_bf16_f32 v24, v24, v25
	v_mul_f32_e32 v25, v21, v21
	v_mul_f32_e32 v33, v23, v23
	v_add_f32_e32 v36, v36, v37
	v_fmac_f32_e32 v25, v20, v20
	v_fmac_f32_e32 v33, v22, v22
	v_add_f32_e32 v32, v36, v32
	v_add_f32_e32 v25, v25, v33
	v_add_f32_e32 v25, v32, v25
	v_mul_f32_e32 v32, v13, v13
	v_mul_f32_e32 v33, v15, v15
	v_fmac_f32_e32 v32, v12, v12
	v_fmac_f32_e32 v33, v14, v14
	v_add_f32_e32 v32, v32, v33
	v_add_f32_e32 v32, v25, v32
	v_mov_b32_e32 v33, v32
	s_nop 1
	v_permlane16_swap_b32_e32 v32, v33
	v_cvt_pk_bf16_f32 v25, v26, v27
	global_store_dwordx2 v[30:31], v[24:25], off offset:32
	v_cvt_pk_bf16_f32 v24, v20, v21
	v_cvt_pk_bf16_f32 v25, v22, v23
	s_waitcnt lgkmcnt(0)
	v_add_f32_e32 v20, v32, v33
	v_mov_b32_e32 v21, v20
	s_nop 1
	v_permlane32_swap_b32_e32 v20, v21
	v_cvt_pk_bf16_f32 v12, v12, v13
	v_cvt_pk_bf16_f32 v13, v14, v15
	global_store_dwordx2 v[30:31], v[24:25], off offset:256
	global_store_dwordx2 v[30:31], v[12:13], off offset:288
	s_and_saveexec_b64 s[22:23], s[0:1]
	s_cbranch_execz .LBB0_1455
	v_lshl_add_u64 v[12:13], v[28:29], 2, s[14:15]
	s_waitcnt lgkmcnt(0)
	v_add_f32_e32 v14, v20, v21
	global_atomic_add_f32 v[12:13], v14, off
.LBB0_1455:
	s_or_b64 exec, exec, s[22:23]
	v_add_u32_e32 v12, 0x40b0, v149
	v_ashrrev_i32_e32 v13, 31, v12
	v_lshlrev_b64 v[14:15], 11, v[12:13]
	v_mul_f32_e32 v20, v17, v17
	v_lshl_add_u64 v[14:15], s[10:11], 0, v[14:15]
	v_fmac_f32_e32 v20, v16, v16
	v_cvt_pk_bf16_f32 v16, v16, v17
	v_cvt_pk_bf16_f32 v17, v18, v19
	v_lshl_add_u64 v[14:15], v[136:137], 1, v[14:15]
	global_store_dwordx2 v[14:15], v[16:17], off
	v_mul_f32_e32 v16, v9, v9
	v_mul_f32_e32 v17, v11, v11
	s_waitcnt lgkmcnt(0)
	v_mul_f32_e32 v21, v19, v19
	v_fmac_f32_e32 v16, v8, v8
	v_fmac_f32_e32 v17, v10, v10
	v_fmac_f32_e32 v21, v18, v18
	v_add_f32_e32 v16, v16, v17
	v_cvt_pk_bf16_f32 v8, v8, v9
	v_mul_f32_e32 v9, v5, v5
	v_mul_f32_e32 v17, v7, v7
	v_add_f32_e32 v20, v20, v21
	v_fmac_f32_e32 v9, v4, v4
	v_fmac_f32_e32 v17, v6, v6
	v_add_f32_e32 v16, v20, v16
	v_add_f32_e32 v9, v9, v17
	v_add_f32_e32 v9, v16, v9
	v_mul_f32_e32 v16, v1, v1
	v_mul_f32_e32 v17, v3, v3
	v_fmac_f32_e32 v16, v0, v0
	v_fmac_f32_e32 v17, v2, v2
	v_add_f32_e32 v16, v16, v17
	v_add_f32_e32 v16, v9, v16
	v_mov_b32_e32 v17, v16
	s_nop 1
	v_permlane16_swap_b32_e32 v16, v17
	v_cvt_pk_bf16_f32 v9, v10, v11
	global_store_dwordx2 v[14:15], v[8:9], off offset:32
	v_cvt_pk_bf16_f32 v8, v4, v5
	v_cvt_pk_bf16_f32 v9, v6, v7
	s_waitcnt lgkmcnt(0)
	v_add_f32_e32 v4, v16, v17
	v_mov_b32_e32 v5, v4
	s_nop 1
	v_permlane32_swap_b32_e32 v4, v5
	v_cvt_pk_bf16_f32 v0, v0, v1
	v_cvt_pk_bf16_f32 v1, v2, v3
	global_store_dwordx2 v[14:15], v[8:9], off offset:256
	global_store_dwordx2 v[14:15], v[0:1], off offset:288
	s_and_saveexec_b64 s[22:23], s[0:1]
	s_cbranch_execz .LBB0_1428
	v_lshl_add_u64 v[0:1], v[12:13], 2, s[14:15]
	s_waitcnt lgkmcnt(0)
	v_add_f32_e32 v2, v4, v5
	global_atomic_add_f32 v[0:1], v2, off
	s_branch .LBB0_1428
